# lagging wave half now takes its stagger barrier at the end of the per-tile header instead of right after its epilogue (both halves compute the next-tile header concurrently)
# speedup vs baseline: 1.0166x; 1.0021x over previous
; __device__ __forceinline__ int lane_id_v() { int l; asm volatile("v_mbcnt_lo_u32_b32 %0, -1, 0\n\tv_mbcnt_hi_u32_b32 %0, -1, %0" : "=v"(l)); return l; }
; #define PG8_WAIT_V(n) asm volatile("s_waitcnt vmcnt(" #n ")" ::: "memory")
; template <class Epi, class Sched, bool ALIGN_EPI, bool SP2>
; __device__ __forceinline__ void gemm_phase(PG8_LAS unsigned char* lds, const Gemm g, const Sched& S, const Epi& E, int wid) {
;     const int lane = lane_id_v(), tid = wid * 64 + lane;
;     const int wr = wid >> 2, wc = wid & 3, fr = lane & 15, fq = lane >> 4;
;     const int K = g.K, nt = K / BK, lda = g.lda;
;     unsigned voffA[2], voffB[2];
; #pragma unroll
;     for (int i = 0; i < 2; ++i) { const int u_ = wid + 8 * i, rr_ = lane >> 3, ch_ = (lane & 7) ^ ((rr_ >> 1) & 3); const int R = u_ * 8 + rr_, C = ch_ * 8;
;         const int Rb = Epi::PERM ? ((R & ~31) + perm32(R & 31)) : R;
;         voffA[i] = (unsigned)(R * lda + C) * 2u; voffB[i] = (unsigned)(Rb * K + C) * 2u; }
;     const size_t kstep = (size_t)(BK * 2);
;     const size_t hstepA = (size_t)HALF * lda * 2, hstepB = (size_t)HALF * K * 2;
;     const size_t tstepA = 2 * hstepA, tstepB = 2 * hstepB;
;     const unsigned ldsw = (unsigned)wid * (unsigned)USTR;
;     const int foff = (fr >> 3) * USTR + (fr & 7) * 128 + ((fq ^ ((fr >> 1) & 3)) << 4);
;     const int aoff = wr * 8 * USTR + foff, boff = wc * 4 * USTR + foff;
;     ...
;     Unit cur, nxt; int ui = 0;
;     if (!S.next(0, cur)) return;
;     f32x4 acc[2][2][4][2];
; #pragma unroll
;     for (int a = 0; a < 2; ++a)
; #pragma unroll
;         for (int b = 0; b < 2; ++b)
; #pragma unroll
;             for (int m = 0; m < 4; ++m)
; #pragma unroll
;                 for (int n = 0; n < 2; ++n) acc[a][b][m][n] = (f32x4){0.f, 0.f, 0.f, 0.f};
;     bf16x8 At[4][2], B0[2][2], B1[2][2];
;     const char* cA = (const char*)g.A + (size_t)cur.pm * tstepA; const char* cB = (const char*)g.Bt + (size_t)cur.pn * tstepB;
;     if constexpr (SP2) {
;         PG8_STAGE(PG8_SB(0, 0), cB, voffB); PG8_STAGE(PG8_SB(0, 1), cB + hstepB, voffB); PG8_STAGE(PG8_SA(0, 0), cA, voffA); PG8_STAGE(PG8_SA(0, 1), cA + hstepA, voffA);
;         if (wr == 1) PG8_BAR;
;         PG8_WAIT_V(2); PG8_BAR;
;         PG8_STAGE(PG8_SB(1, 0), cB + kstep, voffB); PG8_STAGE(PG8_SA(1, 0), cA + kstep, voffA); PG8_STAGE(PG8_SB(1, 1), cB + hstepB + kstep, voffB);
;         PG8_WAIT_V(6); PG8_BAR;
.LBB0_134:
	v_readlane_b32 s0, v254, 48
	s_cmp_lt_i32 s0, 5
	s_mov_b64 s[46:47], 0
	s_cbranch_scc1 .LBB0_172
	s_cmp_gt_i32 s0, 5
	s_cbranch_scc0 .LBB0_173
	s_cmp_eq_u32 s0, 6
	s_cbranch_scc0 .LBB0_174
	v_readlane_b32 s22, v252, 11
	v_readlane_b32 s23, v252, 12
	s_andn2_b64 vcc, exec, s[22:23]
	s_waitcnt lgkmcnt(0)
	v_mbcnt_lo_u32_b32 v1, -1, 0
	v_mbcnt_hi_u32_b32 v1, -1, v1
	s_cbranch_vccnz .LBB0_176
	v_ashrrev_i32_e32 v0, 3, v1
	v_readlane_b32 s0, v252, 10
	s_waitcnt vmcnt(0)
	v_lshlrev_b32_e32 v2, 4, v1
	v_and_b32_e32 v6, 48, v1
	v_add_u32_e32 v3, s0, v0
	v_add_u32_e32 v4, 64, v3
	v_lshlrev_b32_e32 v5, 11, v4
	v_and_b32_e32 v2, 0x70, v2
	v_lshlrev_b32_e32 v4, 12, v4
	v_bitop3_b32 v162, v4, v6, v2 bitop3:0xf6
	v_lshlrev_b32_e32 v4, 11, v3
	s_add_i32 s0, s33, 0
	v_readlane_b32 s22, v255, 16
	v_bitop3_b32 v192, v6, v4, v2 bitop3:0xde
	s_add_i32 m0, s0, 0x11000
	v_readlane_b32 s23, v255, 17
	v_bitop3_b32 v160, v5, v6, v2 bitop3:0xf6
	v_lshlrev_b32_e32 v3, 12, v3
	v_bitop3_b32 v164, v6, v3, v2 bitop3:0xde
	s_add_i32 s5, s0, 0x2200
	s_add_i32 s29, s0, 0x4400
	global_load_lds_dwordx4 v192, s[22:23]
	s_add_i32 m0, s0, 0x13200
	s_add_i32 s56, s0, 0x6600
	global_load_lds_dwordx4 v160, s[22:23]
	v_readlane_b32 s22, v255, 14
	s_add_i32 m0, s0, 0x15400
	v_readlane_b32 s23, v255, 15
	s_nop 4
	global_load_lds_dwordx4 v192, s[22:23]
	s_add_i32 m0, s0, 0x17600
	s_nop 0
	global_load_lds_dwordx4 v160, s[22:23]
	v_readlane_b32 s22, v253, 36
	s_mov_b32 m0, s0
	v_readlane_b32 s23, v253, 37
	s_nop 4
	global_load_lds_dwordx4 v164, s[22:23]
	s_mov_b32 m0, s5
	s_nop 0
	global_load_lds_dwordx4 v162, s[22:23]
	v_readlane_b32 s22, v253, 38
	s_mov_b32 m0, s29
	v_readlane_b32 s23, v253, 39
	s_nop 4
	global_load_lds_dwordx4 v164, s[22:23]
	s_mov_b32 m0, s56
	s_nop 0
	global_load_lds_dwordx4 v162, s[22:23]
	v_readlane_b32 s22, v252, 13
	v_readlane_b32 s23, v252, 14
	s_andn2_b64 vcc, exec, s[22:23]
	s_nop 0
	v_cndmask_b32_e64 v3, 0, 1, s[22:23]
	v_cmp_ne_u32_e64 s[34:35], 1, v3
	s_cbranch_vccnz .LBB0_140
.LBB0_140:
	v_readlane_b32 s40, v255, 16
	v_readlane_b32 s41, v255, 17
	v_bitop3_b32 v10, v1, v2, 48 bitop3:0x6c
	v_mov_b32_e32 v161, v193
	v_lshl_add_u64 v[2:3], s[40:41], 0, v[192:193]
	v_readlane_b32 s38, v253, 36
	v_lshl_add_u64 v[4:5], s[40:41], 0, v[160:161]
	v_mov_b32_e32 v165, v193
	v_readlane_b32 s39, v253, 37
	v_lshl_add_u64 v[2:3], v[2:3], 0, s[6:7]
	s_add_i32 m0, s0, 0x19800
	v_lshl_add_u64 v[6:7], s[38:39], 0, v[164:165]
	v_mov_b32_e32 v163, v193
	s_waitcnt vmcnt(2)
	s_barrier
	global_load_lds_dwordx4 v[2:3], off
	v_lshl_add_u64 v[2:3], v[4:5], 0, s[6:7]
	s_add_i32 m0, s0, 0x1ba00
	s_add_i32 s57, s0, 0x8800
	v_lshl_add_u64 v[8:9], s[38:39], 0, v[162:163]
	global_load_lds_dwordx4 v[2:3], off
	v_lshl_add_u64 v[2:3], v[6:7], 0, s[6:7]
	s_mov_b32 m0, s57
	s_add_i32 s76, s0, 0xaa00
	v_readlane_b32 s22, v255, 18
	global_load_lds_dwordx4 v[2:3], off
	v_lshl_add_u64 v[2:3], v[8:9], 0, s[6:7]
	s_mov_b32 m0, s76
	v_readlane_b32 s23, v255, 19
	global_load_lds_dwordx4 v[2:3], off
	s_nop 0
	v_lshl_add_u64 v[2:3], s[22:23], 0, v[192:193]
	s_add_i32 m0, s0, 0x1dc00
	v_lshlrev_b32_e32 v12, 7, v1
	global_load_lds_dwordx4 v[2:3], off
	v_lshl_add_u64 v[2:3], s[22:23], 0, v[160:161]
	s_add_i32 m0, s0, 0x1fe00
	v_bfe_i32 v11, v1, 3, 1
	global_load_lds_dwordx4 v[2:3], off
	v_and_b32_e32 v12, 0x380, v12
	s_movk_i32 s2, 0x440
	v_and_or_b32 v11, v11, s2, v12
	v_lshlrev_b32_e32 v12, 3, v1
	v_and_b32_e32 v12, 48, v12
	v_and_b32_e32 v1, -16, v1
	v_xad_u32 v1, v12, v1, v11
	v_readlane_b32 s2, v254, 12
	s_waitcnt vmcnt(6)
	v_lshlrev_b32_e32 v0, 12, v0
	v_readlane_b32 s22, v253, 34
	v_add_u32_e32 v11, s2, v1
	s_mul_i32 s2, s17, 0x1100
	v_add_u32_e32 v216, s2, v1
	v_readlane_b32 s2, v254, 15
	v_mov_b32_e32 v166, v196
	v_mov_b32_e32 v167, v196
	v_add3_u32 v168, s2, v10, v0
	v_readlane_b32 s2, v254, 16
	v_mov_b32_e32 v169, v193
	v_mov_b32_e32 v171, v193
	v_add3_u32 v170, s2, v10, v0
	s_mov_b32 s77, 0
	v_add_u32_e32 v217, 0, v11
	v_readlane_b32 s2, v253, 26
	s_mov_b32 s10, s22
	s_barrier
	v_readlane_b32 s23, v253, 35
	s_branch .LBB0_143

; #define PG8_LAS __attribute__((address_space(3)))
; #define PG8_STAGE(bufoff, gbase, voff) do { _Pragma("unroll") for (int _i = 0; _i < 2; ++_i) \
;         __builtin_amdgcn_global_load_lds((const unsigned*)((const char*)(gbase) + (voff)[_i]), (PG8_LAS unsigned*)(lds + (bufoff) + ldsw + _i * (8 * USTR)), 16, 0, 0); } while (0)
; #define PG8_WAIT_V(n) asm volatile("s_waitcnt vmcnt(" #n ")" ::: "memory")
; #define PG8_BAR __builtin_amdgcn_s_barrier()
; template <class Epi, class Sched, bool ALIGN_EPI, bool SP2>
; __device__ __forceinline__ void gemm_phase(PG8_LAS unsigned char* lds, const Gemm g, const Sched& S, const Epi& E, int wid) {
;     ...
;         const bool has_next = S.next(ui + 1, nxt);
;         const char* nA = has_next ? (const char*)g.A + (size_t)nxt.pm * tstepA : cA; const char* nB = has_next ? (const char*)g.Bt + (size_t)nxt.pn * tstepB : cB;
;         for (int t = 0; t < nt; t += 2) {
;             const bool last = (t == nt - 2);
;             const char* a1 = cA + (size_t)(t + 1) * kstep;
;             const char* a2 = last ? nA : cA + (size_t)(t + 2) * kstep; const char* b2 = last ? nB : cB + (size_t)(t + 2) * kstep;
;             const char* a3 = a2 + kstep; const char* b3 = b2 + kstep;
;             if constexpr (Epi::PRE == 1) { if (last) {
;                 const char* rsrc; const char* ssrc; E.pre(cur, rsrc, ssrc);
; #pragma unroll
;                 for (int _i = 0; _i < 2; ++_i) __builtin_amdgcn_global_load_lds((const unsigned*)(rsrc + (wid + 8 * _i) * 1024 + lane * 16), (PG8_LAS unsigned*)(lds + LDS_XOFF + (wid + 8 * _i) * 1024), 16, 0, 0);
;                 if (wid == 0) __builtin_amdgcn_global_load_lds((const unsigned*)(ssrc + lane * 16), (PG8_LAS unsigned*)(lds + LDS_XOFF + 16384), 16, 0, 0);
;             } }
;             if constexpr (SP2) {
;             PG8_LDB(B0, 0, 0); PG8_LDB(B1, 0, 1); PG8_SCHED; PG8_LDA(At, 0, 0); PG8_STAGE(PG8_SA(1, 1), a1 + hstepA, voffA);
;             PG8_WAIT_V(8); PG8_WAIT_L(0); PG8_BAR; PG8_MMA(0, 0, At, B0); PG8_MMA(0, 1, At, B1); PG8_BAR; PG8_SCHED;
;             PG8_LDA(At, 0, 1); PG8_STAGE(PG8_SB(0, 0), b2, voffB); PG8_STAGE(PG8_SB(0, 1), b2 + hstepB, voffB); PG8_STAGE(PG8_SA(0, 0), a2, voffA);
;             PG8_WAIT_V(8); PG8_WAIT_L(0); PG8_BAR; PG8_MMA(1, 0, At, B0); PG8_MMA(1, 1, At, B1); PG8_BAR; PG8_SCHED;
;     ...
;         if constexpr (ALIGN_EPI) { if (wr == 1) PG8_BAR; }
.LBB0_149:
	s_ashr_i32 s69, s68, 31
	s_lshl_b64 s[26:27], s[68:69], 20
	s_add_u32 s70, s30, s26
	s_addc_u32 s71, s31, s27
	s_and_b64 s[26:27], s[36:37], exec
	s_cselect_b32 s26, s71, s39
	s_cselect_b32 s27, s70, s38
	s_ashr_i32 s23, s22, 31
	s_lshl_b64 s[72:73], s[22:23], 19
	v_readlane_b32 s23, v255, 12
	s_add_u32 s72, s23, s72
	v_readlane_b32 s23, v255, 13
	s_addc_u32 s73, s23, s73
	s_and_b64 s[74:75], s[36:37], exec
	s_cselect_b32 s23, s73, s41
	s_cselect_b32 s69, s72, s40
	s_add_u32 s38, s38, 0x80080
	s_addc_u32 s39, s39, 0
	s_add_u32 s78, s40, 0x100
	s_addc_u32 s79, s41, 0
	s_mov_b32 s89, -2
	s_waitcnt vmcnt(0)
	s_and_b64 vcc, exec, s[34:35]
	s_cbranch_vccnz .Lhb_mixout
	s_barrier
.Lhb_mixout:
	s_add_u32 s40, s38, 0xfff80080
	s_addc_u32 s41, s39, -1
	s_add_i32 s95, 0, 0x11000
	s_cmp_eq_u32 s89, 12
	s_cselect_b32 s75, s26, s41
	s_cselect_b32 s74, s27, s40
	s_cselect_b32 s41, s23, s79
	s_cselect_b32 s40, s69, s78
	s_add_i32 s44, 0, 0x15400
	v_add_u32_e32 v60, s95, v216
	v_add_u32_e32 v156, s44, v216
	ds_read_b128 v[48:51], v60
	ds_read_b128 v[52:55], v60 offset:64
	ds_read_b128 v[56:59], v60 offset:2176
	ds_read_b128 v[60:63], v60 offset:2240
	ds_read_b128 v[144:147], v156
	ds_read_b128 v[148:151], v156 offset:64
	ds_read_b128 v[152:155], v156 offset:2176
	ds_read_b128 v[156:159], v156 offset:2240
	v_lshl_add_u64 v[198:199], s[38:39], 0, v[168:169]
	s_add_i32 m0, s0, 0xcc00
	ds_read_b128 v[172:175], v217
	ds_read_b128 v[176:179], v217 offset:64
	ds_read_b128 v[180:183], v217 offset:2176
	ds_read_b128 v[184:187], v217 offset:2240
	ds_read_b128 v[188:191], v217 offset:4352
	ds_read_b128 v[208:211], v217 offset:4416
	ds_read_b128 v[212:215], v217 offset:6528
	ds_read_b128 v[218:221], v217 offset:6592
	global_load_lds_dwordx4 v[198:199], off
	v_lshl_add_u64 v[198:199], s[38:39], 0, v[170:171]
	s_add_i32 m0, s0, 0xee00
	s_nop 0
	global_load_lds_dwordx4 v[198:199], off
	s_waitcnt vmcnt(8)
	s_waitcnt lgkmcnt(0)
	s_barrier
	s_setprio 1
	s_waitcnt lgkmcnt(0)
	v_mfma_f32_16x16x32_bf16 v[140:143], v[48:51], v[172:175], 0
	v_mfma_f32_16x16x32_bf16 v[136:139], v[56:59], v[172:175], 0
	v_mfma_f32_16x16x32_bf16 v[124:127], v[48:51], v[180:183], 0
	v_mfma_f32_16x16x32_bf16 v[120:123], v[56:59], v[180:183], 0
	v_mfma_f32_16x16x32_bf16 v[108:111], v[48:51], v[188:191], 0
	v_mfma_f32_16x16x32_bf16 v[104:107], v[56:59], v[188:191], 0
	v_mfma_f32_16x16x32_bf16 v[92:95], v[48:51], v[212:215], 0
	v_mfma_f32_16x16x32_bf16 v[88:91], v[56:59], v[212:215], 0
	v_mfma_f32_16x16x32_bf16 v[140:143], v[52:55], v[176:179], v[140:143]
	v_mfma_f32_16x16x32_bf16 v[136:139], v[60:63], v[176:179], v[136:139]
	v_mfma_f32_16x16x32_bf16 v[124:127], v[52:55], v[184:187], v[124:127]
	v_mfma_f32_16x16x32_bf16 v[120:123], v[60:63], v[184:187], v[120:123]
	v_mfma_f32_16x16x32_bf16 v[108:111], v[52:55], v[208:211], v[108:111]
	v_mfma_f32_16x16x32_bf16 v[104:107], v[60:63], v[208:211], v[104:107]
	v_mfma_f32_16x16x32_bf16 v[92:95], v[52:55], v[218:221], v[92:95]
	v_mfma_f32_16x16x32_bf16 v[88:91], v[60:63], v[218:221], v[88:91]
	s_setprio 0
	s_setprio 1
	v_mfma_f32_16x16x32_bf16 v[132:135], v[144:147], v[172:175], 0
	v_mfma_f32_16x16x32_bf16 v[128:131], v[152:155], v[172:175], 0
	v_mfma_f32_16x16x32_bf16 v[116:119], v[144:147], v[180:183], 0
	v_mfma_f32_16x16x32_bf16 v[112:115], v[152:155], v[180:183], 0
	v_mfma_f32_16x16x32_bf16 v[100:103], v[144:147], v[188:191], 0
	v_mfma_f32_16x16x32_bf16 v[96:99], v[152:155], v[188:191], 0
	v_mfma_f32_16x16x32_bf16 v[84:87], v[144:147], v[212:215], 0
	v_mfma_f32_16x16x32_bf16 v[80:83], v[152:155], v[212:215], 0
	v_mfma_f32_16x16x32_bf16 v[132:135], v[148:151], v[176:179], v[132:135]
	v_mfma_f32_16x16x32_bf16 v[128:131], v[156:159], v[176:179], v[128:131]
	v_mfma_f32_16x16x32_bf16 v[116:119], v[148:151], v[184:187], v[116:119]
	v_mfma_f32_16x16x32_bf16 v[112:115], v[156:159], v[184:187], v[112:115]
	v_mfma_f32_16x16x32_bf16 v[100:103], v[148:151], v[208:211], v[100:103]
	v_mfma_f32_16x16x32_bf16 v[96:99], v[156:159], v[208:211], v[96:99]
	v_mfma_f32_16x16x32_bf16 v[84:87], v[148:151], v[218:221], v[84:87]
	v_mfma_f32_16x16x32_bf16 v[80:83], v[156:159], v[218:221], v[80:83]
	s_setprio 0
	s_barrier
	s_add_i32 s45, s95, s33
	v_lshl_add_u64 v[198:199], s[40:41], 0, v[192:193]
	s_mov_b32 m0, s45
	ds_read_b128 v[172:175], v217 offset:17408
	ds_read_b128 v[176:179], v217 offset:17472
	ds_read_b128 v[180:183], v217 offset:19584
	ds_read_b128 v[184:187], v217 offset:19648
	ds_read_b128 v[188:191], v217 offset:21760
	ds_read_b128 v[208:211], v217 offset:21824
	ds_read_b128 v[212:215], v217 offset:23936
	ds_read_b128 v[218:221], v217 offset:24000
	global_load_lds_dwordx4 v[198:199], off
	s_add_i32 m0, s45, 0x2200
	s_add_u32 vcc_lo, s40, 0x40000
	v_lshl_add_u64 v[200:201], s[40:41], 0, v[160:161]
	s_addc_u32 vcc_hi, s41, 0
	s_add_i32 s44, s44, s33
	global_load_lds_dwordx4 v[200:201], off
	v_lshl_add_u64 v[222:223], vcc, 0, v[192:193]
	s_mov_b32 m0, s44
	v_lshl_add_u64 v[224:225], s[74:75], 0, v[162:163]
	global_load_lds_dwordx4 v[222:223], off
	v_lshl_add_u64 v[222:223], vcc, 0, v[160:161]
	s_add_i32 m0, s44, 0x2200
	s_nop 0
	global_load_lds_dwordx4 v[222:223], off
	v_lshl_add_u64 v[222:223], s[74:75], 0, v[164:165]
	s_mov_b32 m0, s0
	s_nop 0
	global_load_lds_dwordx4 v[222:223], off
	s_mov_b32 m0, s5
	s_nop 0
	global_load_lds_dwordx4 v[224:225], off
	s_waitcnt vmcnt(8)
	s_waitcnt lgkmcnt(0)
	s_barrier
; #define PG8_STAGE(bufoff, gbase, voff) do { _Pragma("unroll") for (int _i = 0; _i < 2; ++_i) \
;         __builtin_amdgcn_global_load_lds((const unsigned*)((const char*)(gbase) + (voff)[_i]), (PG8_LAS unsigned*)(lds + (bufoff) + ldsw + _i * (8 * USTR)), 16, 0, 0); } while (0)
; #define PG8_LDA(dst, b, h) do { _Pragma("unroll") for (int m = 0; m < 4; ++m) _Pragma("unroll") for (int k = 0; k < 2; ++k) dst[m][k] = *(const PG8_LAS bf16x8*)(lds + PG8_SA(b, h) + aoff + m * (2 * USTR) + k * 64); } while (0)
; #define PG8_LDB(dst, b, h) do { _Pragma("unroll") for (int n = 0; n < 2; ++n) _Pragma("unroll") for (int k = 0; k < 2; ++k) dst[n][k] = *(const PG8_LAS bf16x8*)(lds + PG8_SB(b, h) + boff + n * (2 * USTR) + k * 64); } while (0)
; #define PG8_MMA(ai, bj, At, Bt) do { __builtin_amdgcn_s_setprio(1); _Pragma("unroll") for (int m = 0; m < 4; ++m) _Pragma("unroll") for (int n = 0; n < 2; ++n) _Pragma("unroll") for (int k = 0; k < 2; ++k) \
;         acc[ai][bj][m][n] = __builtin_amdgcn_mfma_f32_16x16x32_bf16(Bt[n][k], At[m][k], acc[ai][bj][m][n], 0, 0, 0); __builtin_amdgcn_s_setprio(0); } while (0)
; #define PG8_WAIT_V(n) asm volatile("s_waitcnt vmcnt(" #n ")" ::: "memory")
; #define PG8_WAIT_L(n) asm volatile("s_waitcnt lgkmcnt(" #n ")" ::: "memory")
; #define PG8_BAR __builtin_amdgcn_s_barrier()
; #define PG8_SCHED __builtin_amdgcn_sched_barrier(0)
; template <class Epi, class Sched, bool ALIGN_EPI, bool SP2>
; __device__ __forceinline__ void gemm_phase(PG8_LAS unsigned char* lds, const Gemm g, const Sched& S, const Epi& E, int wid) {
;     ...
;             PG8_WAIT_V(8); PG8_WAIT_L(0); PG8_BAR; PG8_MMA(1, 0, At, B0); PG8_MMA(1, 1, At, B1); PG8_BAR; PG8_SCHED;
;             PG8_LDB(B0, 1, 0); PG8_LDB(B1, 1, 1); PG8_SCHED; PG8_LDA(At, 1, 0); PG8_STAGE(PG8_SA(0, 1), a2 + hstepA, voffA);
;             PG8_WAIT_V(8); PG8_WAIT_L(0); PG8_BAR; PG8_MMA(0, 0, At, B0); PG8_MMA(0, 1, At, B1); PG8_BAR; PG8_SCHED;
	s_setprio 1
	s_waitcnt lgkmcnt(0)
	v_mfma_f32_16x16x32_bf16 v[76:79], v[48:51], v[172:175], 0
	v_mfma_f32_16x16x32_bf16 v[72:75], v[56:59], v[172:175], 0
	v_mfma_f32_16x16x32_bf16 v[44:47], v[48:51], v[180:183], 0
	v_mfma_f32_16x16x32_bf16 v[40:43], v[56:59], v[180:183], 0
	v_mfma_f32_16x16x32_bf16 v[24:27], v[48:51], v[188:191], 0
	v_mfma_f32_16x16x32_bf16 v[28:31], v[56:59], v[188:191], 0
	v_mfma_f32_16x16x32_bf16 v[4:7], v[48:51], v[212:215], 0
	v_mfma_f32_16x16x32_bf16 v[12:15], v[56:59], v[212:215], 0
	v_mfma_f32_16x16x32_bf16 v[76:79], v[52:55], v[176:179], v[76:79]
	v_mfma_f32_16x16x32_bf16 v[72:75], v[60:63], v[176:179], v[72:75]
	v_mfma_f32_16x16x32_bf16 v[44:47], v[52:55], v[184:187], v[44:47]
	v_mfma_f32_16x16x32_bf16 v[40:43], v[60:63], v[184:187], v[40:43]
	v_mfma_f32_16x16x32_bf16 v[24:27], v[52:55], v[208:211], v[24:27]
	v_mfma_f32_16x16x32_bf16 v[28:31], v[60:63], v[208:211], v[28:31]
	v_mfma_f32_16x16x32_bf16 v[4:7], v[52:55], v[218:221], v[4:7]
	v_mfma_f32_16x16x32_bf16 v[12:15], v[60:63], v[218:221], v[12:15]
	s_setprio 0
	s_setprio 1
	v_mfma_f32_16x16x32_bf16 v[36:39], v[144:147], v[180:183], 0
	v_mfma_f32_16x16x32_bf16 v[32:35], v[152:155], v[180:183], 0
	v_mfma_f32_16x16x32_bf16 v[20:23], v[144:147], v[188:191], 0
	v_mfma_f32_16x16x32_bf16 v[16:19], v[152:155], v[188:191], 0
	v_mfma_f32_16x16x32_bf16 v[8:11], v[144:147], v[212:215], 0
	v_mfma_f32_16x16x32_bf16 v[0:3], v[152:155], v[212:215], 0
	v_mfma_f32_16x16x32_bf16 v[48:51], v[144:147], v[172:175], 0
	v_mfma_f32_16x16x32_bf16 v[52:55], v[152:155], v[172:175], 0
	v_mfma_f32_16x16x32_bf16 v[36:39], v[148:151], v[184:187], v[36:39]
	v_mfma_f32_16x16x32_bf16 v[32:35], v[156:159], v[184:187], v[32:35]
	v_mfma_f32_16x16x32_bf16 v[20:23], v[148:151], v[208:211], v[20:23]
	v_mfma_f32_16x16x32_bf16 v[16:19], v[156:159], v[208:211], v[16:19]
	v_mfma_f32_16x16x32_bf16 v[8:11], v[148:151], v[218:221], v[8:11]
	v_mfma_f32_16x16x32_bf16 v[0:3], v[156:159], v[218:221], v[0:3]
	v_mfma_f32_16x16x32_bf16 v[48:51], v[148:151], v[176:179], v[48:51]
	v_mfma_f32_16x16x32_bf16 v[52:55], v[156:159], v[176:179], v[52:55]
	s_setprio 0
	s_barrier
	s_add_i32 s44, 0, 0x19800
	s_add_i32 s45, 0, 0x1dc00
	v_add_u32_e32 v68, s44, v216
	v_add_u32_e32 v156, s45, v216
	ds_read_b128 v[56:59], v68
	ds_read_b128 v[60:63], v68 offset:64
	ds_read_b128 v[64:67], v68 offset:2176
	ds_read_b128 v[68:71], v68 offset:2240
	ds_read_b128 v[144:147], v156
	ds_read_b128 v[148:151], v156 offset:64
	ds_read_b128 v[152:155], v156 offset:2176
	ds_read_b128 v[156:159], v156 offset:2240
	s_add_u32 s74, s74, 0x80000
	s_addc_u32 s75, s75, 0
	s_mov_b32 m0, s29
	v_lshl_add_u64 v[226:227], s[74:75], 0, v[164:165]
	ds_read_b128 v[172:175], v217 offset:34816
	ds_read_b128 v[176:179], v217 offset:34880
	ds_read_b128 v[180:183], v217 offset:36992
	ds_read_b128 v[184:187], v217 offset:37056
	ds_read_b128 v[188:191], v217 offset:39168
	ds_read_b128 v[208:211], v217 offset:39232
	ds_read_b128 v[212:215], v217 offset:41344
	ds_read_b128 v[218:221], v217 offset:41408
	global_load_lds_dwordx4 v[226:227], off
	v_lshl_add_u64 v[226:227], s[74:75], 0, v[162:163]
	s_mov_b32 m0, s56
	s_nop 0
	global_load_lds_dwordx4 v[226:227], off
	s_waitcnt vmcnt(8)
	s_waitcnt lgkmcnt(0)
	s_barrier
	s_setprio 1
	s_waitcnt lgkmcnt(0)
	v_mfma_f32_16x16x32_bf16 v[140:143], v[56:59], v[172:175], v[140:143]
	v_mfma_f32_16x16x32_bf16 v[136:139], v[64:67], v[172:175], v[136:139]
	v_mfma_f32_16x16x32_bf16 v[124:127], v[56:59], v[180:183], v[124:127]
	v_mfma_f32_16x16x32_bf16 v[120:123], v[64:67], v[180:183], v[120:123]
	v_mfma_f32_16x16x32_bf16 v[108:111], v[56:59], v[188:191], v[108:111]
	v_mfma_f32_16x16x32_bf16 v[104:107], v[64:67], v[188:191], v[104:107]
	v_mfma_f32_16x16x32_bf16 v[92:95], v[56:59], v[212:215], v[92:95]
	v_mfma_f32_16x16x32_bf16 v[88:91], v[64:67], v[212:215], v[88:91]
	v_mfma_f32_16x16x32_bf16 v[140:143], v[60:63], v[176:179], v[140:143]
	v_mfma_f32_16x16x32_bf16 v[136:139], v[68:71], v[176:179], v[136:139]
	v_mfma_f32_16x16x32_bf16 v[124:127], v[60:63], v[184:187], v[124:127]
	v_mfma_f32_16x16x32_bf16 v[120:123], v[68:71], v[184:187], v[120:123]
	v_mfma_f32_16x16x32_bf16 v[108:111], v[60:63], v[208:211], v[108:111]
	v_mfma_f32_16x16x32_bf16 v[104:107], v[68:71], v[208:211], v[104:107]
	v_mfma_f32_16x16x32_bf16 v[92:95], v[60:63], v[218:221], v[92:95]
	v_mfma_f32_16x16x32_bf16 v[88:91], v[68:71], v[218:221], v[88:91]
	s_setprio 0
	s_setprio 1
	v_mfma_f32_16x16x32_bf16 v[132:135], v[144:147], v[172:175], v[132:135]
	v_mfma_f32_16x16x32_bf16 v[128:131], v[152:155], v[172:175], v[128:131]
	v_mfma_f32_16x16x32_bf16 v[116:119], v[144:147], v[180:183], v[116:119]
	v_mfma_f32_16x16x32_bf16 v[112:115], v[152:155], v[180:183], v[112:115]
	v_mfma_f32_16x16x32_bf16 v[100:103], v[144:147], v[188:191], v[100:103]
	v_mfma_f32_16x16x32_bf16 v[96:99], v[152:155], v[188:191], v[96:99]
	v_mfma_f32_16x16x32_bf16 v[84:87], v[144:147], v[212:215], v[84:87]
	v_mfma_f32_16x16x32_bf16 v[80:83], v[152:155], v[212:215], v[80:83]
	v_mfma_f32_16x16x32_bf16 v[132:135], v[148:151], v[176:179], v[132:135]
	v_mfma_f32_16x16x32_bf16 v[128:131], v[156:159], v[176:179], v[128:131]
	v_mfma_f32_16x16x32_bf16 v[116:119], v[148:151], v[184:187], v[116:119]
	v_mfma_f32_16x16x32_bf16 v[112:115], v[156:159], v[184:187], v[112:115]
	v_mfma_f32_16x16x32_bf16 v[100:103], v[148:151], v[208:211], v[100:103]
	v_mfma_f32_16x16x32_bf16 v[96:99], v[156:159], v[208:211], v[96:99]
	v_mfma_f32_16x16x32_bf16 v[84:87], v[148:151], v[218:221], v[84:87]
	v_mfma_f32_16x16x32_bf16 v[80:83], v[156:159], v[218:221], v[80:83]
	s_setprio 0
	s_barrier
; #define PG8_STAGE(bufoff, gbase, voff) do { _Pragma("unroll") for (int _i = 0; _i < 2; ++_i) \
;         __builtin_amdgcn_global_load_lds((const unsigned*)((const char*)(gbase) + (voff)[_i]), (PG8_LAS unsigned*)(lds + (bufoff) + ldsw + _i * (8 * USTR)), 16, 0, 0); } while (0)
; #define PG8_LDA(dst, b, h) do { _Pragma("unroll") for (int m = 0; m < 4; ++m) _Pragma("unroll") for (int k = 0; k < 2; ++k) dst[m][k] = *(const PG8_LAS bf16x8*)(lds + PG8_SA(b, h) + aoff + m * (2 * USTR) + k * 64); } while (0)
; #define PG8_MMA(ai, bj, At, Bt) do { __builtin_amdgcn_s_setprio(1); _Pragma("unroll") for (int m = 0; m < 4; ++m) _Pragma("unroll") for (int n = 0; n < 2; ++n) _Pragma("unroll") for (int k = 0; k < 2; ++k) \
;         acc[ai][bj][m][n] = __builtin_amdgcn_mfma_f32_16x16x32_bf16(Bt[n][k], At[m][k], acc[ai][bj][m][n], 0, 0, 0); __builtin_amdgcn_s_setprio(0); } while (0)
; #define PG8_WAIT_V(n) asm volatile("s_waitcnt vmcnt(" #n ")" ::: "memory")
; #define PG8_WAIT_L(n) asm volatile("s_waitcnt lgkmcnt(" #n ")" ::: "memory")
; #define PG8_BAR __builtin_amdgcn_s_barrier()
; #define PG8_SCHED __builtin_amdgcn_sched_barrier(0)
; template <class Epi, class Sched, bool ALIGN_EPI, bool SP2>
; __device__ __forceinline__ void gemm_phase(PG8_LAS unsigned char* lds, const Gemm g, const Sched& S, const Epi& E, int wid) {
;     ...
;             PG8_LDA(At, 1, 1); PG8_STAGE(PG8_SB(1, 0), b3, voffB); PG8_STAGE(PG8_SB(1, 1), b3 + hstepB, voffB); PG8_STAGE(PG8_SA(1, 0), a3, voffA);
;             PG8_WAIT_V(8); PG8_WAIT_L(0); PG8_BAR; PG8_MMA(1, 0, At, B0); PG8_MMA(1, 1, At, B1); PG8_BAR; PG8_SCHED;
	s_add_i32 s44, s44, s33
	v_lshl_add_u64 v[198:199], v[198:199], 0, s[6:7]
	s_mov_b32 m0, s44
	ds_read_b128 v[172:175], v217 offset:52224
	ds_read_b128 v[176:179], v217 offset:52288
	ds_read_b128 v[180:183], v217 offset:54400
	ds_read_b128 v[184:187], v217 offset:54464
	ds_read_b128 v[188:191], v217 offset:56576
	ds_read_b128 v[208:211], v217 offset:56640
	ds_read_b128 v[212:215], v217 offset:58752
	ds_read_b128 v[218:221], v217 offset:58816
	global_load_lds_dwordx4 v[198:199], off
	s_add_i32 m0, s44, 0x2200
	s_add_u32 s40, s40, 0x40080
	v_lshl_add_u64 v[198:199], v[200:201], 0, s[6:7]
	s_addc_u32 s41, s41, 0
	s_add_i32 s44, s45, s33
	global_load_lds_dwordx4 v[198:199], off
	v_lshl_add_u64 v[198:199], s[40:41], 0, v[192:193]
	s_mov_b32 m0, s44
	s_nop 0
	global_load_lds_dwordx4 v[198:199], off
	v_lshl_add_u64 v[198:199], s[40:41], 0, v[160:161]
	s_add_i32 m0, s44, 0x2200
	s_nop 0
	global_load_lds_dwordx4 v[198:199], off
	v_lshl_add_u64 v[198:199], v[222:223], 0, s[6:7]
	s_mov_b32 m0, s57
	s_nop 0
	global_load_lds_dwordx4 v[198:199], off
	v_lshl_add_u64 v[198:199], v[224:225], 0, s[6:7]
	s_mov_b32 m0, s76
	s_nop 0
	global_load_lds_dwordx4 v[198:199], off
	s_waitcnt vmcnt(8)
	s_waitcnt lgkmcnt(0)
	s_barrier
	s_setprio 1
	s_waitcnt lgkmcnt(0)
	v_mfma_f32_16x16x32_bf16 v[76:79], v[56:59], v[172:175], v[76:79]
	v_mfma_f32_16x16x32_bf16 v[72:75], v[64:67], v[172:175], v[72:75]
	v_mfma_f32_16x16x32_bf16 v[44:47], v[56:59], v[180:183], v[44:47]
	v_mfma_f32_16x16x32_bf16 v[40:43], v[64:67], v[180:183], v[40:43]
	v_mfma_f32_16x16x32_bf16 v[24:27], v[56:59], v[188:191], v[24:27]
	v_mfma_f32_16x16x32_bf16 v[28:31], v[64:67], v[188:191], v[28:31]
	v_mfma_f32_16x16x32_bf16 v[4:7], v[56:59], v[212:215], v[4:7]
	v_mfma_f32_16x16x32_bf16 v[12:15], v[64:67], v[212:215], v[12:15]
	v_mfma_f32_16x16x32_bf16 v[76:79], v[60:63], v[176:179], v[76:79]
	v_mfma_f32_16x16x32_bf16 v[72:75], v[68:71], v[176:179], v[72:75]
	v_mfma_f32_16x16x32_bf16 v[44:47], v[60:63], v[184:187], v[44:47]
	v_mfma_f32_16x16x32_bf16 v[40:43], v[68:71], v[184:187], v[40:43]
	v_mfma_f32_16x16x32_bf16 v[24:27], v[60:63], v[208:211], v[24:27]
	v_mfma_f32_16x16x32_bf16 v[28:31], v[68:71], v[208:211], v[28:31]
	v_mfma_f32_16x16x32_bf16 v[4:7], v[60:63], v[218:221], v[4:7]
	v_mfma_f32_16x16x32_bf16 v[12:15], v[68:71], v[218:221], v[12:15]
	s_setprio 0
	s_setprio 1
	v_mfma_f32_16x16x32_bf16 v[48:51], v[144:147], v[172:175], v[48:51]
	v_mfma_f32_16x16x32_bf16 v[68:71], v[148:151], v[176:179], v[48:51]
	v_mfma_f32_16x16x32_bf16 v[48:51], v[152:155], v[172:175], v[52:55]
	v_mfma_f32_16x16x32_bf16 v[36:39], v[144:147], v[180:183], v[36:39]
	v_mfma_f32_16x16x32_bf16 v[32:35], v[152:155], v[180:183], v[32:35]
	v_mfma_f32_16x16x32_bf16 v[20:23], v[144:147], v[188:191], v[20:23]
	v_mfma_f32_16x16x32_bf16 v[16:19], v[152:155], v[188:191], v[16:19]
	v_mfma_f32_16x16x32_bf16 v[8:11], v[144:147], v[212:215], v[8:11]
	v_mfma_f32_16x16x32_bf16 v[0:3], v[152:155], v[212:215], v[0:3]
	v_mfma_f32_16x16x32_bf16 v[64:67], v[156:159], v[176:179], v[48:51]
	v_mfma_f32_16x16x32_bf16 v[36:39], v[148:151], v[184:187], v[36:39]
	v_mfma_f32_16x16x32_bf16 v[32:35], v[156:159], v[184:187], v[32:35]
	v_mfma_f32_16x16x32_bf16 v[20:23], v[148:151], v[208:211], v[20:23]
	v_mfma_f32_16x16x32_bf16 v[16:19], v[156:159], v[208:211], v[16:19]
	v_mfma_f32_16x16x32_bf16 v[8:11], v[148:151], v[218:221], v[8:11]
	v_mfma_f32_16x16x32_bf16 v[0:3], v[156:159], v[218:221], v[0:3]
	s_setprio 0
	s_barrier
	s_add_i32 s89, s89, 2
	s_add_u32 s38, s38, 0x100
	s_addc_u32 s39, s39, 0
	s_add_u32 s78, s78, 0x100
	s_addc_u32 s79, s79, 0
	s_cmp_gt_u32 s89, 13

; #define PG8_BAR __builtin_amdgcn_s_barrier()
; template <class Epi, class Sched, bool ALIGN_EPI, bool SP2>
; __device__ __forceinline__ void gemm_phase(PG8_LAS unsigned char* lds, const Gemm g, const Sched& S, const Epi& E, int wid) {
;     ...
;         if (!has_next) break;
; #pragma unroll
;         for (int a = 0; a < 2; ++a)
; #pragma unroll
;             for (int b = 0; b < 2; ++b)
; #pragma unroll
;                 for (int m = 0; m < 4; ++m)
; #pragma unroll
;                     for (int n = 0; n < 2; ++n) acc[a][b][m][n] = (f32x4){0.f, 0.f, 0.f, 0.f};
;         cur = nxt; cA = nA; cB = nB; ++ui;
;         if constexpr (ALIGN_EPI) { if (wr == 1) PG8_BAR; }
;     }
.LBB0_169:
	s_or_b64 exec, exec, s[26:27]
	s_andn2_b64 vcc, exec, s[36:37]
	s_mov_b64 s[26:27], -1
	s_cbranch_vccnz .LBB0_142
	s_and_b64 vcc, exec, s[34:35]
	s_cbranch_vccnz .LBB0_141
	s_branch .LBB0_141

; #define PG8_STAGE(bufoff, gbase, voff) do { _Pragma("unroll") for (int _i = 0; _i < 2; ++_i) \
;         __builtin_amdgcn_global_load_lds((const unsigned*)((const char*)(gbase) + (voff)[_i]), (PG8_LAS unsigned*)(lds + (bufoff) + ldsw + _i * (8 * USTR)), 16, 0, 0); } while (0)
; #define PG8_WAIT_V(n) asm volatile("s_waitcnt vmcnt(" #n ")" ::: "memory")
; #define PG8_BAR __builtin_amdgcn_s_barrier()
; template <class Epi, class Sched, bool ALIGN_EPI, bool SP2>
; __device__ __forceinline__ void gemm_phase(PG8_LAS unsigned char* lds, const Gemm g, const Sched& S, const Epi& E, int wid) {
;     ...
; #pragma unroll
;     for (int i = 0; i < 2; ++i) { const int u_ = wid + 8 * i, rr_ = lane >> 3, ch_ = (lane & 7) ^ ((rr_ >> 1) & 3); const int R = u_ * 8 + rr_, C = ch_ * 8;
;         const int Rb = Epi::PERM ? ((R & ~31) + perm32(R & 31)) : R;
;         voffA[i] = (unsigned)(R * lda + C) * 2u; voffB[i] = (unsigned)(Rb * K + C) * 2u; }
;     ...
;     if constexpr (SP2) {
;         PG8_STAGE(PG8_SB(0, 0), cB, voffB); PG8_STAGE(PG8_SB(0, 1), cB + hstepB, voffB); PG8_STAGE(PG8_SA(0, 0), cA, voffA); PG8_STAGE(PG8_SA(0, 1), cA + hstepA, voffA);
;         if (wr == 1) PG8_BAR;
;         PG8_WAIT_V(2); PG8_BAR;
;         PG8_STAGE(PG8_SB(1, 0), cB + kstep, voffB); PG8_STAGE(PG8_SA(1, 0), cA + kstep, voffA); PG8_STAGE(PG8_SB(1, 1), cB + hstepB + kstep, voffB);
;         PG8_WAIT_V(6); PG8_BAR;
.LBB0_271:
	s_andn2_b64 vcc, exec, s[40:41]
	s_cbranch_vccnz .LBB0_360
	v_readlane_b32 s26, v254, 50
	v_readlane_b32 s27, v254, 51
	s_mov_b64 s[22:23], -1
	s_and_b64 vcc, exec, s[26:27]
	s_cbranch_vccz .LBB0_363
	v_readlane_b32 s22, v252, 23
	v_readlane_b32 s23, v252, 24
	s_andn2_b64 vcc, exec, s[22:23]
	s_waitcnt vmcnt(0)
	v_mbcnt_lo_u32_b32 v2, -1, 0
	v_mbcnt_hi_u32_b32 v2, -1, v2
	s_cbranch_vccnz .LBB0_362
	v_ashrrev_i32_e32 v0, 3, v2
	v_readlane_b32 s0, v252, 10
	v_and_b32_e32 v4, 7, v2
	v_readlane_b32 s22, v255, 32
	s_waitcnt lgkmcnt(0)
	v_add_u32_e32 v1, s0, v0
	s_movk_i32 s0, 0xb00
	v_mul_lo_u32 v3, v1, s0
	v_lshrrev_b32_e32 v1, 4, v2
	v_bitop3_b32 v1, v1, v4, 3 bitop3:0x6c
	v_lshlrev_b32_e32 v1, 3, v1
	v_or_b32_e32 v3, v1, v3
	s_add_i32 s0, s33, 0
	v_lshlrev_b32_e32 v208, 1, v3
	s_add_i32 m0, s0, 0x11000
	v_readlane_b32 s23, v255, 33
	v_add_u32_e32 v210, 0x58000, v208
	s_add_i32 s5, s0, 0x2200
	s_add_i32 s29, s0, 0x4400
	s_add_i32 s56, s0, 0x6600
	s_nop 0
	global_load_lds_dwordx4 v208, s[22:23]
	s_add_i32 m0, s0, 0x13200
	s_nop 0
	global_load_lds_dwordx4 v210, s[22:23]
	v_readlane_b32 s22, v255, 30
	s_add_i32 m0, s0, 0x15400
	v_readlane_b32 s23, v255, 31
	s_nop 4
	global_load_lds_dwordx4 v208, s[22:23]
	s_add_i32 m0, s0, 0x17600
	s_nop 0
	global_load_lds_dwordx4 v210, s[22:23]
	v_readlane_b32 s22, v253, 49
	s_mov_b32 m0, s0
	v_readlane_b32 s23, v253, 50
	s_nop 4
	global_load_lds_dwordx4 v208, s[22:23]
	s_mov_b32 m0, s5
	s_nop 0
	global_load_lds_dwordx4 v210, s[22:23]
	v_readlane_b32 s22, v253, 51
	s_mov_b32 m0, s29
	v_readlane_b32 s23, v253, 52
	s_nop 4
	global_load_lds_dwordx4 v208, s[22:23]
	s_mov_b32 m0, s56
	s_nop 0
	global_load_lds_dwordx4 v210, s[22:23]
	v_readlane_b32 s22, v252, 13
	v_readlane_b32 s23, v252, 14
	s_andn2_b64 vcc, exec, s[22:23]
	s_nop 0
	v_cndmask_b32_e64 v3, 0, 1, s[22:23]
	v_cmp_ne_u32_e64 s[34:35], 1, v3
	s_cbranch_vccnz .LBB0_276
.LBB0_276:
	v_lshlrev_b32_e32 v12, 7, v2
	v_bfe_i32 v3, v2, 3, 1
	v_and_b32_e32 v12, 0x380, v12
	s_movk_i32 s2, 0x440
	v_and_or_b32 v3, v3, s2, v12
	v_lshlrev_b32_e32 v12, 3, v2
	v_readlane_b32 s40, v255, 32
	v_and_b32_e32 v12, 48, v12
	v_and_b32_e32 v2, -16, v2
	v_mov_b32_e32 v209, v193
	v_readlane_b32 s41, v255, 33
	v_xad_u32 v2, v12, v2, v3
	v_readlane_b32 s2, v254, 12
	v_lshl_add_u64 v[4:5], s[40:41], 0, v[208:209]
	v_mov_b32_e32 v211, v193
	v_readlane_b32 s42, v253, 49
	v_add_u32_e32 v12, s2, v2
	s_mul_i32 s2, s17, 0x1100
	v_lshl_add_u64 v[6:7], s[40:41], 0, v[210:211]
	v_readlane_b32 s43, v253, 50
	v_add_u32_e32 v197, s2, v2
	v_lshl_add_u64 v[2:3], v[4:5], 0, s[6:7]
	s_add_i32 m0, s0, 0x19800
	v_lshl_add_u64 v[8:9], s[42:43], 0, v[208:209]
	s_waitcnt vmcnt(2)
	s_barrier
	global_load_lds_dwordx4 v[2:3], off
	v_lshl_add_u64 v[2:3], v[6:7], 0, s[6:7]
	s_add_i32 m0, s0, 0x1ba00
	s_add_i32 s57, s0, 0x8800
	v_lshl_add_u64 v[10:11], s[42:43], 0, v[210:211]
	global_load_lds_dwordx4 v[2:3], off
	v_lshl_add_u64 v[2:3], v[8:9], 0, s[6:7]
	s_mov_b32 m0, s57
	s_add_i32 s70, s0, 0xaa00
	v_readlane_b32 s22, v255, 34
	global_load_lds_dwordx4 v[2:3], off
	v_lshl_add_u64 v[2:3], v[10:11], 0, s[6:7]
	s_mov_b32 m0, s70
	v_readlane_b32 s23, v255, 35
	global_load_lds_dwordx4 v[2:3], off
	s_nop 0
	v_lshl_add_u64 v[2:3], s[22:23], 0, v[208:209]
	s_add_i32 m0, s0, 0x1dc00
	s_movk_i32 s2, 0xb00
	global_load_lds_dwordx4 v[2:3], off
	v_lshl_add_u64 v[2:3], s[22:23], 0, v[210:211]
	s_add_i32 m0, s0, 0x1fe00
	v_mul_lo_u32 v0, v0, s2
	global_load_lds_dwordx4 v[2:3], off
	v_readlane_b32 s2, v254, 20
	s_waitcnt vmcnt(6)
	v_mov_b32_e32 v213, v193
	v_mov_b32_e32 v215, v193
	v_add_u32_e32 v2, s2, v0
	v_readlane_b32 s2, v254, 21
	v_add_lshl_u32 v212, v2, v1, 1
	s_mov_b32 s71, 0
	v_add_u32_e32 v0, s2, v0
	v_add_lshl_u32 v214, v0, v1, 1
	v_add_u32_e32 v241, 0, v12
	v_readlane_b32 s2, v253, 22
	v_readlane_b32 s10, v253, 48
	s_barrier
	s_branch .LBB0_279

; #define PG8_LAS __attribute__((address_space(3)))
; #define PG8_STAGE(bufoff, gbase, voff) do { _Pragma("unroll") for (int _i = 0; _i < 2; ++_i) \
;         __builtin_amdgcn_global_load_lds((const unsigned*)((const char*)(gbase) + (voff)[_i]), (PG8_LAS unsigned*)(lds + (bufoff) + ldsw + _i * (8 * USTR)), 16, 0, 0); } while (0)
; #define PG8_WAIT_V(n) asm volatile("s_waitcnt vmcnt(" #n ")" ::: "memory")
; #define PG8_WAIT_L(n) asm volatile("s_waitcnt lgkmcnt(" #n ")" ::: "memory")
; #define PG8_BAR __builtin_amdgcn_s_barrier()
; template <class Epi, class Sched, bool ALIGN_EPI, bool SP2>
; __device__ __forceinline__ void gemm_phase(PG8_LAS unsigned char* lds, const Gemm g, const Sched& S, const Epi& E, int wid) {
;     ...
;         const bool has_next = S.next(ui + 1, nxt);
;         const char* nA = has_next ? (const char*)g.A + (size_t)nxt.pm * tstepA : cA; const char* nB = has_next ? (const char*)g.Bt + (size_t)nxt.pn * tstepB : cB;
;         for (int t = 0; t < nt; t += 2) {
;             const bool last = (t == nt - 2);
;             const char* a1 = cA + (size_t)(t + 1) * kstep;
;             const char* a2 = last ? nA : cA + (size_t)(t + 2) * kstep; const char* b2 = last ? nB : cB + (size_t)(t + 2) * kstep;
;             const char* a3 = a2 + kstep; const char* b3 = b2 + kstep;
;             if constexpr (Epi::PRE == 1) { if (last) {
;                 const char* rsrc; const char* ssrc; E.pre(cur, rsrc, ssrc);
; #pragma unroll
;                 for (int _i = 0; _i < 2; ++_i) __builtin_amdgcn_global_load_lds((const unsigned*)(rsrc + (wid + 8 * _i) * 1024 + lane * 16), (PG8_LAS unsigned*)(lds + LDS_XOFF + (wid + 8 * _i) * 1024), 16, 0, 0);
;                 if (wid == 0) __builtin_amdgcn_global_load_lds((const unsigned*)(ssrc + lane * 16), (PG8_LAS unsigned*)(lds + LDS_XOFF + 16384), 16, 0, 0);
;             } }
;             if constexpr (SP2) {
;             PG8_LDB(B0, 0, 0); PG8_LDB(B1, 0, 1); PG8_SCHED; PG8_LDA(At, 0, 0); PG8_STAGE(PG8_SA(1, 1), a1 + hstepA, voffA);
;             PG8_WAIT_V(8); PG8_WAIT_L(0); PG8_BAR; PG8_MMA(0, 0, At, B0); PG8_MMA(0, 1, At, B1); PG8_BAR; PG8_SCHED;
;             PG8_LDA(At, 0, 1); PG8_STAGE(PG8_SB(0, 0), b2, voffB); PG8_STAGE(PG8_SB(0, 1), b2 + hstepB, voffB); PG8_STAGE(PG8_SA(0, 0), a2, voffA);
;             PG8_WAIT_V(8); PG8_WAIT_L(0); PG8_BAR; PG8_MMA(1, 0, At, B0); PG8_MMA(1, 1, At, B1); PG8_BAR; PG8_SCHED;
.LBB0_289:
	s_add_u32 s38, s42, 0xb0080
	s_addc_u32 s39, s43, 0
	s_add_u32 s26, s40, 0x100
	s_addc_u32 s27, s41, 0
	s_mov_b32 s68, -2
	s_waitcnt vmcnt(0)
	s_and_b64 vcc, exec, s[34:35]
	s_cbranch_vccnz .Lhb_down
	s_barrier
.Lhb_down:
	s_add_u32 s40, s38, 0xfff50080
	s_addc_u32 s41, s39, -1
	s_add_i32 s69, 0, 0x11000
	s_cmp_eq_u32 s68, 40
	s_cselect_b32 s43, s23, s41
	s_cselect_b32 s42, s22, s40
	s_cselect_b32 s41, s45, s27
	s_cselect_b32 s40, s44, s26
	s_add_i32 s76, 0, 0x15400
	v_add_u32_e32 v52, s69, v197
	v_add_u32_e32 v156, s76, v197
	ds_read_b128 v[40:43], v52
	ds_read_b128 v[44:47], v52 offset:64
	ds_read_b128 v[48:51], v52 offset:2176
	ds_read_b128 v[52:55], v52 offset:2240
	ds_read_b128 v[144:147], v156
	ds_read_b128 v[148:151], v156 offset:64
	ds_read_b128 v[152:155], v156 offset:2176
	ds_read_b128 v[156:159], v156 offset:2240
	v_lshl_add_u64 v[198:199], s[38:39], 0, v[212:213]
	s_add_i32 m0, s0, 0xcc00
	ds_read_b128 v[160:163], v241
	ds_read_b128 v[164:167], v241 offset:64
	ds_read_b128 v[168:171], v241 offset:2176
	ds_read_b128 v[172:175], v241 offset:2240
	ds_read_b128 v[176:179], v241 offset:4352
	ds_read_b128 v[180:183], v241 offset:4416
	ds_read_b128 v[184:187], v241 offset:6528
	ds_read_b128 v[188:191], v241 offset:6592
	global_load_lds_dwordx4 v[198:199], off
	v_lshl_add_u64 v[198:199], s[38:39], 0, v[214:215]
	s_add_i32 m0, s0, 0xee00
	s_nop 0
	global_load_lds_dwordx4 v[198:199], off
	s_waitcnt vmcnt(8)
	s_waitcnt lgkmcnt(0)
	s_barrier
	s_setprio 1
	s_waitcnt lgkmcnt(0)
	v_mfma_f32_16x16x32_bf16 v[132:135], v[40:43], v[160:163], 0
	v_mfma_f32_16x16x32_bf16 v[128:131], v[48:51], v[160:163], 0
	v_mfma_f32_16x16x32_bf16 v[124:127], v[40:43], v[168:171], 0
	v_mfma_f32_16x16x32_bf16 v[120:123], v[48:51], v[168:171], 0
	v_mfma_f32_16x16x32_bf16 v[108:111], v[40:43], v[176:179], 0
	v_mfma_f32_16x16x32_bf16 v[104:107], v[48:51], v[176:179], 0
	v_mfma_f32_16x16x32_bf16 v[92:95], v[40:43], v[184:187], 0
	v_mfma_f32_16x16x32_bf16 v[88:91], v[48:51], v[184:187], 0
	v_mfma_f32_16x16x32_bf16 v[132:135], v[44:47], v[164:167], v[132:135]
	v_mfma_f32_16x16x32_bf16 v[128:131], v[52:55], v[164:167], v[128:131]
	v_mfma_f32_16x16x32_bf16 v[124:127], v[44:47], v[172:175], v[124:127]
	v_mfma_f32_16x16x32_bf16 v[120:123], v[52:55], v[172:175], v[120:123]
	v_mfma_f32_16x16x32_bf16 v[108:111], v[44:47], v[180:183], v[108:111]
	v_mfma_f32_16x16x32_bf16 v[104:107], v[52:55], v[180:183], v[104:107]
	v_mfma_f32_16x16x32_bf16 v[92:95], v[44:47], v[188:191], v[92:95]
	v_mfma_f32_16x16x32_bf16 v[88:91], v[52:55], v[188:191], v[88:91]
	s_setprio 0
	s_setprio 1
	v_mfma_f32_16x16x32_bf16 v[140:143], v[144:147], v[160:163], 0
	v_mfma_f32_16x16x32_bf16 v[136:139], v[152:155], v[160:163], 0
	v_mfma_f32_16x16x32_bf16 v[116:119], v[144:147], v[168:171], 0
	v_mfma_f32_16x16x32_bf16 v[112:115], v[152:155], v[168:171], 0
	v_mfma_f32_16x16x32_bf16 v[100:103], v[144:147], v[176:179], 0
	v_mfma_f32_16x16x32_bf16 v[96:99], v[152:155], v[176:179], 0
	v_mfma_f32_16x16x32_bf16 v[84:87], v[144:147], v[184:187], 0
	v_mfma_f32_16x16x32_bf16 v[80:83], v[152:155], v[184:187], 0
	v_mfma_f32_16x16x32_bf16 v[140:143], v[148:151], v[164:167], v[140:143]
	v_mfma_f32_16x16x32_bf16 v[136:139], v[156:159], v[164:167], v[136:139]
	v_mfma_f32_16x16x32_bf16 v[116:119], v[148:151], v[172:175], v[116:119]
	v_mfma_f32_16x16x32_bf16 v[112:115], v[156:159], v[172:175], v[112:115]
	v_mfma_f32_16x16x32_bf16 v[100:103], v[148:151], v[180:183], v[100:103]
	v_mfma_f32_16x16x32_bf16 v[96:99], v[156:159], v[180:183], v[96:99]
	v_mfma_f32_16x16x32_bf16 v[84:87], v[148:151], v[188:191], v[84:87]
	v_mfma_f32_16x16x32_bf16 v[80:83], v[156:159], v[188:191], v[80:83]
	s_setprio 0
	s_barrier
	s_add_i32 s69, s69, s33
	v_lshl_add_u64 v[198:199], s[40:41], 0, v[208:209]
	s_mov_b32 m0, s69
	ds_read_b128 v[160:163], v241 offset:17408
	ds_read_b128 v[164:167], v241 offset:17472
	ds_read_b128 v[168:171], v241 offset:19584
	ds_read_b128 v[172:175], v241 offset:19648
	ds_read_b128 v[176:179], v241 offset:21760
	ds_read_b128 v[180:183], v241 offset:21824
	ds_read_b128 v[184:187], v241 offset:23936
	ds_read_b128 v[188:191], v241 offset:24000
	global_load_lds_dwordx4 v[198:199], off
	s_add_i32 m0, s69, 0x2200
	s_add_u32 s74, s40, 0xb0000
	v_lshl_add_u64 v[200:201], s[40:41], 0, v[210:211]
	s_addc_u32 s75, s41, 0
	s_add_i32 s69, s76, s33
	global_load_lds_dwordx4 v[200:201], off
	v_lshl_add_u64 v[216:217], s[74:75], 0, v[208:209]
	s_mov_b32 m0, s69
	v_lshl_add_u64 v[218:219], s[42:43], 0, v[210:211]
	global_load_lds_dwordx4 v[216:217], off
	v_lshl_add_u64 v[216:217], s[74:75], 0, v[210:211]
	s_add_i32 m0, s69, 0x2200
	s_nop 0
	global_load_lds_dwordx4 v[216:217], off
	v_lshl_add_u64 v[216:217], s[42:43], 0, v[208:209]
	s_mov_b32 m0, s0
	s_nop 0
	global_load_lds_dwordx4 v[216:217], off
	s_mov_b32 m0, s5
	s_nop 0
	global_load_lds_dwordx4 v[218:219], off
	s_waitcnt vmcnt(8)
	s_waitcnt lgkmcnt(0)
	s_barrier
; #define PG8_STAGE(bufoff, gbase, voff) do { _Pragma("unroll") for (int _i = 0; _i < 2; ++_i) \
;         __builtin_amdgcn_global_load_lds((const unsigned*)((const char*)(gbase) + (voff)[_i]), (PG8_LAS unsigned*)(lds + (bufoff) + ldsw + _i * (8 * USTR)), 16, 0, 0); } while (0)
; #define PG8_LDA(dst, b, h) do { _Pragma("unroll") for (int m = 0; m < 4; ++m) _Pragma("unroll") for (int k = 0; k < 2; ++k) dst[m][k] = *(const PG8_LAS bf16x8*)(lds + PG8_SA(b, h) + aoff + m * (2 * USTR) + k * 64); } while (0)
; #define PG8_LDB(dst, b, h) do { _Pragma("unroll") for (int n = 0; n < 2; ++n) _Pragma("unroll") for (int k = 0; k < 2; ++k) dst[n][k] = *(const PG8_LAS bf16x8*)(lds + PG8_SB(b, h) + boff + n * (2 * USTR) + k * 64); } while (0)
; #define PG8_MMA(ai, bj, At, Bt) do { __builtin_amdgcn_s_setprio(1); _Pragma("unroll") for (int m = 0; m < 4; ++m) _Pragma("unroll") for (int n = 0; n < 2; ++n) _Pragma("unroll") for (int k = 0; k < 2; ++k) \
;         acc[ai][bj][m][n] = __builtin_amdgcn_mfma_f32_16x16x32_bf16(Bt[n][k], At[m][k], acc[ai][bj][m][n], 0, 0, 0); __builtin_amdgcn_s_setprio(0); } while (0)
; #define PG8_WAIT_V(n) asm volatile("s_waitcnt vmcnt(" #n ")" ::: "memory")
; #define PG8_WAIT_L(n) asm volatile("s_waitcnt lgkmcnt(" #n ")" ::: "memory")
; #define PG8_BAR __builtin_amdgcn_s_barrier()
; #define PG8_SCHED __builtin_amdgcn_sched_barrier(0)
; template <class Epi, class Sched, bool ALIGN_EPI, bool SP2>
; __device__ __forceinline__ void gemm_phase(PG8_LAS unsigned char* lds, const Gemm g, const Sched& S, const Epi& E, int wid) {
;     ...
;             PG8_WAIT_V(8); PG8_WAIT_L(0); PG8_BAR; PG8_MMA(1, 0, At, B0); PG8_MMA(1, 1, At, B1); PG8_BAR; PG8_SCHED;
;             PG8_LDB(B0, 1, 0); PG8_LDB(B1, 1, 1); PG8_SCHED; PG8_LDA(At, 1, 0); PG8_STAGE(PG8_SA(0, 1), a2 + hstepA, voffA);
;             PG8_WAIT_V(8); PG8_WAIT_L(0); PG8_BAR; PG8_MMA(0, 0, At, B0); PG8_MMA(0, 1, At, B1); PG8_BAR; PG8_SCHED;
	s_setprio 1
	s_waitcnt lgkmcnt(0)
	v_mfma_f32_16x16x32_bf16 v[76:79], v[40:43], v[160:163], 0
	v_mfma_f32_16x16x32_bf16 v[72:75], v[48:51], v[160:163], 0
	v_mfma_f32_16x16x32_bf16 v[60:63], v[40:43], v[168:171], 0
	v_mfma_f32_16x16x32_bf16 v[56:59], v[48:51], v[168:171], 0
	v_mfma_f32_16x16x32_bf16 v[24:27], v[40:43], v[176:179], 0
	v_mfma_f32_16x16x32_bf16 v[28:31], v[48:51], v[176:179], 0
	v_mfma_f32_16x16x32_bf16 v[8:11], v[40:43], v[184:187], 0
	v_mfma_f32_16x16x32_bf16 v[12:15], v[48:51], v[184:187], 0
	v_mfma_f32_16x16x32_bf16 v[76:79], v[44:47], v[164:167], v[76:79]
	v_mfma_f32_16x16x32_bf16 v[72:75], v[52:55], v[164:167], v[72:75]
	v_mfma_f32_16x16x32_bf16 v[60:63], v[44:47], v[172:175], v[60:63]
	v_mfma_f32_16x16x32_bf16 v[56:59], v[52:55], v[172:175], v[56:59]
	v_mfma_f32_16x16x32_bf16 v[24:27], v[44:47], v[180:183], v[24:27]
	v_mfma_f32_16x16x32_bf16 v[28:31], v[52:55], v[180:183], v[28:31]
	v_mfma_f32_16x16x32_bf16 v[8:11], v[44:47], v[188:191], v[8:11]
	v_mfma_f32_16x16x32_bf16 v[12:15], v[52:55], v[188:191], v[12:15]
	s_setprio 0
	s_setprio 1
	v_mfma_f32_16x16x32_bf16 v[36:39], v[144:147], v[168:171], 0
	v_mfma_f32_16x16x32_bf16 v[32:35], v[152:155], v[168:171], 0
	v_mfma_f32_16x16x32_bf16 v[20:23], v[144:147], v[176:179], 0
	v_mfma_f32_16x16x32_bf16 v[16:19], v[152:155], v[176:179], 0
	v_mfma_f32_16x16x32_bf16 v[4:7], v[144:147], v[184:187], 0
	v_mfma_f32_16x16x32_bf16 v[0:3], v[152:155], v[184:187], 0
	v_mfma_f32_16x16x32_bf16 v[40:43], v[144:147], v[160:163], 0
	v_mfma_f32_16x16x32_bf16 v[44:47], v[152:155], v[160:163], 0
	v_mfma_f32_16x16x32_bf16 v[36:39], v[148:151], v[172:175], v[36:39]
	v_mfma_f32_16x16x32_bf16 v[32:35], v[156:159], v[172:175], v[32:35]
	v_mfma_f32_16x16x32_bf16 v[20:23], v[148:151], v[180:183], v[20:23]
	v_mfma_f32_16x16x32_bf16 v[16:19], v[156:159], v[180:183], v[16:19]
	v_mfma_f32_16x16x32_bf16 v[4:7], v[148:151], v[188:191], v[4:7]
	v_mfma_f32_16x16x32_bf16 v[0:3], v[156:159], v[188:191], v[0:3]
	v_mfma_f32_16x16x32_bf16 v[40:43], v[148:151], v[164:167], v[40:43]
	v_mfma_f32_16x16x32_bf16 v[44:47], v[156:159], v[164:167], v[44:47]
	s_setprio 0
	s_barrier
	s_add_i32 s69, 0, 0x19800
	s_add_i32 s74, 0, 0x1dc00
	v_add_u32_e32 v68, s69, v197
	v_add_u32_e32 v156, s74, v197
	ds_read_b128 v[48:51], v68
	ds_read_b128 v[52:55], v68 offset:64
	ds_read_b128 v[64:67], v68 offset:2176
	ds_read_b128 v[68:71], v68 offset:2240
	ds_read_b128 v[144:147], v156
	ds_read_b128 v[148:151], v156 offset:64
	ds_read_b128 v[152:155], v156 offset:2176
	ds_read_b128 v[156:159], v156 offset:2240
	s_add_u32 s42, s42, 0xb0000
	s_addc_u32 s43, s43, 0
	s_mov_b32 m0, s29
	v_lshl_add_u64 v[220:221], s[42:43], 0, v[208:209]
	ds_read_b128 v[160:163], v241 offset:34816
	ds_read_b128 v[164:167], v241 offset:34880
	ds_read_b128 v[168:171], v241 offset:36992
	ds_read_b128 v[172:175], v241 offset:37056
	ds_read_b128 v[176:179], v241 offset:39168
	ds_read_b128 v[180:183], v241 offset:39232
	ds_read_b128 v[184:187], v241 offset:41344
	ds_read_b128 v[188:191], v241 offset:41408
	global_load_lds_dwordx4 v[220:221], off
	v_lshl_add_u64 v[220:221], s[42:43], 0, v[210:211]
	s_mov_b32 m0, s56
	s_nop 0
	global_load_lds_dwordx4 v[220:221], off
	s_waitcnt vmcnt(8)
	s_waitcnt lgkmcnt(0)
	s_barrier
	s_setprio 1
	s_waitcnt lgkmcnt(0)
	v_mfma_f32_16x16x32_bf16 v[132:135], v[48:51], v[160:163], v[132:135]
	v_mfma_f32_16x16x32_bf16 v[128:131], v[64:67], v[160:163], v[128:131]
	v_mfma_f32_16x16x32_bf16 v[124:127], v[48:51], v[168:171], v[124:127]
	v_mfma_f32_16x16x32_bf16 v[120:123], v[64:67], v[168:171], v[120:123]
	v_mfma_f32_16x16x32_bf16 v[108:111], v[48:51], v[176:179], v[108:111]
	v_mfma_f32_16x16x32_bf16 v[104:107], v[64:67], v[176:179], v[104:107]
	v_mfma_f32_16x16x32_bf16 v[92:95], v[48:51], v[184:187], v[92:95]
	v_mfma_f32_16x16x32_bf16 v[88:91], v[64:67], v[184:187], v[88:91]
	v_mfma_f32_16x16x32_bf16 v[132:135], v[52:55], v[164:167], v[132:135]
	v_mfma_f32_16x16x32_bf16 v[128:131], v[68:71], v[164:167], v[128:131]
	v_mfma_f32_16x16x32_bf16 v[124:127], v[52:55], v[172:175], v[124:127]
	v_mfma_f32_16x16x32_bf16 v[120:123], v[68:71], v[172:175], v[120:123]
	v_mfma_f32_16x16x32_bf16 v[108:111], v[52:55], v[180:183], v[108:111]
	v_mfma_f32_16x16x32_bf16 v[104:107], v[68:71], v[180:183], v[104:107]
	v_mfma_f32_16x16x32_bf16 v[92:95], v[52:55], v[188:191], v[92:95]
	v_mfma_f32_16x16x32_bf16 v[88:91], v[68:71], v[188:191], v[88:91]
	s_setprio 0
	s_setprio 1
	v_mfma_f32_16x16x32_bf16 v[140:143], v[144:147], v[160:163], v[140:143]
	v_mfma_f32_16x16x32_bf16 v[136:139], v[152:155], v[160:163], v[136:139]
	v_mfma_f32_16x16x32_bf16 v[116:119], v[144:147], v[168:171], v[116:119]
	v_mfma_f32_16x16x32_bf16 v[112:115], v[152:155], v[168:171], v[112:115]
	v_mfma_f32_16x16x32_bf16 v[100:103], v[144:147], v[176:179], v[100:103]
	v_mfma_f32_16x16x32_bf16 v[96:99], v[152:155], v[176:179], v[96:99]
	v_mfma_f32_16x16x32_bf16 v[84:87], v[144:147], v[184:187], v[84:87]
	v_mfma_f32_16x16x32_bf16 v[80:83], v[152:155], v[184:187], v[80:83]
	v_mfma_f32_16x16x32_bf16 v[140:143], v[148:151], v[164:167], v[140:143]
	v_mfma_f32_16x16x32_bf16 v[136:139], v[156:159], v[164:167], v[136:139]
	v_mfma_f32_16x16x32_bf16 v[116:119], v[148:151], v[172:175], v[116:119]
	v_mfma_f32_16x16x32_bf16 v[112:115], v[156:159], v[172:175], v[112:115]
	v_mfma_f32_16x16x32_bf16 v[100:103], v[148:151], v[180:183], v[100:103]
	v_mfma_f32_16x16x32_bf16 v[96:99], v[156:159], v[180:183], v[96:99]
	v_mfma_f32_16x16x32_bf16 v[84:87], v[148:151], v[188:191], v[84:87]
	v_mfma_f32_16x16x32_bf16 v[80:83], v[156:159], v[188:191], v[80:83]
	s_setprio 0
	s_barrier
; #define PG8_STAGE(bufoff, gbase, voff) do { _Pragma("unroll") for (int _i = 0; _i < 2; ++_i) \
;         __builtin_amdgcn_global_load_lds((const unsigned*)((const char*)(gbase) + (voff)[_i]), (PG8_LAS unsigned*)(lds + (bufoff) + ldsw + _i * (8 * USTR)), 16, 0, 0); } while (0)
; #define PG8_LDA(dst, b, h) do { _Pragma("unroll") for (int m = 0; m < 4; ++m) _Pragma("unroll") for (int k = 0; k < 2; ++k) dst[m][k] = *(const PG8_LAS bf16x8*)(lds + PG8_SA(b, h) + aoff + m * (2 * USTR) + k * 64); } while (0)
; #define PG8_MMA(ai, bj, At, Bt) do { __builtin_amdgcn_s_setprio(1); _Pragma("unroll") for (int m = 0; m < 4; ++m) _Pragma("unroll") for (int n = 0; n < 2; ++n) _Pragma("unroll") for (int k = 0; k < 2; ++k) \
;         acc[ai][bj][m][n] = __builtin_amdgcn_mfma_f32_16x16x32_bf16(Bt[n][k], At[m][k], acc[ai][bj][m][n], 0, 0, 0); __builtin_amdgcn_s_setprio(0); } while (0)
; #define PG8_WAIT_V(n) asm volatile("s_waitcnt vmcnt(" #n ")" ::: "memory")
; #define PG8_WAIT_L(n) asm volatile("s_waitcnt lgkmcnt(" #n ")" ::: "memory")
; #define PG8_BAR __builtin_amdgcn_s_barrier()
; #define PG8_SCHED __builtin_amdgcn_sched_barrier(0)
; template <class Epi, class Sched, bool ALIGN_EPI, bool SP2>
; __device__ __forceinline__ void gemm_phase(PG8_LAS unsigned char* lds, const Gemm g, const Sched& S, const Epi& E, int wid) {
;     ...
;             PG8_LDA(At, 1, 1); PG8_STAGE(PG8_SB(1, 0), b3, voffB); PG8_STAGE(PG8_SB(1, 1), b3 + hstepB, voffB); PG8_STAGE(PG8_SA(1, 0), a3, voffA);
;             PG8_WAIT_V(8); PG8_WAIT_L(0); PG8_BAR; PG8_MMA(1, 0, At, B0); PG8_MMA(1, 1, At, B1); PG8_BAR; PG8_SCHED;
	s_add_i32 s42, s69, s33
	v_lshl_add_u64 v[198:199], v[198:199], 0, s[6:7]
	s_mov_b32 m0, s42
	ds_read_b128 v[160:163], v241 offset:52224
	ds_read_b128 v[164:167], v241 offset:52288
	ds_read_b128 v[168:171], v241 offset:54400
	ds_read_b128 v[172:175], v241 offset:54464
	ds_read_b128 v[176:179], v241 offset:56576
	ds_read_b128 v[180:183], v241 offset:56640
	ds_read_b128 v[184:187], v241 offset:58752
	ds_read_b128 v[188:191], v241 offset:58816
	global_load_lds_dwordx4 v[198:199], off
	s_add_i32 m0, s42, 0x2200
	s_add_u32 s40, s40, 0xb0080
	v_lshl_add_u64 v[198:199], v[200:201], 0, s[6:7]
	s_addc_u32 s41, s41, 0
	s_add_i32 s42, s74, s33
	global_load_lds_dwordx4 v[198:199], off
	v_lshl_add_u64 v[198:199], s[40:41], 0, v[208:209]
	s_mov_b32 m0, s42
	s_nop 0
	global_load_lds_dwordx4 v[198:199], off
	v_lshl_add_u64 v[198:199], s[40:41], 0, v[210:211]
	s_add_i32 m0, s42, 0x2200
	s_nop 0
	global_load_lds_dwordx4 v[198:199], off
	v_lshl_add_u64 v[198:199], v[216:217], 0, s[6:7]
	s_mov_b32 m0, s57
	s_nop 0
	global_load_lds_dwordx4 v[198:199], off
	v_lshl_add_u64 v[198:199], v[218:219], 0, s[6:7]
	s_mov_b32 m0, s70
	s_nop 0
	global_load_lds_dwordx4 v[198:199], off
	s_waitcnt vmcnt(8)
	s_waitcnt lgkmcnt(0)
	s_barrier
	s_setprio 1
	s_waitcnt lgkmcnt(0)
	v_mfma_f32_16x16x32_bf16 v[76:79], v[48:51], v[160:163], v[76:79]
	v_mfma_f32_16x16x32_bf16 v[72:75], v[64:67], v[160:163], v[72:75]
	v_mfma_f32_16x16x32_bf16 v[60:63], v[48:51], v[168:171], v[60:63]
	v_mfma_f32_16x16x32_bf16 v[56:59], v[64:67], v[168:171], v[56:59]
	v_mfma_f32_16x16x32_bf16 v[24:27], v[48:51], v[176:179], v[24:27]
	v_mfma_f32_16x16x32_bf16 v[28:31], v[64:67], v[176:179], v[28:31]
	v_mfma_f32_16x16x32_bf16 v[8:11], v[48:51], v[184:187], v[8:11]
	v_mfma_f32_16x16x32_bf16 v[12:15], v[64:67], v[184:187], v[12:15]
	v_mfma_f32_16x16x32_bf16 v[76:79], v[52:55], v[164:167], v[76:79]
	v_mfma_f32_16x16x32_bf16 v[72:75], v[68:71], v[164:167], v[72:75]
	v_mfma_f32_16x16x32_bf16 v[60:63], v[52:55], v[172:175], v[60:63]
	v_mfma_f32_16x16x32_bf16 v[56:59], v[68:71], v[172:175], v[56:59]
	v_mfma_f32_16x16x32_bf16 v[24:27], v[52:55], v[180:183], v[24:27]
	v_mfma_f32_16x16x32_bf16 v[28:31], v[68:71], v[180:183], v[28:31]
	v_mfma_f32_16x16x32_bf16 v[8:11], v[52:55], v[188:191], v[8:11]
	v_mfma_f32_16x16x32_bf16 v[12:15], v[68:71], v[188:191], v[12:15]
	s_setprio 0
	s_setprio 1
	v_mfma_f32_16x16x32_bf16 v[40:43], v[144:147], v[160:163], v[40:43]
	v_mfma_f32_16x16x32_bf16 v[68:71], v[148:151], v[164:167], v[40:43]
	v_mfma_f32_16x16x32_bf16 v[40:43], v[152:155], v[160:163], v[44:47]
	v_mfma_f32_16x16x32_bf16 v[36:39], v[144:147], v[168:171], v[36:39]
	v_mfma_f32_16x16x32_bf16 v[32:35], v[152:155], v[168:171], v[32:35]
	v_mfma_f32_16x16x32_bf16 v[20:23], v[144:147], v[176:179], v[20:23]
	v_mfma_f32_16x16x32_bf16 v[16:19], v[152:155], v[176:179], v[16:19]
	v_mfma_f32_16x16x32_bf16 v[4:7], v[144:147], v[184:187], v[4:7]
	v_mfma_f32_16x16x32_bf16 v[0:3], v[152:155], v[184:187], v[0:3]
	v_mfma_f32_16x16x32_bf16 v[64:67], v[156:159], v[164:167], v[40:43]
	v_mfma_f32_16x16x32_bf16 v[36:39], v[148:151], v[172:175], v[36:39]
	v_mfma_f32_16x16x32_bf16 v[32:35], v[156:159], v[172:175], v[32:35]
	v_mfma_f32_16x16x32_bf16 v[20:23], v[148:151], v[180:183], v[20:23]
	v_mfma_f32_16x16x32_bf16 v[16:19], v[156:159], v[180:183], v[16:19]
	v_mfma_f32_16x16x32_bf16 v[4:7], v[148:151], v[188:191], v[4:7]
	v_mfma_f32_16x16x32_bf16 v[0:3], v[156:159], v[188:191], v[0:3]
	s_setprio 0
	s_barrier
	s_add_i32 s68, s68, 2
	s_add_u32 s38, s38, 0x100
	s_addc_u32 s39, s39, 0
	s_add_u32 s26, s26, 0x100
	s_addc_u32 s27, s27, 0
	s_cmp_gt_u32 s68, 41

; #define PG8_BAR __builtin_amdgcn_s_barrier()
; template <class Epi, class Sched, bool ALIGN_EPI, bool SP2>
; __device__ __forceinline__ void gemm_phase(PG8_LAS unsigned char* lds, const Gemm g, const Sched& S, const Epi& E, int wid) {
;     ...
;         if (!has_next) break;
; #pragma unroll
;         for (int a = 0; a < 2; ++a)
; #pragma unroll
;             for (int b = 0; b < 2; ++b)
; #pragma unroll
;                 for (int m = 0; m < 4; ++m)
; #pragma unroll
;                     for (int n = 0; n < 2; ++n) acc[a][b][m][n] = (f32x4){0.f, 0.f, 0.f, 0.f};
;         cur = nxt; cA = nA; cB = nB; ++ui;
;         if constexpr (ALIGN_EPI) { if (wr == 1) PG8_BAR; }
;     }
.LBB0_357:
	s_or_b64 exec, exec, s[26:27]
	s_and_b64 vcc, exec, s[36:37]
	s_mov_b64 s[26:27], -1
	s_cbranch_vccnz .LBB0_278
	s_and_b64 vcc, exec, s[34:35]
	s_cbranch_vccnz .LBB0_277
	s_branch .LBB0_277

; #define PG8_STAGE(bufoff, gbase, voff) do { _Pragma("unroll") for (int _i = 0; _i < 2; ++_i) \
;         __builtin_amdgcn_global_load_lds((const unsigned*)((const char*)(gbase) + (voff)[_i]), (PG8_LAS unsigned*)(lds + (bufoff) + ldsw + _i * (8 * USTR)), 16, 0, 0); } while (0)
; #define PG8_WAIT_V(n) asm volatile("s_waitcnt vmcnt(" #n ")" ::: "memory")
; #define PG8_BAR __builtin_amdgcn_s_barrier()
; template <class Epi, class Sched, bool ALIGN_EPI, bool SP2>
; __device__ __forceinline__ void gemm_phase(PG8_LAS unsigned char* lds, const Gemm g, const Sched& S, const Epi& E, int wid) {
;     ...
; #pragma unroll
;     for (int i = 0; i < 2; ++i) { const int u_ = wid + 8 * i, rr_ = lane >> 3, ch_ = (lane & 7) ^ ((rr_ >> 1) & 3); const int R = u_ * 8 + rr_, C = ch_ * 8;
;         const int Rb = Epi::PERM ? ((R & ~31) + perm32(R & 31)) : R;
;         voffA[i] = (unsigned)(R * lda + C) * 2u; voffB[i] = (unsigned)(Rb * K + C) * 2u; }
;     ...
;     if constexpr (SP2) {
;         PG8_STAGE(PG8_SB(0, 0), cB, voffB); PG8_STAGE(PG8_SB(0, 1), cB + hstepB, voffB); PG8_STAGE(PG8_SA(0, 0), cA, voffA); PG8_STAGE(PG8_SA(0, 1), cA + hstepA, voffA);
;         if (wr == 1) PG8_BAR;
;         PG8_WAIT_V(2); PG8_BAR;
;         PG8_STAGE(PG8_SB(1, 0), cB + kstep, voffB); PG8_STAGE(PG8_SA(1, 0), cA + kstep, voffA); PG8_STAGE(PG8_SB(1, 1), cB + hstepB + kstep, voffB);
;         PG8_WAIT_V(6); PG8_BAR;
.LBB0_363:
	s_andn2_b64 vcc, exec, s[22:23]
	s_cbranch_vccnz .LBB0_383
	v_readlane_b32 s22, v252, 27
	v_readlane_b32 s23, v252, 28
	s_andn2_b64 vcc, exec, s[22:23]
	s_waitcnt lgkmcnt(0)
	v_mbcnt_lo_u32_b32 v1, -1, 0
	v_mbcnt_hi_u32_b32 v1, -1, v1
	s_cbranch_vccnz .LBB0_383
	s_waitcnt vmcnt(0)
	v_ashrrev_i32_e32 v2, 3, v1
	v_readlane_b32 s0, v252, 10
	v_and_b32_e32 v6, 3, v2
	v_lshlrev_b32_e32 v0, 4, v1
	v_add_u32_e32 v4, s0, v2
	v_add_u32_e32 v5, 64, v4
	s_mov_b32 s0, 0x1fffe0
	v_lshrrev_b32_e32 v7, 2, v4
	v_lshlrev_b32_e32 v8, 1, v4
	v_and_or_b32 v3, v5, s0, v6
	v_and_b32_e32 v7, 4, v7
	v_and_b32_e32 v8, 24, v8
	v_or3_b32 v3, v3, v7, v8
	v_lshlrev_b32_e32 v9, 11, v3
	v_and_b32_e32 v10, 0x70, v0
	v_and_b32_e32 v3, 48, v1
	v_lshlrev_b32_e32 v5, 11, v5
	v_bitop3_b32 v146, v5, v10, v3 bitop3:0xf6
	v_and_or_b32 v5, v4, s0, v6
	v_or3_b32 v5, v5, v7, v8
	v_lshlrev_b32_e32 v5, 11, v5
	s_add_i32 s0, s33, 0
	v_readlane_b32 s22, v255, 8
	v_bitop3_b32 v192, v5, v10, v3 bitop3:0xf6
	s_add_i32 m0, s0, 0x11000
	v_readlane_b32 s23, v255, 9
	v_bitop3_b32 v144, v9, v10, v3 bitop3:0xf6
	v_lshlrev_b32_e32 v4, 11, v4
	v_bitop3_b32 v148, v4, v10, v3 bitop3:0xf6
	s_add_i32 s5, s0, 0x2200
	s_add_i32 s10, s0, 0x4400
	global_load_lds_dwordx4 v192, s[22:23]
	s_add_i32 m0, s0, 0x13200
	s_add_i32 s29, s0, 0x6600
	global_load_lds_dwordx4 v144, s[22:23]
	v_readlane_b32 s22, v255, 0
	s_add_i32 m0, s0, 0x15400
	v_readlane_b32 s23, v255, 1
	s_nop 4
	global_load_lds_dwordx4 v192, s[22:23]
	s_add_i32 m0, s0, 0x17600
	s_nop 0
	global_load_lds_dwordx4 v144, s[22:23]
	v_readlane_b32 s22, v255, 4
	s_mov_b32 m0, s0
	v_readlane_b32 s23, v255, 5
	s_nop 4
	global_load_lds_dwordx4 v148, s[22:23]
	s_mov_b32 m0, s5
	s_nop 0
	global_load_lds_dwordx4 v146, s[22:23]
	v_readlane_b32 s22, v255, 6
	s_mov_b32 m0, s10
	v_readlane_b32 s23, v255, 7
	s_nop 4
	global_load_lds_dwordx4 v148, s[22:23]
	s_mov_b32 m0, s29
	s_nop 0
	global_load_lds_dwordx4 v146, s[22:23]
	v_readlane_b32 s22, v252, 13
	v_readlane_b32 s23, v252, 14
	s_andn2_b64 vcc, exec, s[22:23]
	s_nop 0
	v_cndmask_b32_e64 v4, 0, 1, s[22:23]
	v_cmp_ne_u32_e64 s[34:35], 1, v4
	s_cbranch_vccnz .LBB0_367
.LBB0_367:
	v_readlane_b32 s68, v255, 8
	v_readlane_b32 s69, v255, 9
	v_mov_b32_e32 v145, v193
	v_readlane_b32 s38, v255, 4
	v_lshl_add_u64 v[4:5], s[68:69], 0, v[192:193]
	v_lshl_add_u64 v[6:7], s[68:69], 0, v[144:145]
	v_mov_b32_e32 v149, v193
	v_readlane_b32 s39, v255, 5
	v_lshl_add_u64 v[4:5], v[4:5], 0, s[6:7]
	s_add_i32 m0, s0, 0x19800
	v_lshl_add_u64 v[8:9], s[38:39], 0, v[148:149]
	v_mov_b32_e32 v147, v193
	s_waitcnt vmcnt(2)
	s_barrier
	global_load_lds_dwordx4 v[4:5], off
	v_lshl_add_u64 v[4:5], v[6:7], 0, s[6:7]
	s_add_i32 m0, s0, 0x1ba00
	s_add_i32 s56, s0, 0x8800
	v_lshl_add_u64 v[10:11], s[38:39], 0, v[146:147]
	global_load_lds_dwordx4 v[4:5], off
	v_lshl_add_u64 v[4:5], v[8:9], 0, s[6:7]
	s_mov_b32 m0, s56
	s_add_i32 s57, s0, 0xaa00
	v_readlane_b32 s22, v255, 10
	global_load_lds_dwordx4 v[4:5], off
	v_lshl_add_u64 v[4:5], v[10:11], 0, s[6:7]
	s_mov_b32 m0, s57
	v_readlane_b32 s23, v255, 11
	global_load_lds_dwordx4 v[4:5], off
	s_nop 0
	v_lshl_add_u64 v[4:5], s[22:23], 0, v[192:193]
	s_add_i32 m0, s0, 0x1dc00
	s_movk_i32 s2, 0x70
	global_load_lds_dwordx4 v[4:5], off
	v_lshl_add_u64 v[4:5], s[22:23], 0, v[144:145]
	s_add_i32 m0, s0, 0x1fe00
	v_lshlrev_b32_e32 v13, 7, v1
	global_load_lds_dwordx4 v[4:5], off
	v_bitop3_b32 v3, v0, v3, s2 bitop3:0x6c
	v_bfe_i32 v12, v1, 3, 1
	v_and_b32_e32 v13, 0x380, v13
	s_movk_i32 s2, 0x440
	v_and_or_b32 v12, v12, s2, v13
	v_lshlrev_b32_e32 v13, 3, v1
	v_and_b32_e32 v13, 48, v13
	v_and_b32_e32 v1, -16, v1
	v_xad_u32 v1, v13, v1, v12
	v_readlane_b32 s2, v254, 12
	v_readlane_b32 s22, v254, 54
	v_readlane_b32 s23, v254, 55
	v_add_u32_e32 v12, s2, v1
	s_mul_i32 s2, s17, 0x1100
	v_add_u32_e32 v161, s2, v1
	v_ashrrev_i32_e32 v1, 31, v0
	s_waitcnt vmcnt(6)
	v_lshl_add_u64 v[150:151], s[96:97], 0, v[0:1]
	v_lshl_add_u64 v[152:153], s[22:23], 0, v[0:1]
	v_lshlrev_b32_e32 v0, 11, v2
	v_readlane_b32 s2, v254, 17
	v_readlane_b32 s26, v253, 30
	v_mov_b32_e32 v155, v193
	v_add3_u32 v154, s2, v3, v0
	v_readlane_b32 s2, v254, 18
	v_mov_b32_e32 v157, v193
	s_mov_b32 s72, 0
	v_add3_u32 v156, s2, v3, v0
	v_add_u32_e32 v163, 0, v12
	s_mov_b32 s70, s26
	v_readlane_b32 s2, v253, 23
	s_barrier
	v_readlane_b32 s27, v253, 31
	s_waitcnt vmcnt(0)
	s_branch .LBB0_370

; #define PG8_LAS __attribute__((address_space(3)))
; #define PG8_WAIT_V(n) asm volatile("s_waitcnt vmcnt(" #n ")" ::: "memory")
; #define PG8_WAIT_L(n) asm volatile("s_waitcnt lgkmcnt(" #n ")" ::: "memory")
; #define PG8_BAR __builtin_amdgcn_s_barrier()
; template <class Epi, class Sched, bool ALIGN_EPI, bool SP2>
; __device__ __forceinline__ void gemm_phase(PG8_LAS unsigned char* lds, const Gemm g, const Sched& S, const Epi& E, int wid) {
;     ...
;         const bool has_next = S.next(ui + 1, nxt);
;         const char* nA = has_next ? (const char*)g.A + (size_t)nxt.pm * tstepA : cA; const char* nB = has_next ? (const char*)g.Bt + (size_t)nxt.pn * tstepB : cB;
;         for (int t = 0; t < nt; t += 2) {
;             const bool last = (t == nt - 2);
;             const char* a1 = cA + (size_t)(t + 1) * kstep;
;             const char* a2 = last ? nA : cA + (size_t)(t + 2) * kstep; const char* b2 = last ? nB : cB + (size_t)(t + 2) * kstep;
;             const char* a3 = a2 + kstep; const char* b3 = b2 + kstep;
;             if constexpr (Epi::PRE == 1) { if (last) {
;                 const char* rsrc; const char* ssrc; E.pre(cur, rsrc, ssrc);
; #pragma unroll
;                 for (int _i = 0; _i < 2; ++_i) __builtin_amdgcn_global_load_lds((const unsigned*)(rsrc + (wid + 8 * _i) * 1024 + lane * 16), (PG8_LAS unsigned*)(lds + LDS_XOFF + (wid + 8 * _i) * 1024), 16, 0, 0);
;                 if (wid == 0) __builtin_amdgcn_global_load_lds((const unsigned*)(ssrc + lane * 16), (PG8_LAS unsigned*)(lds + LDS_XOFF + 16384), 16, 0, 0);
;             } }
;             if constexpr (SP2) {
;             PG8_LDB(B0, 0, 0); PG8_LDB(B1, 0, 1); PG8_SCHED; PG8_LDA(At, 0, 0); PG8_STAGE(PG8_SA(1, 1), a1 + hstepA, voffA);
;             PG8_WAIT_V(8); PG8_WAIT_L(0); PG8_BAR; PG8_MMA(0, 0, At, B0); PG8_MMA(0, 1, At, B1); PG8_BAR; PG8_SCHED;
;             PG8_LDA(At, 0, 1); PG8_STAGE(PG8_SB(0, 0), b2, voffB); PG8_STAGE(PG8_SB(0, 1), b2 + hstepB, voffB); PG8_STAGE(PG8_SA(0, 0), a2, voffA);
;             PG8_WAIT_V(8); PG8_WAIT_L(0); PG8_BAR; PG8_MMA(1, 0, At, B0); PG8_MMA(1, 1, At, B1); PG8_BAR; PG8_SCHED;
;     __device__ __forceinline__ void pre(const pg8::Unit& u, const char*& rsrc, const char*& ssrc) const {
;         rsrc = (const char*)(rss + (size_t)(rowbase + u.pm * 256) * 16); ssrc = (const char*)(S + (size_t)batch_of(rowbase + u.pm * 256) * NUP + u.pn * 256); }
.LBB0_372:
	s_ashr_i32 s41, s40, 31
	s_lshl_b64 s[26:27], s[40:41], 19
	v_readlane_b32 s23, v255, 2
	s_add_u32 s42, s23, s26
	v_readlane_b32 s23, v255, 3
	s_addc_u32 s43, s23, s27
	s_and_b64 s[26:27], s[36:37], exec
	s_cselect_b32 s26, s43, s39
	s_cselect_b32 s27, s42, s38
	s_ashr_i32 s23, s22, 31
	s_lshl_b64 s[44:45], s[22:23], 19
	v_readlane_b32 s23, v254, 62
	s_add_u32 s44, s23, s44
	v_readlane_b32 s23, v254, 63
	s_addc_u32 s45, s23, s45
	s_and_b64 s[74:75], s[36:37], exec
	s_cselect_b32 s41, s45, s69
	s_cselect_b32 s73, s44, s68
	s_lshl_b32 s23, s70, 8
	s_lshl_b32 s70, s2, 8
	s_ashr_i32 s71, s70, 31
	v_readlane_b32 s46, v254, 49
	v_lshl_add_u64 v[0:1], s[70:71], 2, v[152:153]
	s_add_i32 s70, s23, s46
	s_ashr_i32 s71, s70, 31
	s_lshl_b64 s[74:75], s[70:71], 6
	v_lshl_add_u64 v[2:3], v[150:151], 0, s[74:75]
	s_add_i32 s74, s70, 0xffff8000
	s_lshr_b32 s74, s74, 14
	s_ashr_i32 s71, s70, 12
	s_add_i32 s74, s74, 8
	s_cmp_lt_i32 s70, 0x8000
	s_cselect_b32 s70, s71, s74
	s_add_u32 s38, s38, 0x40080
	v_readlane_b32 s46, v252, 20
	s_addc_u32 s39, s39, 0
	v_readlane_b32 s47, v252, 21
	v_mad_i64_i32 v[84:85], s[70:71], s70, v240, v[0:1]
	s_add_u32 s74, s68, 0x100
	v_lshl_add_u64 v[80:81], v[2:3], 0, s[18:19]
	v_lshl_add_u64 v[82:83], v[2:3], 0, s[46:47]
	s_addc_u32 s75, s69, 0
	s_mov_b32 s76, -2
	s_and_b64 vcc, exec, s[34:35]
	s_cbranch_vccnz .Lhb_up
	s_barrier
.Lhb_up:
	s_cmp_eq_u32 s76, 12
	s_cselect_b64 s[68:69], -1, 0
	s_add_u32 s70, s38, 0xfffc0080
	s_addc_u32 s71, s39, -1
	s_and_b64 s[68:69], s[68:69], exec
	s_cselect_b32 s71, s26, s71
	s_cselect_b32 s70, s27, s70
	s_cselect_b32 s69, s41, s75
	s_cselect_b32 s68, s73, s74
	s_add_i32 s77, 0, 0x11000
	v_add_u32_e32 v94, s77, v161
	s_add_i32 s89, 0, 0x15400
	ds_read_b128 v[86:89], v94
	ds_read_b128 v[90:93], v94 offset:64
	ds_read_b128 v[164:167], v94 offset:2176
	ds_read_b128 v[168:171], v94 offset:2240
	v_add_u32_e32 v94, s89, v161
	ds_read_b128 v[172:175], v94
	ds_read_b128 v[176:179], v94 offset:64
	ds_read_b128 v[180:183], v94 offset:2176
	ds_read_b128 v[184:187], v94 offset:2240
	v_lshl_add_u64 v[94:95], s[38:39], 0, v[154:155]
	s_add_i32 m0, s0, 0xcc00
	ds_read_b128 v[188:191], v163
	ds_read_b128 v[208:211], v163 offset:64
	ds_read_b128 v[212:215], v163 offset:2176
	ds_read_b128 v[216:219], v163 offset:2240
	ds_read_b128 v[220:223], v163 offset:4352
	ds_read_b128 v[224:227], v163 offset:4416
	ds_read_b128 v[228:231], v163 offset:6528
	ds_read_b128 v[242:245], v163 offset:6592
	global_load_lds_dwordx4 v[94:95], off
	v_lshl_add_u64 v[94:95], s[38:39], 0, v[156:157]
	s_add_i32 m0, s0, 0xee00
	s_nop 0
	global_load_lds_dwordx4 v[94:95], off
	s_waitcnt vmcnt(8)
	s_waitcnt lgkmcnt(0)
	s_barrier
	s_setprio 1
	s_waitcnt lgkmcnt(0)
	v_mfma_f32_16x16x32_bf16 v[140:143], v[86:89], v[188:191], 0
	v_mfma_f32_16x16x32_bf16 v[136:139], v[164:167], v[188:191], 0
	v_mfma_f32_16x16x32_bf16 v[124:127], v[86:89], v[212:215], 0
	v_mfma_f32_16x16x32_bf16 v[120:123], v[164:167], v[212:215], 0
	v_mfma_f32_16x16x32_bf16 v[108:111], v[86:89], v[220:223], 0
	v_mfma_f32_16x16x32_bf16 v[104:107], v[164:167], v[220:223], 0
	v_mfma_f32_16x16x32_bf16 v[76:79], v[86:89], v[228:231], 0
	v_mfma_f32_16x16x32_bf16 v[72:75], v[164:167], v[228:231], 0
	v_mfma_f32_16x16x32_bf16 v[140:143], v[90:93], v[208:211], v[140:143]
	v_mfma_f32_16x16x32_bf16 v[136:139], v[168:171], v[208:211], v[136:139]
	v_mfma_f32_16x16x32_bf16 v[124:127], v[90:93], v[216:219], v[124:127]
	v_mfma_f32_16x16x32_bf16 v[120:123], v[168:171], v[216:219], v[120:123]
	v_mfma_f32_16x16x32_bf16 v[108:111], v[90:93], v[224:227], v[108:111]
	v_mfma_f32_16x16x32_bf16 v[104:107], v[168:171], v[224:227], v[104:107]
	v_mfma_f32_16x16x32_bf16 v[76:79], v[90:93], v[242:245], v[76:79]
	v_mfma_f32_16x16x32_bf16 v[72:75], v[168:171], v[242:245], v[72:75]
	s_setprio 0
	s_setprio 1
	v_mfma_f32_16x16x32_bf16 v[132:135], v[172:175], v[188:191], 0
	v_mfma_f32_16x16x32_bf16 v[128:131], v[180:183], v[188:191], 0
	v_mfma_f32_16x16x32_bf16 v[116:119], v[172:175], v[212:215], 0
	v_mfma_f32_16x16x32_bf16 v[112:115], v[180:183], v[212:215], 0
	v_mfma_f32_16x16x32_bf16 v[100:103], v[172:175], v[220:223], 0
	v_mfma_f32_16x16x32_bf16 v[94:97], v[180:183], v[220:223], 0
	v_mfma_f32_16x16x32_bf16 v[68:71], v[172:175], v[228:231], 0
	v_mfma_f32_16x16x32_bf16 v[64:67], v[180:183], v[228:231], 0
	v_mfma_f32_16x16x32_bf16 v[132:135], v[176:179], v[208:211], v[132:135]
	v_mfma_f32_16x16x32_bf16 v[128:131], v[184:187], v[208:211], v[128:131]
	v_mfma_f32_16x16x32_bf16 v[116:119], v[176:179], v[216:219], v[116:119]
	v_mfma_f32_16x16x32_bf16 v[112:115], v[184:187], v[216:219], v[112:115]
	v_mfma_f32_16x16x32_bf16 v[100:103], v[176:179], v[224:227], v[100:103]
	v_mfma_f32_16x16x32_bf16 v[94:97], v[184:187], v[224:227], v[94:97]
	v_mfma_f32_16x16x32_bf16 v[68:71], v[176:179], v[242:245], v[68:71]
	v_mfma_f32_16x16x32_bf16 v[64:67], v[184:187], v[242:245], v[64:67]
	s_setprio 0
	s_barrier
	s_add_i32 s77, s77, s33
	v_lshl_add_u64 v[158:159], s[68:69], 0, v[192:193]
	s_mov_b32 m0, s77
	ds_read_b128 v[188:191], v163 offset:17408
	ds_read_b128 v[208:211], v163 offset:17472
	ds_read_b128 v[212:215], v163 offset:19584
	ds_read_b128 v[216:219], v163 offset:19648
	ds_read_b128 v[220:223], v163 offset:21760
	ds_read_b128 v[224:227], v163 offset:21824
	ds_read_b128 v[228:231], v163 offset:23936
	ds_read_b128 v[242:245], v163 offset:24000
	global_load_lds_dwordx4 v[158:159], off
	s_add_i32 m0, s77, 0x2200
	s_add_u32 s78, s68, 0x40000
	v_lshl_add_u64 v[198:199], s[68:69], 0, v[144:145]
	s_addc_u32 s79, s69, 0
	s_add_i32 s77, s89, s33
	global_load_lds_dwordx4 v[198:199], off
	v_lshl_add_u64 v[98:99], s[78:79], 0, v[192:193]
	s_mov_b32 m0, s77
	v_lshl_add_u64 v[200:201], s[70:71], 0, v[148:149]
	global_load_lds_dwordx4 v[98:99], off
	v_lshl_add_u64 v[98:99], s[78:79], 0, v[144:145]
	s_add_i32 m0, s77, 0x2200
	v_lshl_add_u64 v[232:233], s[70:71], 0, v[146:147]
	global_load_lds_dwordx4 v[98:99], off
	s_mov_b32 m0, s0
	s_nop 0
	global_load_lds_dwordx4 v[200:201], off
	s_mov_b32 m0, s5
	s_nop 0
	global_load_lds_dwordx4 v[232:233], off
	s_waitcnt vmcnt(8)
	s_waitcnt lgkmcnt(0)
	s_barrier
; #define PG8_STAGE(bufoff, gbase, voff) do { _Pragma("unroll") for (int _i = 0; _i < 2; ++_i) \
;         __builtin_amdgcn_global_load_lds((const unsigned*)((const char*)(gbase) + (voff)[_i]), (PG8_LAS unsigned*)(lds + (bufoff) + ldsw + _i * (8 * USTR)), 16, 0, 0); } while (0)
; #define PG8_LDA(dst, b, h) do { _Pragma("unroll") for (int m = 0; m < 4; ++m) _Pragma("unroll") for (int k = 0; k < 2; ++k) dst[m][k] = *(const PG8_LAS bf16x8*)(lds + PG8_SA(b, h) + aoff + m * (2 * USTR) + k * 64); } while (0)
; #define PG8_LDB(dst, b, h) do { _Pragma("unroll") for (int n = 0; n < 2; ++n) _Pragma("unroll") for (int k = 0; k < 2; ++k) dst[n][k] = *(const PG8_LAS bf16x8*)(lds + PG8_SB(b, h) + boff + n * (2 * USTR) + k * 64); } while (0)
; #define PG8_MMA(ai, bj, At, Bt) do { __builtin_amdgcn_s_setprio(1); _Pragma("unroll") for (int m = 0; m < 4; ++m) _Pragma("unroll") for (int n = 0; n < 2; ++n) _Pragma("unroll") for (int k = 0; k < 2; ++k) \
;         acc[ai][bj][m][n] = __builtin_amdgcn_mfma_f32_16x16x32_bf16(Bt[n][k], At[m][k], acc[ai][bj][m][n], 0, 0, 0); __builtin_amdgcn_s_setprio(0); } while (0)
; #define PG8_WAIT_V(n) asm volatile("s_waitcnt vmcnt(" #n ")" ::: "memory")
; #define PG8_WAIT_L(n) asm volatile("s_waitcnt lgkmcnt(" #n ")" ::: "memory")
; #define PG8_BAR __builtin_amdgcn_s_barrier()
; #define PG8_SCHED __builtin_amdgcn_sched_barrier(0)
; template <class Epi, class Sched, bool ALIGN_EPI, bool SP2>
; __device__ __forceinline__ void gemm_phase(PG8_LAS unsigned char* lds, const Gemm g, const Sched& S, const Epi& E, int wid) {
;     ...
;             PG8_WAIT_V(8); PG8_WAIT_L(0); PG8_BAR; PG8_MMA(1, 0, At, B0); PG8_MMA(1, 1, At, B1); PG8_BAR; PG8_SCHED;
;             PG8_LDB(B0, 1, 0); PG8_LDB(B1, 1, 1); PG8_SCHED; PG8_LDA(At, 1, 0); PG8_STAGE(PG8_SA(0, 1), a2 + hstepA, voffA);
;             PG8_WAIT_V(8); PG8_WAIT_L(0); PG8_BAR; PG8_MMA(0, 0, At, B0); PG8_MMA(0, 1, At, B1); PG8_BAR; PG8_SCHED;
	s_setprio 1
	s_waitcnt lgkmcnt(0)
	v_mfma_f32_16x16x32_bf16 v[60:63], v[86:89], v[188:191], 0
	v_mfma_f32_16x16x32_bf16 v[56:59], v[164:167], v[188:191], 0
	v_mfma_f32_16x16x32_bf16 v[44:47], v[86:89], v[212:215], 0
	v_mfma_f32_16x16x32_bf16 v[40:43], v[164:167], v[212:215], 0
	v_mfma_f32_16x16x32_bf16 v[28:31], v[86:89], v[220:223], 0
	v_mfma_f32_16x16x32_bf16 v[24:27], v[164:167], v[220:223], 0
	v_mfma_f32_16x16x32_bf16 v[12:15], v[86:89], v[228:231], 0
	v_mfma_f32_16x16x32_bf16 v[8:11], v[164:167], v[228:231], 0
	v_mfma_f32_16x16x32_bf16 v[60:63], v[90:93], v[208:211], v[60:63]
	v_mfma_f32_16x16x32_bf16 v[56:59], v[168:171], v[208:211], v[56:59]
	v_mfma_f32_16x16x32_bf16 v[44:47], v[90:93], v[216:219], v[44:47]
	v_mfma_f32_16x16x32_bf16 v[40:43], v[168:171], v[216:219], v[40:43]
	v_mfma_f32_16x16x32_bf16 v[28:31], v[90:93], v[224:227], v[28:31]
	v_mfma_f32_16x16x32_bf16 v[24:27], v[168:171], v[224:227], v[24:27]
	v_mfma_f32_16x16x32_bf16 v[12:15], v[90:93], v[242:245], v[12:15]
	v_mfma_f32_16x16x32_bf16 v[8:11], v[168:171], v[242:245], v[8:11]
	s_setprio 0
	s_setprio 1
	v_mfma_f32_16x16x32_bf16 v[52:55], v[172:175], v[188:191], 0
	v_mfma_f32_16x16x32_bf16 v[48:51], v[180:183], v[188:191], 0
	v_mfma_f32_16x16x32_bf16 v[36:39], v[172:175], v[212:215], 0
	v_mfma_f32_16x16x32_bf16 v[32:35], v[180:183], v[212:215], 0
	v_mfma_f32_16x16x32_bf16 v[20:23], v[172:175], v[220:223], 0
	v_mfma_f32_16x16x32_bf16 v[16:19], v[180:183], v[220:223], 0
	v_mfma_f32_16x16x32_bf16 v[4:7], v[172:175], v[228:231], 0
	v_mfma_f32_16x16x32_bf16 v[0:3], v[180:183], v[228:231], 0
	v_mfma_f32_16x16x32_bf16 v[52:55], v[176:179], v[208:211], v[52:55]
	v_mfma_f32_16x16x32_bf16 v[48:51], v[184:187], v[208:211], v[48:51]
	v_mfma_f32_16x16x32_bf16 v[36:39], v[176:179], v[216:219], v[36:39]
	v_mfma_f32_16x16x32_bf16 v[32:35], v[184:187], v[216:219], v[32:35]
	v_mfma_f32_16x16x32_bf16 v[20:23], v[176:179], v[224:227], v[20:23]
	v_mfma_f32_16x16x32_bf16 v[16:19], v[184:187], v[224:227], v[16:19]
	v_mfma_f32_16x16x32_bf16 v[4:7], v[176:179], v[242:245], v[4:7]
	v_mfma_f32_16x16x32_bf16 v[0:3], v[184:187], v[242:245], v[0:3]
	s_setprio 0
	s_barrier
	s_add_i32 s77, 0, 0x19800
	v_add_u32_e32 v98, s77, v161
	s_add_i32 s78, 0, 0x1dc00
	ds_read_b128 v[86:89], v98
	ds_read_b128 v[90:93], v98 offset:64
	ds_read_b128 v[164:167], v98 offset:2176
	ds_read_b128 v[168:171], v98 offset:2240
	v_add_u32_e32 v98, s78, v161
	ds_read_b128 v[172:175], v98
	ds_read_b128 v[176:179], v98 offset:64
	ds_read_b128 v[180:183], v98 offset:2176
	ds_read_b128 v[184:187], v98 offset:2240
	s_add_u32 s70, s70, 0x40000
	s_addc_u32 s71, s71, 0
	s_mov_b32 m0, s10
	v_lshl_add_u64 v[98:99], s[70:71], 0, v[148:149]
	ds_read_b128 v[188:191], v163 offset:34816
	ds_read_b128 v[208:211], v163 offset:34880
	ds_read_b128 v[212:215], v163 offset:36992
	ds_read_b128 v[216:219], v163 offset:37056
	ds_read_b128 v[220:223], v163 offset:39168
	ds_read_b128 v[224:227], v163 offset:39232
	ds_read_b128 v[228:231], v163 offset:41344
	ds_read_b128 v[242:245], v163 offset:41408
	global_load_lds_dwordx4 v[98:99], off
	v_lshl_add_u64 v[98:99], s[70:71], 0, v[146:147]
	s_mov_b32 m0, s29
	s_nop 0
	global_load_lds_dwordx4 v[98:99], off
	s_waitcnt vmcnt(8)
	s_waitcnt lgkmcnt(0)
	s_barrier
	s_setprio 1
	s_waitcnt lgkmcnt(0)
	v_mfma_f32_16x16x32_bf16 v[140:143], v[86:89], v[188:191], v[140:143]
	v_mfma_f32_16x16x32_bf16 v[136:139], v[164:167], v[188:191], v[136:139]
	v_mfma_f32_16x16x32_bf16 v[124:127], v[86:89], v[212:215], v[124:127]
	v_mfma_f32_16x16x32_bf16 v[120:123], v[164:167], v[212:215], v[120:123]
	v_mfma_f32_16x16x32_bf16 v[108:111], v[86:89], v[220:223], v[108:111]
	v_mfma_f32_16x16x32_bf16 v[104:107], v[164:167], v[220:223], v[104:107]
	v_mfma_f32_16x16x32_bf16 v[76:79], v[86:89], v[228:231], v[76:79]
	v_mfma_f32_16x16x32_bf16 v[72:75], v[164:167], v[228:231], v[72:75]
	v_mfma_f32_16x16x32_bf16 v[140:143], v[90:93], v[208:211], v[140:143]
	v_mfma_f32_16x16x32_bf16 v[136:139], v[168:171], v[208:211], v[136:139]
	v_mfma_f32_16x16x32_bf16 v[124:127], v[90:93], v[216:219], v[124:127]
	v_mfma_f32_16x16x32_bf16 v[120:123], v[168:171], v[216:219], v[120:123]
	v_mfma_f32_16x16x32_bf16 v[108:111], v[90:93], v[224:227], v[108:111]
	v_mfma_f32_16x16x32_bf16 v[104:107], v[168:171], v[224:227], v[104:107]
	v_mfma_f32_16x16x32_bf16 v[76:79], v[90:93], v[242:245], v[76:79]
	v_mfma_f32_16x16x32_bf16 v[72:75], v[168:171], v[242:245], v[72:75]
	s_setprio 0
	s_setprio 1
	v_mfma_f32_16x16x32_bf16 v[132:135], v[172:175], v[188:191], v[132:135]
	v_mfma_f32_16x16x32_bf16 v[128:131], v[180:183], v[188:191], v[128:131]
	v_mfma_f32_16x16x32_bf16 v[116:119], v[172:175], v[212:215], v[116:119]
	v_mfma_f32_16x16x32_bf16 v[112:115], v[180:183], v[212:215], v[112:115]
	v_mfma_f32_16x16x32_bf16 v[98:101], v[172:175], v[220:223], v[100:103]
	v_mfma_f32_16x16x32_bf16 v[94:97], v[180:183], v[220:223], v[94:97]
	v_mfma_f32_16x16x32_bf16 v[68:71], v[172:175], v[228:231], v[68:71]
	v_mfma_f32_16x16x32_bf16 v[64:67], v[180:183], v[228:231], v[64:67]
	v_mfma_f32_16x16x32_bf16 v[132:135], v[176:179], v[208:211], v[132:135]
	v_mfma_f32_16x16x32_bf16 v[128:131], v[184:187], v[208:211], v[128:131]
	v_mfma_f32_16x16x32_bf16 v[116:119], v[176:179], v[216:219], v[116:119]
	v_mfma_f32_16x16x32_bf16 v[112:115], v[184:187], v[216:219], v[112:115]
	v_mfma_f32_16x16x32_bf16 v[100:103], v[176:179], v[224:227], v[98:101]
	v_mfma_f32_16x16x32_bf16 v[96:99], v[184:187], v[224:227], v[94:97]
	v_mfma_f32_16x16x32_bf16 v[68:71], v[176:179], v[242:245], v[68:71]
	v_mfma_f32_16x16x32_bf16 v[64:67], v[184:187], v[242:245], v[64:67]
	s_setprio 0
	s_barrier
; #define PG8_STAGE(bufoff, gbase, voff) do { _Pragma("unroll") for (int _i = 0; _i < 2; ++_i) \
;         __builtin_amdgcn_global_load_lds((const unsigned*)((const char*)(gbase) + (voff)[_i]), (PG8_LAS unsigned*)(lds + (bufoff) + ldsw + _i * (8 * USTR)), 16, 0, 0); } while (0)
; #define PG8_LDA(dst, b, h) do { _Pragma("unroll") for (int m = 0; m < 4; ++m) _Pragma("unroll") for (int k = 0; k < 2; ++k) dst[m][k] = *(const PG8_LAS bf16x8*)(lds + PG8_SA(b, h) + aoff + m * (2 * USTR) + k * 64); } while (0)
; #define PG8_MMA(ai, bj, At, Bt) do { __builtin_amdgcn_s_setprio(1); _Pragma("unroll") for (int m = 0; m < 4; ++m) _Pragma("unroll") for (int n = 0; n < 2; ++n) _Pragma("unroll") for (int k = 0; k < 2; ++k) \
;         acc[ai][bj][m][n] = __builtin_amdgcn_mfma_f32_16x16x32_bf16(Bt[n][k], At[m][k], acc[ai][bj][m][n], 0, 0, 0); __builtin_amdgcn_s_setprio(0); } while (0)
; #define PG8_WAIT_V(n) asm volatile("s_waitcnt vmcnt(" #n ")" ::: "memory")
; #define PG8_WAIT_L(n) asm volatile("s_waitcnt lgkmcnt(" #n ")" ::: "memory")
; #define PG8_BAR __builtin_amdgcn_s_barrier()
; #define PG8_SCHED __builtin_amdgcn_sched_barrier(0)
; template <class Epi, class Sched, bool ALIGN_EPI, bool SP2>
; __device__ __forceinline__ void gemm_phase(PG8_LAS unsigned char* lds, const Gemm g, const Sched& S, const Epi& E, int wid) {
;     ...
;             PG8_LDA(At, 1, 1); PG8_STAGE(PG8_SB(1, 0), b3, voffB); PG8_STAGE(PG8_SB(1, 1), b3 + hstepB, voffB); PG8_STAGE(PG8_SA(1, 0), a3, voffA);
;             PG8_WAIT_V(8); PG8_WAIT_L(0); PG8_BAR; PG8_MMA(1, 0, At, B0); PG8_MMA(1, 1, At, B1); PG8_BAR; PG8_SCHED;
	s_add_i32 s70, s77, s33
	v_lshl_add_u64 v[94:95], v[158:159], 0, s[6:7]
	s_mov_b32 m0, s70
	ds_read_b128 v[188:191], v163 offset:52224
	ds_read_b128 v[208:211], v163 offset:52288
	ds_read_b128 v[212:215], v163 offset:54400
	ds_read_b128 v[216:219], v163 offset:54464
	ds_read_b128 v[220:223], v163 offset:56576
	ds_read_b128 v[224:227], v163 offset:56640
	ds_read_b128 v[228:231], v163 offset:58752
	ds_read_b128 v[242:245], v163 offset:58816
	global_load_lds_dwordx4 v[94:95], off
	s_add_i32 m0, s70, 0x2200
	s_add_u32 s68, s68, 0x40080
	v_lshl_add_u64 v[94:95], v[198:199], 0, s[6:7]
	s_addc_u32 s69, s69, 0
	s_add_i32 s70, s78, s33
	global_load_lds_dwordx4 v[94:95], off
	v_lshl_add_u64 v[94:95], s[68:69], 0, v[192:193]
	s_mov_b32 m0, s70
	s_nop 0
	global_load_lds_dwordx4 v[94:95], off
	v_lshl_add_u64 v[94:95], s[68:69], 0, v[144:145]
	s_add_i32 m0, s70, 0x2200
	s_nop 0
	global_load_lds_dwordx4 v[94:95], off
	v_lshl_add_u64 v[94:95], v[200:201], 0, s[6:7]
	s_mov_b32 m0, s56
	s_nop 0
	global_load_lds_dwordx4 v[94:95], off
	v_lshl_add_u64 v[94:95], v[232:233], 0, s[6:7]
	s_mov_b32 m0, s57
	s_nop 0
	global_load_lds_dwordx4 v[94:95], off
	s_waitcnt vmcnt(8)
	s_waitcnt lgkmcnt(0)
	s_barrier
	s_setprio 1
	s_waitcnt lgkmcnt(0)
	v_mfma_f32_16x16x32_bf16 v[60:63], v[86:89], v[188:191], v[60:63]
	v_mfma_f32_16x16x32_bf16 v[56:59], v[164:167], v[188:191], v[56:59]
	v_mfma_f32_16x16x32_bf16 v[44:47], v[86:89], v[212:215], v[44:47]
	v_mfma_f32_16x16x32_bf16 v[40:43], v[164:167], v[212:215], v[40:43]
	v_mfma_f32_16x16x32_bf16 v[28:31], v[86:89], v[220:223], v[28:31]
	v_mfma_f32_16x16x32_bf16 v[24:27], v[164:167], v[220:223], v[24:27]
	v_mfma_f32_16x16x32_bf16 v[12:15], v[86:89], v[228:231], v[12:15]
	v_mfma_f32_16x16x32_bf16 v[8:11], v[164:167], v[228:231], v[8:11]
	v_mfma_f32_16x16x32_bf16 v[60:63], v[90:93], v[208:211], v[60:63]
	v_mfma_f32_16x16x32_bf16 v[56:59], v[168:171], v[208:211], v[56:59]
	v_mfma_f32_16x16x32_bf16 v[44:47], v[90:93], v[216:219], v[44:47]
	v_mfma_f32_16x16x32_bf16 v[40:43], v[168:171], v[216:219], v[40:43]
	v_mfma_f32_16x16x32_bf16 v[28:31], v[90:93], v[224:227], v[28:31]
	v_mfma_f32_16x16x32_bf16 v[24:27], v[168:171], v[224:227], v[24:27]
	v_mfma_f32_16x16x32_bf16 v[12:15], v[90:93], v[242:245], v[12:15]
	v_mfma_f32_16x16x32_bf16 v[8:11], v[168:171], v[242:245], v[8:11]
	s_setprio 0
	s_setprio 1
	v_mfma_f32_16x16x32_bf16 v[52:55], v[172:175], v[188:191], v[52:55]
	v_mfma_f32_16x16x32_bf16 v[48:51], v[180:183], v[188:191], v[48:51]
	v_mfma_f32_16x16x32_bf16 v[36:39], v[172:175], v[212:215], v[36:39]
	v_mfma_f32_16x16x32_bf16 v[32:35], v[180:183], v[212:215], v[32:35]
	v_mfma_f32_16x16x32_bf16 v[20:23], v[172:175], v[220:223], v[20:23]
	v_mfma_f32_16x16x32_bf16 v[16:19], v[180:183], v[220:223], v[16:19]
	v_mfma_f32_16x16x32_bf16 v[4:7], v[172:175], v[228:231], v[4:7]
	v_mfma_f32_16x16x32_bf16 v[0:3], v[180:183], v[228:231], v[0:3]
	v_mfma_f32_16x16x32_bf16 v[52:55], v[176:179], v[208:211], v[52:55]
	v_mfma_f32_16x16x32_bf16 v[48:51], v[184:187], v[208:211], v[48:51]
	v_mfma_f32_16x16x32_bf16 v[36:39], v[176:179], v[216:219], v[36:39]
	v_mfma_f32_16x16x32_bf16 v[32:35], v[184:187], v[216:219], v[32:35]
	v_mfma_f32_16x16x32_bf16 v[20:23], v[176:179], v[224:227], v[20:23]
	v_mfma_f32_16x16x32_bf16 v[16:19], v[184:187], v[224:227], v[16:19]
	v_mfma_f32_16x16x32_bf16 v[4:7], v[176:179], v[242:245], v[4:7]
	v_mfma_f32_16x16x32_bf16 v[0:3], v[184:187], v[242:245], v[0:3]
	s_setprio 0
	s_barrier
	s_add_i32 s76, s76, 2
	s_add_u32 s38, s38, 0x100
	s_addc_u32 s39, s39, 0
	s_add_u32 s74, s74, 0x100
	s_addc_u32 s75, s75, 0
	s_cmp_gt_u32 s76, 13
	s_branch .LBB0_374

; __device__ __forceinline__ unsigned cvt_pk_bf16(float lo, float hi) { unsigned r; asm volatile("v_cvt_pk_bf16_f32 %0, %1, %2" : "=v"(r) : "v"(lo), "v"(hi)); return r; }
; __device__ __forceinline__ int lane_id_v() { int l; asm volatile("v_mbcnt_lo_u32_b32 %0, -1, 0\n\tv_mbcnt_hi_u32_b32 %0, -1, %0" : "=v"(l)); return l; }
; __device__ __forceinline__ f32x2 silu_mul_pk(f32x2 g, f32x2 u) {
;     const f32x2 t = g * (-1.4426950409f);
;     f32x2 e; e.x = __builtin_amdgcn_exp2f(t.x); e.y = __builtin_amdgcn_exp2f(t.y);
;     const f32x2 d = e + 1.0f;
;     f32x2 r; r.x = __builtin_amdgcn_rcpf(d.x); r.y = __builtin_amdgcn_rcpf(d.y);
;     return (g * u) * r;
; }
;     __device__ __forceinline__ void operator()(const f32x4 (&acc)[2][2][4][2], const pg8::Unit& u, int wr, int wc, int fr_, int fq_) const {
;         const int lane_ = pg8::lane_id_v(); const int fr = lane_ & 15, fq = lane_ >> 4;
;         const int lrow0 = u.pm * 256 + wr * 64 + fr;
;         const int b = batch_of(rowbase + u.pm * 256);
;         f32x4 sv[2][2];
; #pragma unroll
;         for (int bj = 0; bj < 2; ++bj)
; #pragma unroll
;             for (int n = 0; n < 2; ++n) sv[bj][n] = *(const LAS f32x4*)(xl + 16384 + (bj * 128 + wc * 32 + 8 * fq + 4 * n) * 4);
;         float rs8[8]; rows_rstd8_lds(xl, wr * 64 + fr, fq, rs8);
;         const int hcol = u.pn * 128 + wc * 32 + 8 * fq;
; #pragma unroll
;         for (int ai = 0; ai < 2; ++ai)
; #pragma unroll
;             for (int m = 0; m < 4; ++m) {
;                 const int lr = lrow0 + ai * 128 + m * 16;
;                 const float rs = rs8[ai * 4 + m];
;                 const f32x4 g0 = acc[ai][0][m][0] * rs + sv[0][0], g1 = acc[ai][0][m][1] * rs + sv[0][1];
;                 const f32x4 u0 = acc[ai][1][m][0] * rs + sv[1][0], u1 = acc[ai][1][m][1] * rs + sv[1][1];
;                 const f32x2 ha = pg8::silu_mul_pk((f32x2){g0[0], g0[1]}, (f32x2){u0[0], u0[1]}), hb = pg8::silu_mul_pk((f32x2){g0[2], g0[3]}, (f32x2){u0[2], u0[3]});
;                 const f32x2 hc = pg8::silu_mul_pk((f32x2){g1[0], g1[1]}, (f32x2){u1[0], u1[1]}), hd = pg8::silu_mul_pk((f32x2){g1[2], g1[3]}, (f32x2){u1[2], u1[3]});
;                 u32x4 w; w.x = cvt_pk_bf16(ha.x, ha.y); w.y = cvt_pk_bf16(hb.x, hb.y); w.z = cvt_pk_bf16(hc.x, hc.y); w.w = cvt_pk_bf16(hd.x, hd.y);
;                 *(u32x4*)(H + (size_t)lr * FF + hcol) = w;
.LBB0_379:
	v_mbcnt_lo_u32_b32 v228, -1, 0
	v_mbcnt_hi_u32_b32 v228, -1, v228
	v_and_b32_e32 v224, 15, v228
	v_add_u32_e32 v224, s91, v224
	v_lshlrev_b32_e32 v224, 2, v224
	v_add_u32_e32 v224, 0x26800, v224
	ds_read_b32 v208, v224
	ds_read_b32 v209, v224 offset:64
	ds_read_b32 v210, v224 offset:128
	ds_read_b32 v211, v224 offset:192
	ds_read_b32 v212, v224 offset:512
	ds_read_b32 v213, v224 offset:576
	ds_read_b32 v214, v224 offset:640
	ds_read_b32 v215, v224 offset:704
	s_waitcnt lgkmcnt(0)
	v_mbcnt_lo_u32_b32 v158, -1, 0
	v_mbcnt_hi_u32_b32 v158, -1, v158
	s_add_i32 s23, s23, s91
	v_and_b32_e32 v159, 15, v158
	v_or_b32_e32 v165, s23, v159
	v_ashrrev_i32_e32 v167, 4, v158
	v_readlane_b32 s26, v252, 22
	s_add_i32 s23, 0, 0x22400
	v_lshl_add_u32 v80, v167, 5, s26
	ds_read_b128 v[92:95], v80
	ds_read_b128 v[88:91], v80 offset:16
	ds_read_b128 v[84:87], v80 offset:512
	ds_read_b128 v[80:83], v80 offset:528
	s_mov_b32 s26, 0x358637bd
	s_lshl_b32 s2, s2, 7
	s_waitcnt lgkmcnt(0)
	s_waitcnt lgkmcnt(0)
	s_or_b32 s2, s2, s15
	s_mov_b64 s[76:77], s[62:63]
	s_waitcnt lgkmcnt(0)
	s_waitcnt lgkmcnt(0)
	s_nop 0
	s_nop 0
	s_nop 0
	v_mov_b32_e32 v172, v208
	s_waitcnt lgkmcnt(0)
	v_mov_b32_e32 v170, v209
	v_pk_fma_f32 v[126:127], v[126:127], v[170:171], v[94:95] op_sel_hi:[1,0,1]
	v_pk_fma_f32 v[124:125], v[124:125], v[170:171], v[92:93] op_sel_hi:[1,0,1]
	s_waitcnt lgkmcnt(0)
	v_pk_fma_f32 v[116:117], v[116:117], v[170:171], v[84:85] op_sel_hi:[1,0,1]
	v_pk_fma_f32 v[118:119], v[118:119], v[170:171], v[86:87] op_sel_hi:[1,0,1]
	v_pk_mul_f32 v[116:117], v[124:125], v[116:117]
	v_pk_fma_f32 v[120:121], v[120:121], v[170:171], v[88:89] op_sel_hi:[1,0,1]
	s_waitcnt lgkmcnt(0)
	v_pk_mul_f32 v[118:119], v[126:127], v[118:119]
	v_pk_fma_f32 v[112:113], v[112:113], v[170:171], v[80:81] op_sel_hi:[1,0,1]
	v_pk_fma_f32 v[122:123], v[122:123], v[170:171], v[90:91] op_sel_hi:[1,0,1]
	v_pk_mul_f32 v[112:113], v[120:121], v[112:113]
	s_waitcnt lgkmcnt(0)
	v_pk_fma_f32 v[114:115], v[114:115], v[170:171], v[82:83] op_sel_hi:[1,0,1]
	v_pk_mul_f32 v[114:115], v[122:123], v[114:115]
	s_nop 0
	s_nop 0
	v_mov_b32_e32 v168, v210
	v_pk_fma_f32 v[110:111], v[110:111], v[168:169], v[94:95] op_sel_hi:[1,0,1]
	v_pk_fma_f32 v[108:109], v[108:109], v[168:169], v[92:93] op_sel_hi:[1,0,1]
	v_pk_fma_f32 v[100:101], v[100:101], v[168:169], v[84:85] op_sel_hi:[1,0,1]
	s_waitcnt lgkmcnt(0)
	v_mov_b32_e32 v166, v211
	v_pk_mul_f32 v[100:101], v[108:109], v[100:101]
	v_pk_fma_f32 v[102:103], v[102:103], v[168:169], v[86:87] op_sel_hi:[1,0,1]
	s_waitcnt lgkmcnt(0)
	v_pk_fma_f32 v[104:105], v[104:105], v[168:169], v[88:89] op_sel_hi:[1,0,1]
	v_pk_mul_f32 v[102:103], v[110:111], v[102:103]
	v_pk_fma_f32 v[96:97], v[96:97], v[168:169], v[80:81] op_sel_hi:[1,0,1]
	v_pk_fma_f32 v[106:107], v[106:107], v[168:169], v[90:91] op_sel_hi:[1,0,1]
	s_waitcnt lgkmcnt(0)
	v_pk_mul_f32 v[96:97], v[104:105], v[96:97]
	v_pk_fma_f32 v[98:99], v[98:99], v[168:169], v[82:83] op_sel_hi:[1,0,1]
	v_pk_fma_f32 v[78:79], v[78:79], v[166:167], v[94:95] op_sel_hi:[1,0,1]
	v_pk_mul_f32 v[98:99], v[106:107], v[98:99]
	s_waitcnt lgkmcnt(0)
	v_pk_fma_f32 v[76:77], v[76:77], v[166:167], v[92:93] op_sel_hi:[1,0,1]
	v_pk_fma_f32 v[68:69], v[68:69], v[166:167], v[84:85] op_sel_hi:[1,0,1]
	v_pk_mul_f32 v[68:69], v[76:77], v[68:69]
	v_pk_fma_f32 v[70:71], v[70:71], v[166:167], v[86:87] op_sel_hi:[1,0,1]
	v_pk_fma_f32 v[72:73], v[72:73], v[166:167], v[88:89] op_sel_hi:[1,0,1]
	v_pk_mul_f32 v[70:71], v[78:79], v[70:71]
	v_mov_b32_e32 v164, v212
	v_pk_fma_f32 v[64:65], v[64:65], v[166:167], v[80:81] op_sel_hi:[1,0,1]
	v_pk_fma_f32 v[74:75], v[74:75], v[166:167], v[90:91] op_sel_hi:[1,0,1]
	v_pk_mul_f32 v[64:65], v[72:73], v[64:65]
	s_waitcnt lgkmcnt(0)
	v_pk_fma_f32 v[142:143], v[142:143], v[172:173], v[94:95] op_sel_hi:[1,0,1]
	v_pk_fma_f32 v[140:141], v[140:141], v[172:173], v[92:93] op_sel_hi:[1,0,1]
	v_pk_fma_f32 v[132:133], v[132:133], v[172:173], v[84:85] op_sel_hi:[1,0,1]
	v_mov_b32_e32 v162, v213
	v_pk_fma_f32 v[138:139], v[138:139], v[172:173], v[90:91] op_sel_hi:[1,0,1]
	v_pk_fma_f32 v[136:137], v[136:137], v[172:173], v[88:89] op_sel_hi:[1,0,1]
	v_pk_fma_f32 v[134:135], v[134:135], v[172:173], v[86:87] op_sel_hi:[1,0,1]
	v_pk_fma_f32 v[128:129], v[128:129], v[172:173], v[80:81] op_sel_hi:[1,0,1]
	v_pk_fma_f32 v[130:131], v[130:131], v[172:173], v[82:83] op_sel_hi:[1,0,1]
	v_pk_mul_f32 v[172:173], v[140:141], s[88:89] op_sel_hi:[1,0]
	v_pk_mul_f32 v[132:133], v[140:141], v[132:133]
	v_pk_mul_f32 v[140:141], v[142:143], s[88:89] op_sel_hi:[1,0]
	s_waitcnt lgkmcnt(0)
	v_exp_f32_e32 v140, v140
	v_exp_f32_e32 v141, v141
	s_nop 0
	v_pk_add_f32 v[140:141], v[140:141], 1.0 op_sel_hi:[1,0]
	v_rcp_f32_e32 v140, v140
	v_rcp_f32_e32 v141, v141
	v_pk_mul_f32 v[134:135], v[142:143], v[134:135]
	v_exp_f32_e32 v172, v172
	v_pk_mul_f32 v[134:135], v[134:135], v[140:141]
	v_pk_mul_f32 v[140:141], v[136:137], s[88:89] op_sel_hi:[1,0]
	v_exp_f32_e32 v173, v173
	v_exp_f32_e32 v140, v140
	v_exp_f32_e32 v141, v141
	v_pk_mul_f32 v[128:129], v[136:137], v[128:129]
	v_pk_mul_f32 v[136:137], v[138:139], s[88:89] op_sel_hi:[1,0]
	s_waitcnt lgkmcnt(0)
	v_exp_f32_e32 v136, v136
	v_exp_f32_e32 v137, v137
	v_pk_add_f32 v[172:173], v[172:173], 1.0 op_sel_hi:[1,0]
	v_pk_add_f32 v[140:141], v[140:141], 1.0 op_sel_hi:[1,0]
	v_rcp_f32_e32 v172, v172
	v_rcp_f32_e32 v173, v173
	v_rcp_f32_e32 v140, v140
	v_rcp_f32_e32 v141, v141
	v_pk_add_f32 v[136:137], v[136:137], 1.0 op_sel_hi:[1,0]
	s_waitcnt lgkmcnt(0)
; __device__ __forceinline__ unsigned cvt_pk_bf16(float lo, float hi) { unsigned r; asm volatile("v_cvt_pk_bf16_f32 %0, %1, %2" : "=v"(r) : "v"(lo), "v"(hi)); return r; }
; __device__ __forceinline__ f32x2 silu_mul_pk(f32x2 g, f32x2 u) {
;     const f32x2 t = g * (-1.4426950409f);
;     f32x2 e; e.x = __builtin_amdgcn_exp2f(t.x); e.y = __builtin_amdgcn_exp2f(t.y);
;     const f32x2 d = e + 1.0f;
;     f32x2 r; r.x = __builtin_amdgcn_rcpf(d.x); r.y = __builtin_amdgcn_rcpf(d.y);
;     return (g * u) * r;
; }
;     __device__ __forceinline__ void operator()(const f32x4 (&acc)[2][2][4][2], const pg8::Unit& u, int wr, int wc, int fr_, int fq_) const {
;     ...
;             for (int m = 0; m < 4; ++m) {
;                 const int lr = lrow0 + ai * 128 + m * 16;
;                 const float rs = rs8[ai * 4 + m];
;                 const f32x4 g0 = acc[ai][0][m][0] * rs + sv[0][0], g1 = acc[ai][0][m][1] * rs + sv[0][1];
;                 const f32x4 u0 = acc[ai][1][m][0] * rs + sv[1][0], u1 = acc[ai][1][m][1] * rs + sv[1][1];
;                 const f32x2 ha = pg8::silu_mul_pk((f32x2){g0[0], g0[1]}, (f32x2){u0[0], u0[1]}), hb = pg8::silu_mul_pk((f32x2){g0[2], g0[3]}, (f32x2){u0[2], u0[3]});
;                 const f32x2 hc = pg8::silu_mul_pk((f32x2){g1[0], g1[1]}, (f32x2){u1[0], u1[1]}), hd = pg8::silu_mul_pk((f32x2){g1[2], g1[3]}, (f32x2){u1[2], u1[3]});
;                 u32x4 w; w.x = cvt_pk_bf16(ha.x, ha.y); w.y = cvt_pk_bf16(hb.x, hb.y); w.z = cvt_pk_bf16(hc.x, hc.y); w.w = cvt_pk_bf16(hd.x, hd.y);
;                 *(u32x4*)(H + (size_t)lr * FF + hcol) = w;
	v_rcp_f32_e32 v136, v136
	v_rcp_f32_e32 v137, v137
	v_lshl_add_u32 v174, v167, 3, s2
	v_pk_mul_f32 v[132:133], v[132:133], v[172:173]
	v_pk_mul_f32 v[130:131], v[138:139], v[130:131]
	v_pk_mul_f32 v[128:129], v[128:129], v[140:141]
	v_ashrrev_i32_e32 v175, 31, v174
	v_pk_mul_f32 v[130:131], v[130:131], v[136:137]
	v_cvt_pk_bf16_f32 v132, v132, v133
	v_cvt_pk_bf16_f32 v133, v134, v135
	v_cvt_pk_bf16_f32 v134, v128, v129
	v_mov_b64_e32 v[128:129], s[30:31]
	s_movk_i32 s2, 0x1600
	v_cvt_pk_bf16_f32 v135, v130, v131
	v_mad_i64_i32 v[136:137], s[26:27], v165, s2, v[128:129]
	v_lshlrev_b64 v[130:131], 1, v[174:175]
	v_lshl_add_u64 v[136:137], v[136:137], 0, v[130:131]
	global_store_dwordx4 v[136:137], v[132:135], off
	v_pk_fma_f32 v[66:67], v[66:67], v[166:167], v[82:83] op_sel_hi:[1,0,1]
	v_pk_fma_f32 v[62:63], v[62:63], v[164:165], v[94:95] op_sel_hi:[1,0,1]
	v_pk_mul_f32 v[132:133], v[124:125], s[88:89] op_sel_hi:[1,0]
	v_pk_mul_f32 v[124:125], v[126:127], s[88:89] op_sel_hi:[1,0]
	v_exp_f32_e32 v132, v132
	v_exp_f32_e32 v124, v124
	v_exp_f32_e32 v125, v125
	v_exp_f32_e32 v133, v133
	v_or_b32_e32 v134, 16, v165
	v_pk_mul_f32 v[66:67], v[74:75], v[66:67]
	v_pk_add_f32 v[124:125], v[124:125], 1.0 op_sel_hi:[1,0]
	v_pk_add_f32 v[132:133], v[132:133], 1.0 op_sel_hi:[1,0]
	v_rcp_f32_e32 v124, v124
	v_rcp_f32_e32 v125, v125
	v_rcp_f32_e32 v132, v132
	v_rcp_f32_e32 v133, v133
	v_pk_fma_f32 v[60:61], v[60:61], v[164:165], v[92:93] op_sel_hi:[1,0,1]
	v_pk_mul_f32 v[118:119], v[118:119], v[124:125]
	v_pk_mul_f32 v[124:125], v[120:121], s[88:89] op_sel_hi:[1,0]
	v_pk_mul_f32 v[116:117], v[116:117], v[132:133]
	v_exp_f32_e32 v124, v124
	v_exp_f32_e32 v125, v125
	v_pk_fma_f32 v[52:53], v[52:53], v[164:165], v[84:85] op_sel_hi:[1,0,1]
	v_pk_fma_f32 v[54:55], v[54:55], v[164:165], v[86:87] op_sel_hi:[1,0,1]
	v_pk_mul_f32 v[52:53], v[60:61], v[52:53]
	v_pk_add_f32 v[124:125], v[124:125], 1.0 op_sel_hi:[1,0]
	v_pk_fma_f32 v[56:57], v[56:57], v[164:165], v[88:89] op_sel_hi:[1,0,1]
	v_rcp_f32_e32 v124, v124
	v_rcp_f32_e32 v125, v125
	v_pk_mul_f32 v[54:55], v[62:63], v[54:55]
	v_pk_fma_f32 v[48:49], v[48:49], v[164:165], v[80:81] op_sel_hi:[1,0,1]
	v_pk_fma_f32 v[58:59], v[58:59], v[164:165], v[90:91] op_sel_hi:[1,0,1]
	v_pk_mul_f32 v[120:121], v[112:113], v[124:125]
	v_pk_mul_f32 v[112:113], v[122:123], s[88:89] op_sel_hi:[1,0]
	v_pk_mul_f32 v[48:49], v[56:57], v[48:49]
	v_exp_f32_e32 v112, v112
	v_exp_f32_e32 v113, v113
	v_pk_fma_f32 v[50:51], v[50:51], v[164:165], v[82:83] op_sel_hi:[1,0,1]
	v_pk_fma_f32 v[46:47], v[46:47], v[162:163], v[94:95] op_sel_hi:[1,0,1]
	v_pk_mul_f32 v[50:51], v[58:59], v[50:51]
	v_pk_add_f32 v[112:113], v[112:113], 1.0 op_sel_hi:[1,0]
	v_pk_fma_f32 v[44:45], v[44:45], v[162:163], v[92:93] op_sel_hi:[1,0,1]
	v_rcp_f32_e32 v112, v112
	v_rcp_f32_e32 v113, v113
	v_pk_fma_f32 v[36:37], v[36:37], v[162:163], v[84:85] op_sel_hi:[1,0,1]
	v_pk_fma_f32 v[38:39], v[38:39], v[162:163], v[86:87] op_sel_hi:[1,0,1]
	v_pk_mul_f32 v[36:37], v[44:45], v[36:37]
	v_pk_mul_f32 v[122:123], v[114:115], v[112:113]
	v_cvt_pk_bf16_f32 v112, v116, v117
	v_mad_i64_i32 v[116:117], s[26:27], v134, s2, v[128:129]
	v_cvt_pk_bf16_f32 v113, v118, v119
	v_lshl_add_u64 v[116:117], v[116:117], 0, v[130:131]
	v_cvt_pk_bf16_f32 v114, v120, v121
	v_cvt_pk_bf16_f32 v115, v122, v123
	global_store_dwordx4 v[116:117], v[112:115], off
	v_pk_fma_f32 v[40:41], v[40:41], v[162:163], v[88:89] op_sel_hi:[1,0,1]
	v_pk_mul_f32 v[38:39], v[46:47], v[38:39]
	v_pk_mul_f32 v[112:113], v[108:109], s[88:89] op_sel_hi:[1,0]
	v_pk_mul_f32 v[108:109], v[110:111], s[88:89] op_sel_hi:[1,0]
	v_exp_f32_e32 v112, v112
	v_exp_f32_e32 v108, v108
	v_exp_f32_e32 v109, v109
	v_exp_f32_e32 v113, v113
	v_or_b32_e32 v114, 32, v165
	v_pk_fma_f32 v[32:33], v[32:33], v[162:163], v[80:81] op_sel_hi:[1,0,1]
	v_pk_add_f32 v[108:109], v[108:109], 1.0 op_sel_hi:[1,0]
	v_pk_add_f32 v[112:113], v[112:113], 1.0 op_sel_hi:[1,0]
	v_rcp_f32_e32 v108, v108
	v_rcp_f32_e32 v109, v109
	v_rcp_f32_e32 v112, v112
	v_rcp_f32_e32 v113, v113
	v_pk_fma_f32 v[42:43], v[42:43], v[162:163], v[90:91] op_sel_hi:[1,0,1]
	v_pk_mul_f32 v[102:103], v[102:103], v[108:109]
	v_pk_mul_f32 v[108:109], v[104:105], s[88:89] op_sel_hi:[1,0]
	v_pk_mul_f32 v[100:101], v[100:101], v[112:113]
	v_exp_f32_e32 v108, v108
	v_exp_f32_e32 v109, v109
	v_pk_mul_f32 v[32:33], v[40:41], v[32:33]
	v_pk_add_f32 v[108:109], v[108:109], 1.0 op_sel_hi:[1,0]
	v_pk_fma_f32 v[34:35], v[34:35], v[162:163], v[82:83] op_sel_hi:[1,0,1]
	v_rcp_f32_e32 v108, v108
	v_rcp_f32_e32 v109, v109
	v_pk_mul_f32 v[34:35], v[42:43], v[34:35]
	v_pk_mul_f32 v[104:105], v[96:97], v[108:109]
	v_pk_mul_f32 v[96:97], v[106:107], s[88:89] op_sel_hi:[1,0]
	v_exp_f32_e32 v96, v96
	v_exp_f32_e32 v97, v97
	v_mov_b32_e32 v160, v214
	v_pk_fma_f32 v[30:31], v[30:31], v[160:161], v[94:95] op_sel_hi:[1,0,1]
	v_pk_fma_f32 v[28:29], v[28:29], v[160:161], v[92:93] op_sel_hi:[1,0,1]
	v_pk_add_f32 v[96:97], v[96:97], 1.0 op_sel_hi:[1,0]
	v_pk_fma_f32 v[20:21], v[20:21], v[160:161], v[84:85] op_sel_hi:[1,0,1]
	v_rcp_f32_e32 v96, v96
	v_rcp_f32_e32 v97, v97
	v_pk_mul_f32 v[20:21], v[28:29], v[20:21]
	v_pk_fma_f32 v[22:23], v[22:23], v[160:161], v[86:87] op_sel_hi:[1,0,1]
	v_pk_fma_f32 v[24:25], v[24:25], v[160:161], v[88:89] op_sel_hi:[1,0,1]
	v_pk_mul_f32 v[106:107], v[98:99], v[96:97]
	v_cvt_pk_bf16_f32 v96, v100, v101
	v_mad_i64_i32 v[100:101], s[26:27], v114, s2, v[128:129]
	v_cvt_pk_bf16_f32 v97, v102, v103
	v_lshl_add_u64 v[100:101], v[100:101], 0, v[130:131]
	v_cvt_pk_bf16_f32 v98, v104, v105
	v_cvt_pk_bf16_f32 v99, v106, v107
	global_store_dwordx4 v[100:101], v[96:99], off
; __device__ __forceinline__ unsigned cvt_pk_bf16(float lo, float hi) { unsigned r; asm volatile("v_cvt_pk_bf16_f32 %0, %1, %2" : "=v"(r) : "v"(lo), "v"(hi)); return r; }
; __device__ __forceinline__ f32x2 silu_mul_pk(f32x2 g, f32x2 u) {
;     const f32x2 t = g * (-1.4426950409f);
;     f32x2 e; e.x = __builtin_amdgcn_exp2f(t.x); e.y = __builtin_amdgcn_exp2f(t.y);
;     const f32x2 d = e + 1.0f;
;     f32x2 r; r.x = __builtin_amdgcn_rcpf(d.x); r.y = __builtin_amdgcn_rcpf(d.y);
;     return (g * u) * r;
; }
;     __device__ __forceinline__ void operator()(const f32x4 (&acc)[2][2][4][2], const pg8::Unit& u, int wr, int wc, int fr_, int fq_) const {
;     ...
;             for (int m = 0; m < 4; ++m) {
;                 const int lr = lrow0 + ai * 128 + m * 16;
;                 const float rs = rs8[ai * 4 + m];
;                 const f32x4 g0 = acc[ai][0][m][0] * rs + sv[0][0], g1 = acc[ai][0][m][1] * rs + sv[0][1];
;                 const f32x4 u0 = acc[ai][1][m][0] * rs + sv[1][0], u1 = acc[ai][1][m][1] * rs + sv[1][1];
;                 const f32x2 ha = pg8::silu_mul_pk((f32x2){g0[0], g0[1]}, (f32x2){u0[0], u0[1]}), hb = pg8::silu_mul_pk((f32x2){g0[2], g0[3]}, (f32x2){u0[2], u0[3]});
;                 const f32x2 hc = pg8::silu_mul_pk((f32x2){g1[0], g1[1]}, (f32x2){u1[0], u1[1]}), hd = pg8::silu_mul_pk((f32x2){g1[2], g1[3]}, (f32x2){u1[2], u1[3]});
;                 u32x4 w; w.x = cvt_pk_bf16(ha.x, ha.y); w.y = cvt_pk_bf16(hb.x, hb.y); w.z = cvt_pk_bf16(hc.x, hc.y); w.w = cvt_pk_bf16(hd.x, hd.y);
;                 *(u32x4*)(H + (size_t)lr * FF + hcol) = w;
	v_pk_mul_f32 v[22:23], v[30:31], v[22:23]
	v_pk_fma_f32 v[16:17], v[16:17], v[160:161], v[80:81] op_sel_hi:[1,0,1]
	v_pk_mul_f32 v[96:97], v[76:77], s[88:89] op_sel_hi:[1,0]
	v_pk_mul_f32 v[76:77], v[78:79], s[88:89] op_sel_hi:[1,0]
	v_exp_f32_e32 v96, v96
	v_exp_f32_e32 v76, v76
	v_exp_f32_e32 v77, v77
	v_exp_f32_e32 v97, v97
	v_or_b32_e32 v98, 48, v165
	v_pk_fma_f32 v[26:27], v[26:27], v[160:161], v[90:91] op_sel_hi:[1,0,1]
	v_pk_add_f32 v[76:77], v[76:77], 1.0 op_sel_hi:[1,0]
	v_pk_add_f32 v[96:97], v[96:97], 1.0 op_sel_hi:[1,0]
	v_rcp_f32_e32 v76, v76
	v_rcp_f32_e32 v77, v77
	v_rcp_f32_e32 v96, v96
	v_rcp_f32_e32 v97, v97
	v_pk_mul_f32 v[16:17], v[24:25], v[16:17]
	v_pk_mul_f32 v[70:71], v[70:71], v[76:77]
	v_pk_mul_f32 v[76:77], v[72:73], s[88:89] op_sel_hi:[1,0]
	v_pk_mul_f32 v[68:69], v[68:69], v[96:97]
	v_exp_f32_e32 v76, v76
	v_exp_f32_e32 v77, v77
	v_pk_fma_f32 v[18:19], v[18:19], v[160:161], v[82:83] op_sel_hi:[1,0,1]
	v_pk_add_f32 v[76:77], v[76:77], 1.0 op_sel_hi:[1,0]
	v_rcp_f32_e32 v76, v76
	v_rcp_f32_e32 v77, v77
	v_pk_mul_f32 v[18:19], v[26:27], v[18:19]
	v_pk_mul_f32 v[72:73], v[64:65], v[76:77]
	v_pk_mul_f32 v[64:65], v[74:75], s[88:89] op_sel_hi:[1,0]
	v_exp_f32_e32 v64, v64
	v_exp_f32_e32 v65, v65
	v_mov_b32_e32 v158, v215
	v_pk_fma_f32 v[14:15], v[14:15], v[158:159], v[94:95] op_sel_hi:[1,0,1]
	v_pk_fma_f32 v[12:13], v[12:13], v[158:159], v[92:93] op_sel_hi:[1,0,1]
	v_pk_add_f32 v[64:65], v[64:65], 1.0 op_sel_hi:[1,0]
	v_pk_fma_f32 v[4:5], v[4:5], v[158:159], v[84:85] op_sel_hi:[1,0,1]
	v_rcp_f32_e32 v64, v64
	v_rcp_f32_e32 v65, v65
	v_pk_mul_f32 v[4:5], v[12:13], v[4:5]
	v_pk_fma_f32 v[6:7], v[6:7], v[158:159], v[86:87] op_sel_hi:[1,0,1]
	v_pk_fma_f32 v[8:9], v[8:9], v[158:159], v[88:89] op_sel_hi:[1,0,1]
	v_pk_mul_f32 v[74:75], v[66:67], v[64:65]
	v_cvt_pk_bf16_f32 v64, v68, v69
	v_mad_i64_i32 v[68:69], s[26:27], v98, s2, v[128:129]
	v_cvt_pk_bf16_f32 v65, v70, v71
	v_lshl_add_u64 v[68:69], v[68:69], 0, v[130:131]
	v_cvt_pk_bf16_f32 v66, v72, v73
	v_cvt_pk_bf16_f32 v67, v74, v75
	global_store_dwordx4 v[68:69], v[64:67], off
	v_pk_mul_f32 v[6:7], v[14:15], v[6:7]
	v_pk_fma_f32 v[0:1], v[0:1], v[158:159], v[80:81] op_sel_hi:[1,0,1]
	v_pk_mul_f32 v[64:65], v[60:61], s[88:89] op_sel_hi:[1,0]
	v_pk_mul_f32 v[60:61], v[62:63], s[88:89] op_sel_hi:[1,0]
	v_exp_f32_e32 v64, v64
	v_exp_f32_e32 v60, v60
	v_exp_f32_e32 v61, v61
	v_exp_f32_e32 v65, v65
	v_add_u32_e32 v66, 0x80, v165
	v_pk_fma_f32 v[10:11], v[10:11], v[158:159], v[90:91] op_sel_hi:[1,0,1]
	v_pk_add_f32 v[60:61], v[60:61], 1.0 op_sel_hi:[1,0]
	v_pk_add_f32 v[64:65], v[64:65], 1.0 op_sel_hi:[1,0]
	v_rcp_f32_e32 v60, v60
	v_rcp_f32_e32 v61, v61
	v_rcp_f32_e32 v64, v64
	v_rcp_f32_e32 v65, v65
	v_pk_mul_f32 v[0:1], v[8:9], v[0:1]
	v_pk_mul_f32 v[54:55], v[54:55], v[60:61]
	v_pk_mul_f32 v[60:61], v[56:57], s[88:89] op_sel_hi:[1,0]
	v_pk_mul_f32 v[52:53], v[52:53], v[64:65]
	v_exp_f32_e32 v60, v60
	v_exp_f32_e32 v61, v61
	v_pk_fma_f32 v[2:3], v[2:3], v[158:159], v[82:83] op_sel_hi:[1,0,1]
	s_andn2_b64 vcc, exec, s[36:37]
	v_pk_mul_f32 v[2:3], v[10:11], v[2:3]
	v_pk_add_f32 v[60:61], v[60:61], 1.0 op_sel_hi:[1,0]
	s_nop 0
	v_rcp_f32_e32 v60, v60
	v_rcp_f32_e32 v61, v61
	s_nop 0
	v_pk_mul_f32 v[56:57], v[48:49], v[60:61]
	v_pk_mul_f32 v[48:49], v[58:59], s[88:89] op_sel_hi:[1,0]
	s_nop 0
	v_exp_f32_e32 v48, v48
	v_exp_f32_e32 v49, v49
	s_nop 0
	v_pk_add_f32 v[48:49], v[48:49], 1.0 op_sel_hi:[1,0]
	s_nop 0
	v_rcp_f32_e32 v48, v48
	v_rcp_f32_e32 v49, v49
	s_nop 0
	v_pk_mul_f32 v[58:59], v[50:51], v[48:49]
	v_cvt_pk_bf16_f32 v48, v52, v53
	v_mad_i64_i32 v[52:53], s[26:27], v66, s2, v[128:129]
	v_cvt_pk_bf16_f32 v49, v54, v55
	v_lshl_add_u64 v[52:53], v[52:53], 0, v[130:131]
	v_cvt_pk_bf16_f32 v50, v56, v57
	v_cvt_pk_bf16_f32 v51, v58, v59
	global_store_dwordx4 v[52:53], v[48:51], off
	s_nop 1
	v_pk_mul_f32 v[48:49], v[44:45], s[88:89] op_sel_hi:[1,0]
	v_pk_mul_f32 v[44:45], v[46:47], s[88:89] op_sel_hi:[1,0]
	v_exp_f32_e32 v48, v48
	v_exp_f32_e32 v44, v44
	v_exp_f32_e32 v45, v45
; __device__ __forceinline__ unsigned cvt_pk_bf16(float lo, float hi) { unsigned r; asm volatile("v_cvt_pk_bf16_f32 %0, %1, %2" : "=v"(r) : "v"(lo), "v"(hi)); return r; }
; #define PG8_BAR __builtin_amdgcn_s_barrier()
; template <class Epi, class Sched, bool ALIGN_EPI, bool SP2>
; __device__ __forceinline__ void gemm_phase(PG8_LAS unsigned char* lds, const Gemm g, const Sched& S, const Epi& E, int wid) {
;     ...
;         if (!has_next) break;
; #pragma unroll
;         for (int a = 0; a < 2; ++a)
; #pragma unroll
;             for (int b = 0; b < 2; ++b)
; #pragma unroll
;                 for (int m = 0; m < 4; ++m)
; #pragma unroll
;                     for (int n = 0; n < 2; ++n) acc[a][b][m][n] = (f32x4){0.f, 0.f, 0.f, 0.f};
;         cur = nxt; cA = nA; cB = nB; ++ui;
;         if constexpr (ALIGN_EPI) { if (wr == 1) PG8_BAR; }
;     }
;     __device__ __forceinline__ void operator()(const f32x4 (&acc)[2][2][4][2], const pg8::Unit& u, int wr, int wc, int fr_, int fq_) const {
;     ...
;             for (int m = 0; m < 4; ++m) {
;                 const int lr = lrow0 + ai * 128 + m * 16;
;                 const float rs = rs8[ai * 4 + m];
;                 const f32x4 g0 = acc[ai][0][m][0] * rs + sv[0][0], g1 = acc[ai][0][m][1] * rs + sv[0][1];
;                 const f32x4 u0 = acc[ai][1][m][0] * rs + sv[1][0], u1 = acc[ai][1][m][1] * rs + sv[1][1];
;                 const f32x2 ha = pg8::silu_mul_pk((f32x2){g0[0], g0[1]}, (f32x2){u0[0], u0[1]}), hb = pg8::silu_mul_pk((f32x2){g0[2], g0[3]}, (f32x2){u0[2], u0[3]});
;                 const f32x2 hc = pg8::silu_mul_pk((f32x2){g1[0], g1[1]}, (f32x2){u1[0], u1[1]}), hd = pg8::silu_mul_pk((f32x2){g1[2], g1[3]}, (f32x2){u1[2], u1[3]});
;                 u32x4 w; w.x = cvt_pk_bf16(ha.x, ha.y); w.y = cvt_pk_bf16(hb.x, hb.y); w.z = cvt_pk_bf16(hc.x, hc.y); w.w = cvt_pk_bf16(hd.x, hd.y);
;                 *(u32x4*)(H + (size_t)lr * FF + hcol) = w;
	v_exp_f32_e32 v49, v49
	v_add_u32_e32 v50, 0x90, v165
	v_pk_add_f32 v[44:45], v[44:45], 1.0 op_sel_hi:[1,0]
	s_nop 0
	v_rcp_f32_e32 v44, v44
	v_rcp_f32_e32 v45, v45
	v_pk_add_f32 v[48:49], v[48:49], 1.0 op_sel_hi:[1,0]
	v_pk_mul_f32 v[38:39], v[38:39], v[44:45]
	v_pk_mul_f32 v[44:45], v[40:41], s[88:89] op_sel_hi:[1,0]
	v_rcp_f32_e32 v48, v48
	v_exp_f32_e32 v44, v44
	v_exp_f32_e32 v45, v45
	v_rcp_f32_e32 v49, v49
	v_pk_add_f32 v[44:45], v[44:45], 1.0 op_sel_hi:[1,0]
	s_nop 0
	v_rcp_f32_e32 v44, v44
	v_rcp_f32_e32 v45, v45
	v_pk_mul_f32 v[36:37], v[36:37], v[48:49]
	v_pk_mul_f32 v[40:41], v[32:33], v[44:45]
	v_pk_mul_f32 v[32:33], v[42:43], s[88:89] op_sel_hi:[1,0]
	s_nop 0
	v_exp_f32_e32 v32, v32
	v_exp_f32_e32 v33, v33
	s_nop 0
	v_pk_add_f32 v[32:33], v[32:33], 1.0 op_sel_hi:[1,0]
	s_nop 0
	v_rcp_f32_e32 v32, v32
	v_rcp_f32_e32 v33, v33
	s_nop 0
	v_pk_mul_f32 v[42:43], v[34:35], v[32:33]
	v_cvt_pk_bf16_f32 v32, v36, v37
	v_mad_i64_i32 v[36:37], s[26:27], v50, s2, v[128:129]
	v_cvt_pk_bf16_f32 v33, v38, v39
	v_lshl_add_u64 v[36:37], v[36:37], 0, v[130:131]
	v_cvt_pk_bf16_f32 v34, v40, v41
	v_cvt_pk_bf16_f32 v35, v42, v43
	global_store_dwordx4 v[36:37], v[32:35], off
	s_nop 1
	v_pk_mul_f32 v[32:33], v[28:29], s[88:89] op_sel_hi:[1,0]
	v_pk_mul_f32 v[28:29], v[30:31], s[88:89] op_sel_hi:[1,0]
	v_exp_f32_e32 v32, v32
	v_exp_f32_e32 v28, v28
	v_exp_f32_e32 v29, v29
	v_exp_f32_e32 v33, v33
	v_add_u32_e32 v34, 0xa0, v165
	v_pk_add_f32 v[28:29], v[28:29], 1.0 op_sel_hi:[1,0]
	s_nop 0
	v_rcp_f32_e32 v28, v28
	v_rcp_f32_e32 v29, v29
	v_pk_add_f32 v[32:33], v[32:33], 1.0 op_sel_hi:[1,0]
	v_pk_mul_f32 v[22:23], v[22:23], v[28:29]
	v_pk_mul_f32 v[28:29], v[24:25], s[88:89] op_sel_hi:[1,0]
	v_rcp_f32_e32 v32, v32
	v_exp_f32_e32 v28, v28
	v_exp_f32_e32 v29, v29
	v_rcp_f32_e32 v33, v33
	v_pk_add_f32 v[28:29], v[28:29], 1.0 op_sel_hi:[1,0]
	s_nop 0
	v_rcp_f32_e32 v28, v28
	v_rcp_f32_e32 v29, v29
	v_pk_mul_f32 v[20:21], v[20:21], v[32:33]
	v_pk_mul_f32 v[24:25], v[16:17], v[28:29]
	v_pk_mul_f32 v[16:17], v[26:27], s[88:89] op_sel_hi:[1,0]
	s_nop 0
	v_exp_f32_e32 v16, v16
	v_exp_f32_e32 v17, v17
	s_nop 0
	v_pk_add_f32 v[16:17], v[16:17], 1.0 op_sel_hi:[1,0]
	s_nop 0
	v_rcp_f32_e32 v16, v16
	v_rcp_f32_e32 v17, v17
	s_nop 0
	v_pk_mul_f32 v[26:27], v[18:19], v[16:17]
	v_cvt_pk_bf16_f32 v16, v20, v21
	v_mad_i64_i32 v[20:21], s[26:27], v34, s2, v[128:129]
	v_cvt_pk_bf16_f32 v17, v22, v23
	v_lshl_add_u64 v[20:21], v[20:21], 0, v[130:131]
	v_cvt_pk_bf16_f32 v18, v24, v25
	v_cvt_pk_bf16_f32 v19, v26, v27
	global_store_dwordx4 v[20:21], v[16:19], off
	s_nop 1
	v_pk_mul_f32 v[16:17], v[12:13], s[88:89] op_sel_hi:[1,0]
	v_pk_mul_f32 v[12:13], v[14:15], s[88:89] op_sel_hi:[1,0]
	v_exp_f32_e32 v16, v16
	v_exp_f32_e32 v12, v12
	v_exp_f32_e32 v13, v13
	v_exp_f32_e32 v17, v17
	v_add_u32_e32 v18, 0xb0, v165
	v_pk_add_f32 v[12:13], v[12:13], 1.0 op_sel_hi:[1,0]
	s_nop 0
	v_rcp_f32_e32 v12, v12
	v_rcp_f32_e32 v13, v13
	v_pk_add_f32 v[16:17], v[16:17], 1.0 op_sel_hi:[1,0]
	v_pk_mul_f32 v[6:7], v[6:7], v[12:13]
	v_pk_mul_f32 v[12:13], v[8:9], s[88:89] op_sel_hi:[1,0]
	v_rcp_f32_e32 v16, v16
	v_exp_f32_e32 v12, v12
	v_exp_f32_e32 v13, v13
	v_rcp_f32_e32 v17, v17
	v_pk_add_f32 v[12:13], v[12:13], 1.0 op_sel_hi:[1,0]
	s_nop 0
	v_rcp_f32_e32 v12, v12
	v_rcp_f32_e32 v13, v13
	v_pk_mul_f32 v[4:5], v[4:5], v[16:17]
	v_pk_mul_f32 v[8:9], v[0:1], v[12:13]
	v_pk_mul_f32 v[0:1], v[10:11], s[88:89] op_sel_hi:[1,0]
	s_nop 0
	v_exp_f32_e32 v0, v0
	v_exp_f32_e32 v1, v1
	s_nop 0
	v_pk_add_f32 v[0:1], v[0:1], 1.0 op_sel_hi:[1,0]
	s_nop 0
	v_rcp_f32_e32 v0, v0
	v_rcp_f32_e32 v1, v1
	s_nop 0
	v_pk_mul_f32 v[10:11], v[2:3], v[0:1]
	v_cvt_pk_bf16_f32 v0, v4, v5
	v_mad_i64_i32 v[4:5], s[26:27], v18, s2, v[128:129]
	v_lshl_add_u64 v[4:5], v[4:5], 0, v[130:131]
	s_mov_b64 s[26:27], -1
	v_cvt_pk_bf16_f32 v1, v6, v7
	v_cvt_pk_bf16_f32 v2, v8, v9
	v_cvt_pk_bf16_f32 v3, v10, v11
	global_store_dwordx4 v[4:5], v[0:3], off
	s_cbranch_vccnz .LBB0_369
	s_and_b64 vcc, exec, s[34:35]
	s_cbranch_vccnz .LBB0_368
	s_branch .LBB0_368

; #define PG8_STAGE(bufoff, gbase, voff) do { _Pragma("unroll") for (int _i = 0; _i < 2; ++_i) \
;         __builtin_amdgcn_global_load_lds((const unsigned*)((const char*)(gbase) + (voff)[_i]), (PG8_LAS unsigned*)(lds + (bufoff) + ldsw + _i * (8 * USTR)), 16, 0, 0); } while (0)
; #define PG8_WAIT_V(n) asm volatile("s_waitcnt vmcnt(" #n ")" ::: "memory")
; #define PG8_BAR __builtin_amdgcn_s_barrier()
; template <class Epi, class Sched, bool ALIGN_EPI, bool SP2>
; __device__ __forceinline__ void gemm_phase(PG8_LAS unsigned char* lds, const Gemm g, const Sched& S, const Epi& E, int wid) {
;     ...
; #pragma unroll
;     for (int i = 0; i < 2; ++i) { const int u_ = wid + 8 * i, rr_ = lane >> 3, ch_ = (lane & 7) ^ ((rr_ >> 1) & 3); const int R = u_ * 8 + rr_, C = ch_ * 8;
;         const int Rb = Epi::PERM ? ((R & ~31) + perm32(R & 31)) : R;
;         voffA[i] = (unsigned)(R * lda + C) * 2u; voffB[i] = (unsigned)(Rb * K + C) * 2u; }
;     ...
;     if constexpr (SP2) {
;         PG8_STAGE(PG8_SB(0, 0), cB, voffB); PG8_STAGE(PG8_SB(0, 1), cB + hstepB, voffB); PG8_STAGE(PG8_SA(0, 0), cA, voffA); PG8_STAGE(PG8_SA(0, 1), cA + hstepA, voffA);
;         if (wr == 1) PG8_BAR;
;         PG8_WAIT_V(2); PG8_BAR;
;         PG8_STAGE(PG8_SB(1, 0), cB + kstep, voffB); PG8_STAGE(PG8_SA(1, 0), cA + kstep, voffA); PG8_STAGE(PG8_SB(1, 1), cB + hstepB + kstep, voffB);
;         PG8_WAIT_V(6); PG8_BAR;
.LBB0_384:
	v_readlane_b32 s22, v252, 17
	v_readlane_b32 s23, v252, 18
	s_andn2_b64 vcc, exec, s[22:23]
	s_waitcnt lgkmcnt(0)
	v_mbcnt_lo_u32_b32 v1, -1, 0
	v_mbcnt_hi_u32_b32 v1, -1, v1
	s_cbranch_vccnz .LBB0_483
	v_ashrrev_i32_e32 v0, 3, v1
	v_readlane_b32 s0, v252, 10
	v_and_b32_e32 v5, 3, v0
	v_lshlrev_b32_e32 v144, 4, v1
	s_waitcnt vmcnt(0)
	v_add_u32_e32 v3, s0, v0
	v_add_u32_e32 v4, 64, v3
	s_mov_b32 s0, 0x1fffe0
	v_lshrrev_b32_e32 v6, 2, v3
	v_lshlrev_b32_e32 v7, 1, v3
	v_and_or_b32 v2, v4, s0, v5
	v_and_b32_e32 v6, 4, v6
	v_and_b32_e32 v7, 24, v7
	v_or3_b32 v2, v2, v6, v7
	v_lshlrev_b32_e32 v8, 11, v2
	v_and_b32_e32 v9, 0x70, v144
	v_and_b32_e32 v2, 48, v1
	v_lshlrev_b32_e32 v4, 11, v4
	v_bitop3_b32 v148, v4, v9, v2 bitop3:0xf6
	v_and_or_b32 v4, v3, s0, v5
	v_or3_b32 v4, v4, v6, v7
	v_lshlrev_b32_e32 v4, 11, v4
	s_add_i32 s95, s33, 0
	v_readlane_b32 s22, v255, 24
	v_bitop3_b32 v192, v4, v9, v2 bitop3:0xf6
	s_add_i32 m0, s95, 0x11000
	v_readlane_b32 s23, v255, 25
	v_bitop3_b32 v146, v8, v9, v2 bitop3:0xf6
	v_lshlrev_b32_e32 v3, 11, v3
	v_bitop3_b32 v150, v3, v9, v2 bitop3:0xf6
	s_add_i32 s5, s95, 0x2200
	s_add_i32 s56, s95, 0x4400
	global_load_lds_dwordx4 v192, s[22:23]
	s_add_i32 m0, s95, 0x13200
	s_add_i32 s57, s95, 0x6600
	global_load_lds_dwordx4 v146, s[22:23]
	v_readlane_b32 s22, v255, 22
	s_add_i32 m0, s95, 0x15400
	v_readlane_b32 s23, v255, 23
	s_nop 4
	global_load_lds_dwordx4 v192, s[22:23]
	s_add_i32 m0, s95, 0x17600
	s_nop 0
	global_load_lds_dwordx4 v146, s[22:23]
	v_readlane_b32 s22, v253, 44
	s_mov_b32 m0, s95
	v_readlane_b32 s23, v253, 45
	s_nop 4
	global_load_lds_dwordx4 v150, s[22:23]
	s_mov_b32 m0, s5
	s_nop 0
	global_load_lds_dwordx4 v148, s[22:23]
	v_readlane_b32 s22, v253, 46
	s_mov_b32 m0, s56
	v_readlane_b32 s23, v253, 47
	s_nop 4
	global_load_lds_dwordx4 v150, s[22:23]
	s_mov_b32 m0, s57
	s_nop 0
	global_load_lds_dwordx4 v148, s[22:23]
	v_readlane_b32 s22, v252, 13
	v_readlane_b32 s23, v252, 14
	s_andn2_b64 vcc, exec, s[22:23]
	s_nop 0
	v_cndmask_b32_e64 v3, 0, 1, s[22:23]
	v_cmp_ne_u32_e64 s[34:35], 1, v3
	s_cbranch_vccnz .LBB0_387
.LBB0_387:
	s_movk_i32 s0, 0x70
	v_lshlrev_b32_e32 v12, 7, v1
	v_bitop3_b32 v10, v144, v2, s0 bitop3:0x6c
	v_readlane_b32 s40, v255, 24
	v_bfe_i32 v11, v1, 3, 1
	v_and_b32_e32 v12, 0x380, v12
	s_movk_i32 s0, 0x440
	v_readlane_b32 s41, v255, 25
	v_and_or_b32 v11, v11, s0, v12
	v_lshlrev_b32_e32 v12, 3, v1
	v_lshl_add_u64 v[2:3], s[40:41], 0, v[192:193]
	v_mov_b32_e32 v147, v193
	v_readlane_b32 s38, v253, 44
	v_and_b32_e32 v12, 48, v12
	v_and_b32_e32 v1, -16, v1
	v_lshl_add_u64 v[4:5], s[40:41], 0, v[146:147]
	v_mov_b32_e32 v151, v193
	v_readlane_b32 s39, v253, 45
	v_xad_u32 v1, v12, v1, v11
	v_readlane_b32 s0, v254, 12
	v_lshl_add_u64 v[2:3], v[2:3], 0, s[6:7]
	s_add_i32 m0, s95, 0x19800
	v_lshl_add_u64 v[6:7], s[38:39], 0, v[150:151]
	v_mov_b32_e32 v149, v193
	v_add_u32_e32 v11, s0, v1
	s_mul_i32 s0, s17, 0x1100
	s_waitcnt vmcnt(2)
	s_barrier
	global_load_lds_dwordx4 v[2:3], off
	v_lshl_add_u64 v[2:3], v[4:5], 0, s[6:7]
	s_add_i32 m0, s95, 0x1ba00
	s_add_i32 s29, s95, 0x8800
	v_lshl_add_u64 v[8:9], s[38:39], 0, v[148:149]
	v_add_u32_e32 v197, s0, v1
	global_load_lds_dwordx4 v[2:3], off
	v_lshl_add_u64 v[2:3], v[6:7], 0, s[6:7]
	s_mov_b32 m0, s29
	s_add_i32 s0, s95, 0xaa00
	v_readlane_b32 s22, v255, 26
	global_load_lds_dwordx4 v[2:3], off
	v_lshl_add_u64 v[2:3], v[8:9], 0, s[6:7]
	s_mov_b32 m0, s0
	v_readlane_b32 s23, v255, 27
	global_load_lds_dwordx4 v[2:3], off
	s_nop 0
	v_lshl_add_u64 v[2:3], s[22:23], 0, v[192:193]
	s_add_i32 m0, s95, 0x1dc00
	v_lshlrev_b32_e32 v0, 11, v0
	global_load_lds_dwordx4 v[2:3], off
	v_lshl_add_u64 v[2:3], s[22:23], 0, v[146:147]
	s_add_i32 m0, s95, 0x1fe00
	v_readlane_b32 s2, v254, 17
	global_load_lds_dwordx4 v[2:3], off
	s_waitcnt vmcnt(6)
	v_ashrrev_i32_e32 v145, 31, v144
	v_add3_u32 v154, s2, v10, v0
	v_readlane_b32 s2, v254, 18
	v_readlane_b32 s22, v253, 42
	v_lshl_add_u64 v[152:153], s[96:97], 0, v[144:145]
	v_mov_b32_e32 v155, v193
	v_add3_u32 v156, s2, v10, v0
	v_mov_b32_e32 v157, v193
	s_mov_b32 s89, 0
	v_add_u32_e32 v210, 0, v11
	s_mov_b32 s26, s22
	v_readlane_b32 s2, v253, 29
	s_barrier
	v_readlane_b32 s23, v253, 43
	s_waitcnt vmcnt(0)
	s_branch .LBB0_390

; #define PG8_LAS __attribute__((address_space(3)))
; #define PG8_STAGE(bufoff, gbase, voff) do { _Pragma("unroll") for (int _i = 0; _i < 2; ++_i) \
;         __builtin_amdgcn_global_load_lds((const unsigned*)((const char*)(gbase) + (voff)[_i]), (PG8_LAS unsigned*)(lds + (bufoff) + ldsw + _i * (8 * USTR)), 16, 0, 0); } while (0)
; #define PG8_LDA(dst, b, h) do { _Pragma("unroll") for (int m = 0; m < 4; ++m) _Pragma("unroll") for (int k = 0; k < 2; ++k) dst[m][k] = *(const PG8_LAS bf16x8*)(lds + PG8_SA(b, h) + aoff + m * (2 * USTR) + k * 64); } while (0)
; template <class Epi, class Sched, bool ALIGN_EPI, bool SP2>
; __device__ __forceinline__ void gemm_phase(PG8_LAS unsigned char* lds, const Gemm g, const Sched& S, const Epi& E, int wid) {
;     ...
;         const bool has_next = S.next(ui + 1, nxt);
;         const char* nA = has_next ? (const char*)g.A + (size_t)nxt.pm * tstepA : cA; const char* nB = has_next ? (const char*)g.Bt + (size_t)nxt.pn * tstepB : cB;
;         for (int t = 0; t < nt; t += 2) {
;             const bool last = (t == nt - 2);
;             const char* a1 = cA + (size_t)(t + 1) * kstep;
;             const char* a2 = last ? nA : cA + (size_t)(t + 2) * kstep; const char* b2 = last ? nB : cB + (size_t)(t + 2) * kstep;
;             const char* a3 = a2 + kstep; const char* b3 = b2 + kstep;
;             if constexpr (Epi::PRE == 1) { if (last) {
;                 const char* rsrc; const char* ssrc; E.pre(cur, rsrc, ssrc);
; #pragma unroll
;                 for (int _i = 0; _i < 2; ++_i) __builtin_amdgcn_global_load_lds((const unsigned*)(rsrc + (wid + 8 * _i) * 1024 + lane * 16), (PG8_LAS unsigned*)(lds + LDS_XOFF + (wid + 8 * _i) * 1024), 16, 0, 0);
;                 if (wid == 0) __builtin_amdgcn_global_load_lds((const unsigned*)(ssrc + lane * 16), (PG8_LAS unsigned*)(lds + LDS_XOFF + 16384), 16, 0, 0);
;             } }
;             if constexpr (SP2) {
;             PG8_LDB(B0, 0, 0); PG8_LDB(B1, 0, 1); PG8_SCHED; PG8_LDA(At, 0, 0); PG8_STAGE(PG8_SA(1, 1), a1 + hstepA, voffA);
;             PG8_WAIT_V(8); PG8_WAIT_L(0); PG8_BAR; PG8_MMA(0, 0, At, B0); PG8_MMA(0, 1, At, B1); PG8_BAR; PG8_SCHED;
;     __device__ __forceinline__ void pre(const pg8::Unit& u, const char*& rsrc, const char*& ssrc) const {
;         rsrc = (const char*)(rss + (size_t)(u.pm * 256) * 16); ssrc = (const char*)(S + (size_t)batch_of(u.pm * 256) * DIN + u.pn * 256); }
.LBB0_392:
	s_ashr_i32 s69, s68, 31
	s_lshl_b64 s[22:23], s[68:69], 19
	s_add_u32 s74, s8, s22
	s_addc_u32 s75, s9, s23
	s_and_b64 s[22:23], s[36:37], exec
	s_cselect_b32 s10, s75, s39
	s_cselect_b32 s44, s74, s38
	s_ashr_i32 s73, s72, 31
	s_lshl_b64 s[22:23], s[72:73], 19
	v_readlane_b32 s27, v255, 20
	s_add_u32 s78, s27, s22
	v_readlane_b32 s22, v255, 21
	s_addc_u32 s79, s22, s23
	s_and_b64 s[22:23], s[36:37], exec
	s_cselect_b32 s45, s79, s41
	s_cselect_b32 s69, s78, s40
	s_lshl_b32 s22, s26, 8
	s_add_i32 s27, s22, 0xffff8000
	s_ashr_i32 s23, s22, 31
	s_lshr_b32 s27, s27, 14
	s_lshl_b64 s[42:43], s[22:23], 6
	s_ashr_i32 s23, s26, 4
	s_add_i32 s27, s27, 8
	s_cmpk_lt_i32 s26, 0x80
	v_lshl_add_u64 v[0:1], v[152:153], 0, s[42:43]
	v_readlane_b32 s42, v252, 20
	s_cselect_b32 s23, s23, s27
	s_lshl_b32 s26, s2, 8
	v_readlane_b32 s43, v252, 21
	s_mul_hi_i32 s70, s23, 0x2800
	s_mulk_i32 s23, 0x2800
	s_ashr_i32 s27, s26, 31
	v_lshl_add_u64 v[18:19], v[0:1], 0, s[42:43]
	v_readlane_b32 s42, v254, 36
	s_add_u32 s23, s42, s23
	v_readlane_b32 s42, v254, 37
	s_addc_u32 s70, s42, s70
	s_lshl_b64 s[42:43], s[26:27], 2
	s_add_u32 s42, s23, s42
	s_addc_u32 s43, s70, s43
	s_add_u32 s38, s38, 0x40080
	s_addc_u32 s39, s39, 0
	v_lshl_add_u64 v[16:17], v[0:1], 0, s[18:19]
	s_add_u32 s23, s40, 0x100
	s_waitcnt lgkmcnt(0)
	v_lshl_add_u64 v[20:21], s[42:43], 0, v[144:145]
	s_addc_u32 s70, s41, 0
	s_mov_b32 s71, -2
	s_and_b64 vcc, exec, s[34:35]
	s_cbranch_vccnz .Lhb_mixin
	s_barrier
.Lhb_mixin:
	s_cmp_eq_u32 s71, 12
	s_cselect_b64 s[40:41], -1, 0
	s_add_u32 s42, s38, 0xfffc0080
	s_addc_u32 s43, s39, -1
	s_and_b64 s[40:41], s[40:41], exec
	s_cselect_b32 s43, s10, s43
	s_cselect_b32 s42, s44, s42
	s_cselect_b32 s41, s45, s70
	s_cselect_b32 s40, s69, s23
	s_add_i32 s73, 0, 0x11000
	v_add_u32_e32 v30, s73, v197
	s_add_i32 vcc_lo, 0, 0x15400
	ds_read_b128 v[22:25], v30
	ds_read_b128 v[26:29], v30 offset:64
	ds_read_b128 v[158:161], v30 offset:2176
	ds_read_b128 v[162:165], v30 offset:2240
	v_add_u32_e32 v30, vcc_lo, v197
	ds_read_b128 v[166:169], v30
	ds_read_b128 v[170:173], v30 offset:64
	ds_read_b128 v[174:177], v30 offset:2176
	ds_read_b128 v[178:181], v30 offset:2240
	v_lshl_add_u64 v[30:31], s[38:39], 0, v[154:155]
	s_add_i32 m0, s95, 0xcc00
	ds_read_b128 v[182:185], v210
	ds_read_b128 v[186:189], v210 offset:64
	ds_read_b128 v[212:215], v210 offset:2176
	ds_read_b128 v[216:219], v210 offset:2240
	ds_read_b128 v[220:223], v210 offset:4352
	ds_read_b128 v[224:227], v210 offset:4416
	ds_read_b128 v[228:231], v210 offset:6528
	ds_read_b128 v[242:245], v210 offset:6592
	global_load_lds_dwordx4 v[30:31], off
	v_lshl_add_u64 v[30:31], s[38:39], 0, v[156:157]
	s_add_i32 m0, s95, 0xee00
	s_nop 0
	global_load_lds_dwordx4 v[30:31], off
	s_waitcnt vmcnt(8)
	s_waitcnt lgkmcnt(0)
	s_barrier
	s_setprio 1
	s_waitcnt lgkmcnt(0)
	v_mfma_f32_16x16x32_bf16 v[140:143], v[22:25], v[182:185], 0
	v_mfma_f32_16x16x32_bf16 v[136:139], v[158:161], v[182:185], 0
	v_mfma_f32_16x16x32_bf16 v[124:127], v[22:25], v[212:215], 0
	v_mfma_f32_16x16x32_bf16 v[120:123], v[158:161], v[212:215], 0
	v_mfma_f32_16x16x32_bf16 v[108:111], v[22:25], v[220:223], 0
	v_mfma_f32_16x16x32_bf16 v[104:107], v[158:161], v[220:223], 0
	v_mfma_f32_16x16x32_bf16 v[92:95], v[22:25], v[228:231], 0
	v_mfma_f32_16x16x32_bf16 v[88:91], v[158:161], v[228:231], 0
	v_mfma_f32_16x16x32_bf16 v[140:143], v[26:29], v[186:189], v[140:143]
	v_mfma_f32_16x16x32_bf16 v[136:139], v[162:165], v[186:189], v[136:139]
	v_mfma_f32_16x16x32_bf16 v[124:127], v[26:29], v[216:219], v[124:127]
	v_mfma_f32_16x16x32_bf16 v[120:123], v[162:165], v[216:219], v[120:123]
	v_mfma_f32_16x16x32_bf16 v[108:111], v[26:29], v[224:227], v[108:111]
	v_mfma_f32_16x16x32_bf16 v[104:107], v[162:165], v[224:227], v[104:107]
	v_mfma_f32_16x16x32_bf16 v[92:95], v[26:29], v[242:245], v[92:95]
	v_mfma_f32_16x16x32_bf16 v[88:91], v[162:165], v[242:245], v[88:91]
	s_setprio 0
	s_setprio 1
	v_mfma_f32_16x16x32_bf16 v[132:135], v[166:169], v[182:185], 0
	v_mfma_f32_16x16x32_bf16 v[128:131], v[174:177], v[182:185], 0
	v_mfma_f32_16x16x32_bf16 v[116:119], v[166:169], v[212:215], 0
	v_mfma_f32_16x16x32_bf16 v[112:115], v[174:177], v[212:215], 0
	v_mfma_f32_16x16x32_bf16 v[100:103], v[166:169], v[220:223], 0
	v_mfma_f32_16x16x32_bf16 v[96:99], v[174:177], v[220:223], 0
	v_mfma_f32_16x16x32_bf16 v[84:87], v[166:169], v[228:231], 0
	v_mfma_f32_16x16x32_bf16 v[80:83], v[174:177], v[228:231], 0
	v_mfma_f32_16x16x32_bf16 v[132:135], v[170:173], v[186:189], v[132:135]
	v_mfma_f32_16x16x32_bf16 v[128:131], v[178:181], v[186:189], v[128:131]
	v_mfma_f32_16x16x32_bf16 v[116:119], v[170:173], v[216:219], v[116:119]
	v_mfma_f32_16x16x32_bf16 v[112:115], v[178:181], v[216:219], v[112:115]
	v_mfma_f32_16x16x32_bf16 v[100:103], v[170:173], v[224:227], v[100:103]
	v_mfma_f32_16x16x32_bf16 v[96:99], v[178:181], v[224:227], v[96:99]
	v_mfma_f32_16x16x32_bf16 v[84:87], v[170:173], v[242:245], v[84:87]
	v_mfma_f32_16x16x32_bf16 v[80:83], v[178:181], v[242:245], v[80:83]
	s_setprio 0
	s_barrier
; #define PG8_STAGE(bufoff, gbase, voff) do { _Pragma("unroll") for (int _i = 0; _i < 2; ++_i) \
;         __builtin_amdgcn_global_load_lds((const unsigned*)((const char*)(gbase) + (voff)[_i]), (PG8_LAS unsigned*)(lds + (bufoff) + ldsw + _i * (8 * USTR)), 16, 0, 0); } while (0)
; #define PG8_LDA(dst, b, h) do { _Pragma("unroll") for (int m = 0; m < 4; ++m) _Pragma("unroll") for (int k = 0; k < 2; ++k) dst[m][k] = *(const PG8_LAS bf16x8*)(lds + PG8_SA(b, h) + aoff + m * (2 * USTR) + k * 64); } while (0)
; #define PG8_LDB(dst, b, h) do { _Pragma("unroll") for (int n = 0; n < 2; ++n) _Pragma("unroll") for (int k = 0; k < 2; ++k) dst[n][k] = *(const PG8_LAS bf16x8*)(lds + PG8_SB(b, h) + boff + n * (2 * USTR) + k * 64); } while (0)
; #define PG8_MMA(ai, bj, At, Bt) do { __builtin_amdgcn_s_setprio(1); _Pragma("unroll") for (int m = 0; m < 4; ++m) _Pragma("unroll") for (int n = 0; n < 2; ++n) _Pragma("unroll") for (int k = 0; k < 2; ++k) \
;         acc[ai][bj][m][n] = __builtin_amdgcn_mfma_f32_16x16x32_bf16(Bt[n][k], At[m][k], acc[ai][bj][m][n], 0, 0, 0); __builtin_amdgcn_s_setprio(0); } while (0)
; #define PG8_WAIT_V(n) asm volatile("s_waitcnt vmcnt(" #n ")" ::: "memory")
; #define PG8_WAIT_L(n) asm volatile("s_waitcnt lgkmcnt(" #n ")" ::: "memory")
; #define PG8_BAR __builtin_amdgcn_s_barrier()
; #define PG8_SCHED __builtin_amdgcn_sched_barrier(0)
; template <class Epi, class Sched, bool ALIGN_EPI, bool SP2>
; __device__ __forceinline__ void gemm_phase(PG8_LAS unsigned char* lds, const Gemm g, const Sched& S, const Epi& E, int wid) {
;     ...
;             PG8_LDA(At, 0, 1); PG8_STAGE(PG8_SB(0, 0), b2, voffB); PG8_STAGE(PG8_SB(0, 1), b2 + hstepB, voffB); PG8_STAGE(PG8_SA(0, 0), a2, voffA);
;             PG8_WAIT_V(8); PG8_WAIT_L(0); PG8_BAR; PG8_MMA(1, 0, At, B0); PG8_MMA(1, 1, At, B1); PG8_BAR; PG8_SCHED;
;             PG8_LDB(B0, 1, 0); PG8_LDB(B1, 1, 1); PG8_SCHED; PG8_LDA(At, 1, 0); PG8_STAGE(PG8_SA(0, 1), a2 + hstepA, voffA);
;             PG8_WAIT_V(8); PG8_WAIT_L(0); PG8_BAR; PG8_MMA(0, 0, At, B0); PG8_MMA(0, 1, At, B1); PG8_BAR; PG8_SCHED;
	s_add_i32 s73, s73, s33
	v_lshl_add_u64 v[190:191], s[40:41], 0, v[192:193]
	s_mov_b32 m0, s73
	ds_read_b128 v[182:185], v210 offset:17408
	ds_read_b128 v[186:189], v210 offset:17472
	ds_read_b128 v[212:215], v210 offset:19584
	ds_read_b128 v[216:219], v210 offset:19648
	ds_read_b128 v[220:223], v210 offset:21760
	ds_read_b128 v[224:227], v210 offset:21824
	ds_read_b128 v[228:231], v210 offset:23936
	ds_read_b128 v[242:245], v210 offset:24000
	global_load_lds_dwordx4 v[190:191], off
	s_add_i32 m0, s73, 0x2200
	s_add_u32 s76, s40, 0x40000
	v_lshl_add_u64 v[198:199], s[40:41], 0, v[146:147]
	s_addc_u32 s77, s41, 0
	s_add_i32 s73, vcc_lo, s33
	global_load_lds_dwordx4 v[198:199], off
	v_lshl_add_u64 v[30:31], s[76:77], 0, v[192:193]
	s_mov_b32 m0, s73
	v_lshl_add_u64 v[200:201], s[42:43], 0, v[150:151]
	global_load_lds_dwordx4 v[30:31], off
	v_lshl_add_u64 v[30:31], s[76:77], 0, v[146:147]
	s_add_i32 m0, s73, 0x2200
	v_lshl_add_u64 v[208:209], s[42:43], 0, v[148:149]
	global_load_lds_dwordx4 v[30:31], off
	s_mov_b32 m0, s95
	s_nop 0
	global_load_lds_dwordx4 v[200:201], off
	s_mov_b32 m0, s5
	s_nop 0
	global_load_lds_dwordx4 v[208:209], off
	s_waitcnt vmcnt(8)
	s_waitcnt lgkmcnt(0)
	s_barrier
	s_setprio 1
	s_waitcnt lgkmcnt(0)
	v_mfma_f32_16x16x32_bf16 v[76:79], v[22:25], v[182:185], 0
	v_mfma_f32_16x16x32_bf16 v[72:75], v[158:161], v[182:185], 0
	v_mfma_f32_16x16x32_bf16 v[60:63], v[22:25], v[212:215], 0
	v_mfma_f32_16x16x32_bf16 v[56:59], v[158:161], v[212:215], 0
	v_mfma_f32_16x16x32_bf16 v[44:47], v[22:25], v[220:223], 0
	v_mfma_f32_16x16x32_bf16 v[40:43], v[158:161], v[220:223], 0
	v_mfma_f32_16x16x32_bf16 v[12:15], v[22:25], v[228:231], 0
	v_mfma_f32_16x16x32_bf16 v[8:11], v[158:161], v[228:231], 0
	v_mfma_f32_16x16x32_bf16 v[76:79], v[26:29], v[186:189], v[76:79]
	v_mfma_f32_16x16x32_bf16 v[72:75], v[162:165], v[186:189], v[72:75]
	v_mfma_f32_16x16x32_bf16 v[60:63], v[26:29], v[216:219], v[60:63]
	v_mfma_f32_16x16x32_bf16 v[56:59], v[162:165], v[216:219], v[56:59]
	v_mfma_f32_16x16x32_bf16 v[44:47], v[26:29], v[224:227], v[44:47]
	v_mfma_f32_16x16x32_bf16 v[40:43], v[162:165], v[224:227], v[40:43]
	v_mfma_f32_16x16x32_bf16 v[12:15], v[26:29], v[242:245], v[12:15]
	v_mfma_f32_16x16x32_bf16 v[8:11], v[162:165], v[242:245], v[8:11]
	s_setprio 0
	s_setprio 1
	v_mfma_f32_16x16x32_bf16 v[52:55], v[166:169], v[212:215], 0
	v_mfma_f32_16x16x32_bf16 v[48:51], v[174:177], v[212:215], 0
	v_mfma_f32_16x16x32_bf16 v[36:39], v[166:169], v[220:223], 0
	v_mfma_f32_16x16x32_bf16 v[30:33], v[174:177], v[220:223], 0
	v_mfma_f32_16x16x32_bf16 v[4:7], v[166:169], v[228:231], 0
	v_mfma_f32_16x16x32_bf16 v[0:3], v[174:177], v[228:231], 0
	v_mfma_f32_16x16x32_bf16 v[22:25], v[166:169], v[182:185], 0
	v_mfma_f32_16x16x32_bf16 v[26:29], v[174:177], v[182:185], 0
	v_mfma_f32_16x16x32_bf16 v[52:55], v[170:173], v[216:219], v[52:55]
	v_mfma_f32_16x16x32_bf16 v[48:51], v[178:181], v[216:219], v[48:51]
	v_mfma_f32_16x16x32_bf16 v[36:39], v[170:173], v[224:227], v[36:39]
	v_mfma_f32_16x16x32_bf16 v[30:33], v[178:181], v[224:227], v[30:33]
	v_mfma_f32_16x16x32_bf16 v[4:7], v[170:173], v[242:245], v[4:7]
	v_mfma_f32_16x16x32_bf16 v[0:3], v[178:181], v[242:245], v[0:3]
	v_mfma_f32_16x16x32_bf16 v[22:25], v[170:173], v[186:189], v[22:25]
	v_mfma_f32_16x16x32_bf16 v[26:29], v[178:181], v[186:189], v[26:29]
	s_setprio 0
	s_barrier
	s_add_i32 s73, 0, 0x19800
	v_add_u32_e32 v34, s73, v197
	s_add_i32 s76, 0, 0x1dc00
	ds_read_b128 v[64:67], v34
	ds_read_b128 v[68:71], v34 offset:64
	ds_read_b128 v[158:161], v34 offset:2176
	ds_read_b128 v[162:165], v34 offset:2240
	v_add_u32_e32 v34, s76, v197
	ds_read_b128 v[166:169], v34
	ds_read_b128 v[170:173], v34 offset:64
	ds_read_b128 v[174:177], v34 offset:2176
	ds_read_b128 v[178:181], v34 offset:2240
	s_add_u32 s42, s42, 0x40000
	s_addc_u32 s43, s43, 0
	s_mov_b32 m0, s56
	v_lshl_add_u64 v[34:35], s[42:43], 0, v[150:151]
	ds_read_b128 v[182:185], v210 offset:34816
	ds_read_b128 v[186:189], v210 offset:34880
	ds_read_b128 v[212:215], v210 offset:36992
	ds_read_b128 v[216:219], v210 offset:37056
	ds_read_b128 v[220:223], v210 offset:39168
	ds_read_b128 v[224:227], v210 offset:39232
	ds_read_b128 v[228:231], v210 offset:41344
	ds_read_b128 v[242:245], v210 offset:41408
	global_load_lds_dwordx4 v[34:35], off
	v_lshl_add_u64 v[34:35], s[42:43], 0, v[148:149]
	s_mov_b32 m0, s57
	s_nop 0
	global_load_lds_dwordx4 v[34:35], off
	s_waitcnt vmcnt(8)
	s_waitcnt lgkmcnt(0)
	s_barrier
; #define PG8_STAGE(bufoff, gbase, voff) do { _Pragma("unroll") for (int _i = 0; _i < 2; ++_i) \
;         __builtin_amdgcn_global_load_lds((const unsigned*)((const char*)(gbase) + (voff)[_i]), (PG8_LAS unsigned*)(lds + (bufoff) + ldsw + _i * (8 * USTR)), 16, 0, 0); } while (0)
; #define PG8_LDA(dst, b, h) do { _Pragma("unroll") for (int m = 0; m < 4; ++m) _Pragma("unroll") for (int k = 0; k < 2; ++k) dst[m][k] = *(const PG8_LAS bf16x8*)(lds + PG8_SA(b, h) + aoff + m * (2 * USTR) + k * 64); } while (0)
; #define PG8_MMA(ai, bj, At, Bt) do { __builtin_amdgcn_s_setprio(1); _Pragma("unroll") for (int m = 0; m < 4; ++m) _Pragma("unroll") for (int n = 0; n < 2; ++n) _Pragma("unroll") for (int k = 0; k < 2; ++k) \
;         acc[ai][bj][m][n] = __builtin_amdgcn_mfma_f32_16x16x32_bf16(Bt[n][k], At[m][k], acc[ai][bj][m][n], 0, 0, 0); __builtin_amdgcn_s_setprio(0); } while (0)
; #define PG8_WAIT_V(n) asm volatile("s_waitcnt vmcnt(" #n ")" ::: "memory")
; #define PG8_WAIT_L(n) asm volatile("s_waitcnt lgkmcnt(" #n ")" ::: "memory")
; #define PG8_BAR __builtin_amdgcn_s_barrier()
; #define PG8_SCHED __builtin_amdgcn_sched_barrier(0)
; template <class Epi, class Sched, bool ALIGN_EPI, bool SP2>
; __device__ __forceinline__ void gemm_phase(PG8_LAS unsigned char* lds, const Gemm g, const Sched& S, const Epi& E, int wid) {
;     ...
;             PG8_WAIT_V(8); PG8_WAIT_L(0); PG8_BAR; PG8_MMA(0, 0, At, B0); PG8_MMA(0, 1, At, B1); PG8_BAR; PG8_SCHED;
;             PG8_LDA(At, 1, 1); PG8_STAGE(PG8_SB(1, 0), b3, voffB); PG8_STAGE(PG8_SB(1, 1), b3 + hstepB, voffB); PG8_STAGE(PG8_SA(1, 0), a3, voffA);
;             PG8_WAIT_V(8); PG8_WAIT_L(0); PG8_BAR; PG8_MMA(1, 0, At, B0); PG8_MMA(1, 1, At, B1); PG8_BAR; PG8_SCHED;
	s_setprio 1
	s_waitcnt lgkmcnt(0)
	v_mfma_f32_16x16x32_bf16 v[140:143], v[64:67], v[182:185], v[140:143]
	v_mfma_f32_16x16x32_bf16 v[136:139], v[158:161], v[182:185], v[136:139]
	v_mfma_f32_16x16x32_bf16 v[124:127], v[64:67], v[212:215], v[124:127]
	v_mfma_f32_16x16x32_bf16 v[120:123], v[158:161], v[212:215], v[120:123]
	v_mfma_f32_16x16x32_bf16 v[108:111], v[64:67], v[220:223], v[108:111]
	v_mfma_f32_16x16x32_bf16 v[104:107], v[158:161], v[220:223], v[104:107]
	v_mfma_f32_16x16x32_bf16 v[92:95], v[64:67], v[228:231], v[92:95]
	v_mfma_f32_16x16x32_bf16 v[88:91], v[158:161], v[228:231], v[88:91]
	v_mfma_f32_16x16x32_bf16 v[140:143], v[68:71], v[186:189], v[140:143]
	v_mfma_f32_16x16x32_bf16 v[136:139], v[162:165], v[186:189], v[136:139]
	v_mfma_f32_16x16x32_bf16 v[124:127], v[68:71], v[216:219], v[124:127]
	v_mfma_f32_16x16x32_bf16 v[120:123], v[162:165], v[216:219], v[120:123]
	v_mfma_f32_16x16x32_bf16 v[108:111], v[68:71], v[224:227], v[108:111]
	v_mfma_f32_16x16x32_bf16 v[104:107], v[162:165], v[224:227], v[104:107]
	v_mfma_f32_16x16x32_bf16 v[92:95], v[68:71], v[242:245], v[92:95]
	v_mfma_f32_16x16x32_bf16 v[88:91], v[162:165], v[242:245], v[88:91]
	s_setprio 0
	s_setprio 1
	v_mfma_f32_16x16x32_bf16 v[132:135], v[166:169], v[182:185], v[132:135]
	v_mfma_f32_16x16x32_bf16 v[128:131], v[174:177], v[182:185], v[128:131]
	v_mfma_f32_16x16x32_bf16 v[116:119], v[166:169], v[212:215], v[116:119]
	v_mfma_f32_16x16x32_bf16 v[112:115], v[174:177], v[212:215], v[112:115]
	v_mfma_f32_16x16x32_bf16 v[100:103], v[166:169], v[220:223], v[100:103]
	v_mfma_f32_16x16x32_bf16 v[96:99], v[174:177], v[220:223], v[96:99]
	v_mfma_f32_16x16x32_bf16 v[84:87], v[166:169], v[228:231], v[84:87]
	v_mfma_f32_16x16x32_bf16 v[80:83], v[174:177], v[228:231], v[80:83]
	v_mfma_f32_16x16x32_bf16 v[132:135], v[170:173], v[186:189], v[132:135]
	v_mfma_f32_16x16x32_bf16 v[128:131], v[178:181], v[186:189], v[128:131]
	v_mfma_f32_16x16x32_bf16 v[116:119], v[170:173], v[216:219], v[116:119]
	v_mfma_f32_16x16x32_bf16 v[112:115], v[178:181], v[216:219], v[112:115]
	v_mfma_f32_16x16x32_bf16 v[100:103], v[170:173], v[224:227], v[100:103]
	v_mfma_f32_16x16x32_bf16 v[96:99], v[178:181], v[224:227], v[96:99]
	v_mfma_f32_16x16x32_bf16 v[84:87], v[170:173], v[242:245], v[84:87]
	v_mfma_f32_16x16x32_bf16 v[80:83], v[178:181], v[242:245], v[80:83]
	s_setprio 0
	s_barrier
	s_add_i32 s42, s73, s33
	v_lshl_add_u64 v[34:35], v[190:191], 0, s[6:7]
	s_mov_b32 m0, s42
	ds_read_b128 v[182:185], v210 offset:52224
	ds_read_b128 v[186:189], v210 offset:52288
	ds_read_b128 v[212:215], v210 offset:54400
	ds_read_b128 v[216:219], v210 offset:54464
	ds_read_b128 v[220:223], v210 offset:56576
	ds_read_b128 v[224:227], v210 offset:56640
	ds_read_b128 v[228:231], v210 offset:58752
	ds_read_b128 v[242:245], v210 offset:58816
	global_load_lds_dwordx4 v[34:35], off
	s_add_i32 m0, s42, 0x2200
	s_add_u32 s40, s40, 0x40080
	v_lshl_add_u64 v[34:35], v[198:199], 0, s[6:7]
	s_addc_u32 s41, s41, 0
	s_add_i32 s42, s76, s33
	global_load_lds_dwordx4 v[34:35], off
	v_lshl_add_u64 v[34:35], s[40:41], 0, v[192:193]
	s_mov_b32 m0, s42
	s_nop 0
	global_load_lds_dwordx4 v[34:35], off
	v_lshl_add_u64 v[34:35], s[40:41], 0, v[146:147]
	s_add_i32 m0, s42, 0x2200
	s_nop 0
	global_load_lds_dwordx4 v[34:35], off
	v_lshl_add_u64 v[34:35], v[200:201], 0, s[6:7]
	s_mov_b32 m0, s29
	s_nop 0
	global_load_lds_dwordx4 v[34:35], off
	v_lshl_add_u64 v[34:35], v[208:209], 0, s[6:7]
	s_mov_b32 m0, s0
	s_nop 0
	global_load_lds_dwordx4 v[34:35], off
	s_waitcnt vmcnt(8)
	s_waitcnt lgkmcnt(0)
	s_barrier
	s_setprio 1
	s_waitcnt lgkmcnt(0)
	v_mfma_f32_16x16x32_bf16 v[76:79], v[64:67], v[182:185], v[76:79]
	v_mfma_f32_16x16x32_bf16 v[72:75], v[158:161], v[182:185], v[72:75]
	v_mfma_f32_16x16x32_bf16 v[60:63], v[64:67], v[212:215], v[60:63]
	v_mfma_f32_16x16x32_bf16 v[56:59], v[158:161], v[212:215], v[56:59]
	v_mfma_f32_16x16x32_bf16 v[44:47], v[64:67], v[220:223], v[44:47]
	v_mfma_f32_16x16x32_bf16 v[40:43], v[158:161], v[220:223], v[40:43]
	v_mfma_f32_16x16x32_bf16 v[12:15], v[64:67], v[228:231], v[12:15]
	v_mfma_f32_16x16x32_bf16 v[8:11], v[158:161], v[228:231], v[8:11]
	v_mfma_f32_16x16x32_bf16 v[76:79], v[68:71], v[186:189], v[76:79]
	v_mfma_f32_16x16x32_bf16 v[72:75], v[162:165], v[186:189], v[72:75]
	v_mfma_f32_16x16x32_bf16 v[60:63], v[68:71], v[216:219], v[60:63]
	v_mfma_f32_16x16x32_bf16 v[56:59], v[162:165], v[216:219], v[56:59]
	v_mfma_f32_16x16x32_bf16 v[44:47], v[68:71], v[224:227], v[44:47]
	v_mfma_f32_16x16x32_bf16 v[40:43], v[162:165], v[224:227], v[40:43]
	v_mfma_f32_16x16x32_bf16 v[12:15], v[68:71], v[242:245], v[12:15]
	v_mfma_f32_16x16x32_bf16 v[8:11], v[162:165], v[242:245], v[8:11]
	s_setprio 0
	s_setprio 1
	v_mfma_f32_16x16x32_bf16 v[22:25], v[166:169], v[182:185], v[22:25]
	v_mfma_f32_16x16x32_bf16 v[68:71], v[170:173], v[186:189], v[22:25]
	v_mfma_f32_16x16x32_bf16 v[22:25], v[174:177], v[182:185], v[26:29]
	v_mfma_f32_16x16x32_bf16 v[64:67], v[178:181], v[186:189], v[22:25]
	v_mfma_f32_16x16x32_bf16 v[22:25], v[166:169], v[212:215], v[52:55]
	v_mfma_f32_16x16x32_bf16 v[52:55], v[170:173], v[216:219], v[22:25]
	v_mfma_f32_16x16x32_bf16 v[22:25], v[174:177], v[212:215], v[48:51]
	v_mfma_f32_16x16x32_bf16 v[48:51], v[178:181], v[216:219], v[22:25]
	v_mfma_f32_16x16x32_bf16 v[22:25], v[166:169], v[220:223], v[36:39]
	v_mfma_f32_16x16x32_bf16 v[36:39], v[170:173], v[224:227], v[22:25]
	v_mfma_f32_16x16x32_bf16 v[22:25], v[174:177], v[220:223], v[30:33]
	v_mfma_f32_16x16x32_bf16 v[4:7], v[166:169], v[228:231], v[4:7]
	v_mfma_f32_16x16x32_bf16 v[0:3], v[174:177], v[228:231], v[0:3]
	v_mfma_f32_16x16x32_bf16 v[32:35], v[178:181], v[224:227], v[22:25]
	v_mfma_f32_16x16x32_bf16 v[4:7], v[170:173], v[242:245], v[4:7]
	v_mfma_f32_16x16x32_bf16 v[0:3], v[178:181], v[242:245], v[0:3]
	s_setprio 0
	s_barrier
	s_add_i32 s71, s71, 2
	s_add_u32 s38, s38, 0x100
	s_addc_u32 s39, s39, 0
	s_add_u32 s23, s23, 0x100
	s_addc_u32 s70, s70, 0
	s_cmp_gt_u32 s71, 13
	s_branch .LBB0_394

; #define PG8_BAR __builtin_amdgcn_s_barrier()
; template <class Epi, class Sched, bool ALIGN_EPI, bool SP2>
; __device__ __forceinline__ void gemm_phase(PG8_LAS unsigned char* lds, const Gemm g, const Sched& S, const Epi& E, int wid) {
;     ...
;                     for (int n = 0; n < 2; ++n) acc[a][b][m][n] = (f32x4){0.f, 0.f, 0.f, 0.f};
;         cur = nxt; cA = nA; cB = nB; ++ui;
;         if constexpr (ALIGN_EPI) { if (wr == 1) PG8_BAR; }
;     }
.LBB0_480:
	s_and_b64 vcc, exec, s[34:35]
	s_cbranch_vccnz .LBB0_388
	s_branch .LBB0_388
